# speedup vs baseline: 1.0065x; 1.0052x over previous
; #define PG8_STAGE(bufoff, gbase, voff) do { _Pragma("unroll") for (int _i = 0; _i < 2; ++_i) \
;         __builtin_amdgcn_global_load_lds((const unsigned*)((const char*)(gbase) + (voff)[_i]), (PG8_LAS unsigned*)(lds + (bufoff) + ldsw + _i * 8192), 16, 0, 0); } while (0)
; #define PG8_WAIT_V(n) asm volatile("s_waitcnt vmcnt(" #n ")" ::: "memory")
; #define PG8_BAR __builtin_amdgcn_s_barrier()
; template <class Epi, class Sched, bool ALIGN_EPI = false, bool SP2 = false, bool FP8 = false>
; __device__ __forceinline__ void gemm_phase(PG8_LAS unsigned char* lds, const Gemm g, const Sched& S, const Epi& E, const int tid) {
;     ...
;         PG8_STAGE(PG8_SB(0, 0), cB, voffB); PG8_STAGE(PG8_SB(0, 1), cB + hstepB, voffB); PG8_STAGE(PG8_SA(0, 0), cA, voffA); PG8_STAGE(PG8_SA(0, 1), cA + hstepA, voffA);
;         if (wr == 1) PG8_BAR;
;         PG8_WAIT_V(2); PG8_BAR;
;         PG8_STAGE(PG8_SB(1, 0), cB + kstep, voffB); PG8_STAGE(PG8_SA(1, 0), cA + kstep, voffA); PG8_STAGE(PG8_SB(1, 1), cB + hstepB + kstep, voffB);
;         PG8_WAIT_V(6); PG8_BAR;
.LBB0_88:
	s_add_u32 s14, s12, 0x10802700
	s_addc_u32 s15, s13, 0
	s_lshl_b32 s16, s16, 5
	s_and_b32 s25, s16, 0x60
	s_add_i32 m0, s43, 0x18000
	v_lshl_add_u64 v[6:7], v[6:7], 0, s[38:39]
	s_lshl_b32 s24, s5, 13
	s_lshl_b32 s26, s25, 7
	s_waitcnt vmcnt(2)
	s_barrier
	global_load_lds_dwordx4 v[6:7], off
	v_lshl_add_u64 v[4:5], v[4:5], 0, s[38:39]
	s_add_i32 m0, s43, 0x1a000
	s_add_i32 s47, s43, 0x8000
	s_add_i32 s48, s43, 0xa000
	global_load_lds_dwordx4 v[4:5], off
	v_lshl_add_u64 v[0:1], v[0:1], 0, s[38:39]
	s_mov_b32 m0, s47
	s_add_u32 s16, s36, 0x80080
	global_load_lds_dwordx4 v[0:1], off
	v_lshl_add_u64 v[0:1], v[2:3], 0, s[38:39]
	s_mov_b32 m0, s48
	s_addc_u32 s17, s37, 0
	global_load_lds_dwordx4 v[0:1], off
	s_add_i32 m0, s43, 0x1c000
	v_lshl_add_u64 v[0:1], s[16:17], 0, v[134:135]
	global_load_lds_dwordx4 v[0:1], off
	v_lshl_add_u64 v[0:1], s[16:17], 0, v[130:131]
	s_add_i32 m0, s43, 0x1e000
	s_cmpk_lt_u32 s4, 0x100
	global_load_lds_dwordx4 v[0:1], off
	v_lshrrev_b32_e32 v1, 1, v8
	v_and_b32_e32 v1, 24, v1
	v_and_b32_e32 v0, 15, v8
	v_lshlrev_b32_e32 v2, 1, v1
	v_lshl_or_b32 v33, s5, 6, v0
	v_lshl_or_b32 v0, v0, 6, v2
	v_lshlrev_b32_e32 v2, 2, v8
	v_and_b32_e32 v2, 32, v2
	v_bitop3_b32 v3, v0, s24, v2 bitop3:0xde
	v_bitop3_b32 v150, s26, v0, v2 bitop3:0xf6
	v_lshlrev_b32_e32 v0, 15, v13
	v_and_b32_e32 v0, 0xffff0000, v0
	v_or_b32_e32 v151, s25, v1
	v_lshl_add_u32 v0, v12, 12, v0
	v_and_b32_e32 v1, 1, v13
	v_lshl_or_b32 v0, v1, 6, v0
	v_lshl_add_u32 v138, v14, 1, v0
	v_lshlrev_b32_e32 v0, 15, v9
	v_and_b32_e32 v0, 0xffff0000, v0
	s_waitcnt vmcnt(0)
	v_lshl_add_u32 v0, v10, 12, v0
	v_and_b32_e32 v1, 1, v9
	v_lshl_or_b32 v0, v1, 6, v0
	v_readlane_b32 s4, v254, 8
	s_cselect_b64 s[16:17], -1, 0
	v_mov_b32_e32 v139, v32
	v_lshl_add_u32 v140, v11, 1, v0
	v_mov_b32_e32 v141, v32
	s_mov_b32 s49, 0
	v_add_u32_e32 v152, 0, v3
	v_readlane_b32 s50, v254, 7
	s_mov_b32 s51, s4
	s_barrier
	v_readlane_b32 s5, v254, 9
	s_branch .LBB0_91

; #define PG8_STAGE(bufoff, gbase, voff) do { _Pragma("unroll") for (int _i = 0; _i < 2; ++_i) \
;         __builtin_amdgcn_global_load_lds((const unsigned*)((const char*)(gbase) + (voff)[_i]), (PG8_LAS unsigned*)(lds + (bufoff) + ldsw + _i * 8192), 16, 0, 0); } while (0)
; #define PG8_WAIT_V(n) asm volatile("s_waitcnt vmcnt(" #n ")" ::: "memory")
; #define PG8_WAIT_L(n) asm volatile("s_waitcnt lgkmcnt(" #n ")" ::: "memory")
; #define PG8_BAR __builtin_amdgcn_s_barrier()
; #define PG8_SCHED __builtin_amdgcn_sched_barrier(0)
; template <class Epi, class Sched, bool ALIGN_EPI = false, bool SP2 = false, bool FP8 = false>
; __device__ __forceinline__ void gemm_phase(PG8_LAS unsigned char* lds, const Gemm g, const Sched& S, const Epi& E, const int tid) {
;     ...
;             PG8_LDB(B0, 0, 0); PG8_LDB(B1, 0, 1); PG8_SCHED; PG8_LDA(At, 0, 0); PG8_STAGE(PG8_SA(1, 1), a1 + hstepA, voffA);
;             PG8_WAIT_V(8); PG8_WAIT_L(0); PG8_BAR; PG8_MMA(0, 0, At, B0); PG8_MMA(0, 1, At, B1); PG8_BAR; PG8_SCHED;
;             PG8_LDA(At, 0, 1); PG8_STAGE(PG8_SB(0, 0), b2, voffB); PG8_STAGE(PG8_SB(0, 1), b2 + hstepB, voffB); PG8_STAGE(PG8_SA(0, 0), a2, voffA);
;             PG8_WAIT_V(8); PG8_WAIT_L(0); PG8_BAR; PG8_MMA(1, 0, At, B0); PG8_MMA(1, 1, At, B1); PG8_BAR; PG8_SCHED;
.LBB0_98:
	s_add_u32 s36, s34, 0xfff80080
	s_addc_u32 s37, s35, -1
	s_add_i32 s57, 0, 0x10000
	s_cmp_eq_u32 s56, 28
	s_cselect_b32 s41, s27, s37
	s_cselect_b32 s40, s52, s36
	v_add_u32_e32 v153, s57, v150
	s_cselect_b32 s37, s25, s55
	s_cselect_b32 s36, s53, s54
	s_add_i32 s60, 0, 0x14000
	ds_read_b128 v[142:145], v153
	ds_read_b128 v[146:149], v153 offset:1024
	ds_read_b128 v[154:157], v153 offset:2048
	ds_read_b128 v[158:161], v153 offset:3072
	v_add_u32_e32 v153, s60, v150
	ds_read_b128 v[180:183], v153
	ds_read_b128 v[184:187], v153 offset:1024
	ds_read_b128 v[188:191], v153 offset:2048
	ds_read_b128 v[192:195], v153 offset:3072
	v_lshl_add_u64 v[200:201], s[34:35], 0, v[138:139]
	s_add_i32 m0, s43, 0xc000
	ds_read_b128 v[196:199], v152
	ds_read_b128 v[220:223], v152 offset:1024
	ds_read_b128 v[224:227], v152 offset:2048
	ds_read_b128 v[228:231], v152 offset:3072
	ds_read_b128 v[232:235], v152 offset:4096
	ds_read_b128 v[236:239], v152 offset:5120
	ds_read_b128 v[240:243], v152 offset:6144
	ds_read_b128 v[244:247], v152 offset:7168
	global_load_lds_dwordx4 v[200:201], off
	v_lshl_add_u64 v[200:201], s[34:35], 0, v[140:141]
	s_add_i32 m0, s43, 0xe000
	s_nop 0
	global_load_lds_dwordx4 v[200:201], off
	s_cmp_eq_i32 s56, -2
	s_cbranch_scc1 .Lskw_0_0
	s_waitcnt vmcnt(8)
.Lskw_0_0:
	s_waitcnt lgkmcnt(0)
	s_barrier
	s_setprio 1
	s_waitcnt lgkmcnt(0)
	v_mfma_f32_16x16x32_bf16 v[126:129], v[142:145], v[196:199], v[126:129]
	v_mfma_f32_16x16x32_bf16 v[122:125], v[154:157], v[196:199], v[122:125]
	v_mfma_f32_16x16x32_bf16 v[110:113], v[142:145], v[224:227], v[110:113]
	v_mfma_f32_16x16x32_bf16 v[106:109], v[154:157], v[224:227], v[106:109]
	v_mfma_f32_16x16x32_bf16 v[94:97], v[142:145], v[232:235], v[94:97]
	v_mfma_f32_16x16x32_bf16 v[90:93], v[154:157], v[232:235], v[90:93]
	v_mfma_f32_16x16x32_bf16 v[78:81], v[142:145], v[240:243], v[78:81]
	v_mfma_f32_16x16x32_bf16 v[74:77], v[154:157], v[240:243], v[74:77]
	v_mfma_f32_16x16x32_bf16 v[126:129], v[146:149], v[220:223], v[126:129]
	v_mfma_f32_16x16x32_bf16 v[122:125], v[158:161], v[220:223], v[122:125]
	v_mfma_f32_16x16x32_bf16 v[110:113], v[146:149], v[228:231], v[110:113]
	v_mfma_f32_16x16x32_bf16 v[106:109], v[158:161], v[228:231], v[106:109]
	v_mfma_f32_16x16x32_bf16 v[94:97], v[146:149], v[236:239], v[94:97]
	v_mfma_f32_16x16x32_bf16 v[90:93], v[158:161], v[236:239], v[90:93]
	v_mfma_f32_16x16x32_bf16 v[78:81], v[146:149], v[244:247], v[78:81]
	v_mfma_f32_16x16x32_bf16 v[74:77], v[158:161], v[244:247], v[74:77]
	s_setprio 0
	s_setprio 1
	v_mfma_f32_16x16x32_bf16 v[118:121], v[180:183], v[196:199], v[118:121]
	v_mfma_f32_16x16x32_bf16 v[114:117], v[188:191], v[196:199], v[114:117]
	v_mfma_f32_16x16x32_bf16 v[102:105], v[180:183], v[224:227], v[102:105]
	v_mfma_f32_16x16x32_bf16 v[98:101], v[188:191], v[224:227], v[98:101]
	v_mfma_f32_16x16x32_bf16 v[86:89], v[180:183], v[232:235], v[86:89]
	v_mfma_f32_16x16x32_bf16 v[82:85], v[188:191], v[232:235], v[82:85]
	v_mfma_f32_16x16x32_bf16 v[70:73], v[180:183], v[240:243], v[70:73]
	v_mfma_f32_16x16x32_bf16 v[66:69], v[188:191], v[240:243], v[66:69]
	v_mfma_f32_16x16x32_bf16 v[118:121], v[184:187], v[220:223], v[118:121]
	v_mfma_f32_16x16x32_bf16 v[114:117], v[192:195], v[220:223], v[114:117]
	v_mfma_f32_16x16x32_bf16 v[102:105], v[184:187], v[228:231], v[102:105]
	v_mfma_f32_16x16x32_bf16 v[98:101], v[192:195], v[228:231], v[98:101]
	v_mfma_f32_16x16x32_bf16 v[86:89], v[184:187], v[236:239], v[86:89]
	v_mfma_f32_16x16x32_bf16 v[82:85], v[192:195], v[236:239], v[82:85]
	v_mfma_f32_16x16x32_bf16 v[70:73], v[184:187], v[244:247], v[70:73]
	v_mfma_f32_16x16x32_bf16 v[66:69], v[192:195], v[244:247], v[66:69]
	s_setprio 0
	s_barrier
	s_add_i32 s57, s57, s42
	v_lshl_add_u64 v[200:201], s[36:37], 0, v[134:135]
	s_mov_b32 m0, s57
	ds_read_b128 v[196:199], v152 offset:16384
	ds_read_b128 v[220:223], v152 offset:17408
	ds_read_b128 v[224:227], v152 offset:18432
	ds_read_b128 v[228:231], v152 offset:19456
	ds_read_b128 v[232:235], v152 offset:20480
	ds_read_b128 v[236:239], v152 offset:21504
	ds_read_b128 v[240:243], v152 offset:22528
	ds_read_b128 v[244:247], v152 offset:23552
	global_load_lds_dwordx4 v[200:201], off
	s_add_i32 m0, s57, 0x2000
	s_add_u32 s58, s36, 0x80000
	v_lshl_add_u64 v[248:249], s[36:37], 0, v[130:131]
	s_addc_u32 s59, s37, 0
	s_add_i32 s57, s60, s42
	global_load_lds_dwordx4 v[248:249], off
	v_lshl_add_u64 v[250:251], s[58:59], 0, v[134:135]
	s_mov_b32 m0, s57
	v_lshl_add_u64 v[164:165], s[40:41], 0, v[132:133]
	global_load_lds_dwordx4 v[250:251], off
	v_lshl_add_u64 v[250:251], s[58:59], 0, v[130:131]
	s_add_i32 m0, s57, 0x2000
	s_nop 0
	global_load_lds_dwordx4 v[250:251], off
	v_lshl_add_u64 v[250:251], s[40:41], 0, v[136:137]
	s_mov_b32 m0, s43
	s_nop 0
	global_load_lds_dwordx4 v[250:251], off
	s_mov_b32 m0, s44
	s_nop 0
	global_load_lds_dwordx4 v[164:165], off
	s_cmp_eq_i32 s56, -2
	s_cbranch_scc1 .Lskw_0_1
	s_waitcnt vmcnt(8)
; #define PG8_STAGE(bufoff, gbase, voff) do { _Pragma("unroll") for (int _i = 0; _i < 2; ++_i) \
;         __builtin_amdgcn_global_load_lds((const unsigned*)((const char*)(gbase) + (voff)[_i]), (PG8_LAS unsigned*)(lds + (bufoff) + ldsw + _i * 8192), 16, 0, 0); } while (0)
; #define PG8_WAIT_V(n) asm volatile("s_waitcnt vmcnt(" #n ")" ::: "memory")
; #define PG8_WAIT_L(n) asm volatile("s_waitcnt lgkmcnt(" #n ")" ::: "memory")
; #define PG8_BAR __builtin_amdgcn_s_barrier()
; #define PG8_SCHED __builtin_amdgcn_sched_barrier(0)
; template <class Epi, class Sched, bool ALIGN_EPI = false, bool SP2 = false, bool FP8 = false>
; __device__ __forceinline__ void gemm_phase(PG8_LAS unsigned char* lds, const Gemm g, const Sched& S, const Epi& E, const int tid) {
;     ...
;             PG8_WAIT_V(8); PG8_WAIT_L(0); PG8_BAR; PG8_MMA(1, 0, At, B0); PG8_MMA(1, 1, At, B1); PG8_BAR; PG8_SCHED;
;             PG8_LDB(B0, 1, 0); PG8_LDB(B1, 1, 1); PG8_SCHED; PG8_LDA(At, 1, 0); PG8_STAGE(PG8_SA(0, 1), a2 + hstepA, voffA);
;             PG8_WAIT_V(8); PG8_WAIT_L(0); PG8_BAR; PG8_MMA(0, 0, At, B0); PG8_MMA(0, 1, At, B1); PG8_BAR; PG8_SCHED;
;             PG8_LDA(At, 1, 1); PG8_STAGE(PG8_SB(1, 0), b3, voffB); PG8_STAGE(PG8_SB(1, 1), b3 + hstepB, voffB); PG8_STAGE(PG8_SA(1, 0), a3, voffA);
;             PG8_WAIT_V(8); PG8_WAIT_L(0); PG8_BAR; PG8_MMA(1, 0, At, B0); PG8_MMA(1, 1, At, B1); PG8_BAR; PG8_SCHED;
.Lskw_0_1:
	s_waitcnt lgkmcnt(0)
	s_barrier
	s_setprio 1
	s_waitcnt lgkmcnt(0)
	v_mfma_f32_16x16x32_bf16 v[62:65], v[142:145], v[196:199], v[62:65]
	v_mfma_f32_16x16x32_bf16 v[58:61], v[154:157], v[196:199], v[58:61]
	v_mfma_f32_16x16x32_bf16 v[46:49], v[142:145], v[224:227], v[46:49]
	v_mfma_f32_16x16x32_bf16 v[42:45], v[154:157], v[224:227], v[42:45]
	v_mfma_f32_16x16x32_bf16 v[28:31], v[142:145], v[232:235], v[28:31]
	v_mfma_f32_16x16x32_bf16 v[24:27], v[154:157], v[232:235], v[24:27]
	v_mfma_f32_16x16x32_bf16 v[12:15], v[142:145], v[240:243], v[12:15]
	v_mfma_f32_16x16x32_bf16 v[8:11], v[154:157], v[240:243], v[8:11]
	v_mfma_f32_16x16x32_bf16 v[62:65], v[146:149], v[220:223], v[62:65]
	v_mfma_f32_16x16x32_bf16 v[58:61], v[158:161], v[220:223], v[58:61]
	v_mfma_f32_16x16x32_bf16 v[46:49], v[146:149], v[228:231], v[46:49]
	v_mfma_f32_16x16x32_bf16 v[42:45], v[158:161], v[228:231], v[42:45]
	v_mfma_f32_16x16x32_bf16 v[28:31], v[146:149], v[236:239], v[28:31]
	v_mfma_f32_16x16x32_bf16 v[24:27], v[158:161], v[236:239], v[24:27]
	v_mfma_f32_16x16x32_bf16 v[12:15], v[146:149], v[244:247], v[12:15]
	v_mfma_f32_16x16x32_bf16 v[8:11], v[158:161], v[244:247], v[8:11]
	s_setprio 0
	s_setprio 1
	v_mfma_f32_16x16x32_bf16 v[54:57], v[180:183], v[196:199], v[54:57]
	v_mfma_f32_16x16x32_bf16 v[50:53], v[188:191], v[196:199], v[50:53]
	v_mfma_f32_16x16x32_bf16 v[38:41], v[180:183], v[224:227], v[38:41]
	v_mfma_f32_16x16x32_bf16 v[34:37], v[188:191], v[224:227], v[34:37]
	v_mfma_f32_16x16x32_bf16 v[20:23], v[180:183], v[232:235], v[20:23]
	v_mfma_f32_16x16x32_bf16 v[16:19], v[188:191], v[232:235], v[16:19]
	v_mfma_f32_16x16x32_bf16 v[4:7], v[180:183], v[240:243], v[4:7]
	v_mfma_f32_16x16x32_bf16 v[0:3], v[188:191], v[240:243], v[0:3]
	v_mfma_f32_16x16x32_bf16 v[54:57], v[184:187], v[220:223], v[54:57]
	v_mfma_f32_16x16x32_bf16 v[50:53], v[192:195], v[220:223], v[50:53]
	v_mfma_f32_16x16x32_bf16 v[38:41], v[184:187], v[228:231], v[38:41]
	v_mfma_f32_16x16x32_bf16 v[34:37], v[192:195], v[228:231], v[34:37]
	v_mfma_f32_16x16x32_bf16 v[20:23], v[184:187], v[236:239], v[20:23]
	v_mfma_f32_16x16x32_bf16 v[16:19], v[192:195], v[236:239], v[16:19]
	v_mfma_f32_16x16x32_bf16 v[4:7], v[184:187], v[244:247], v[4:7]
	v_mfma_f32_16x16x32_bf16 v[0:3], v[192:195], v[244:247], v[0:3]
	s_setprio 0
	s_barrier
	s_add_i32 s57, 0, 0x18000
	v_add_u32_e32 v153, s57, v150
	s_add_i32 s58, 0, 0x1c000
	ds_read_b128 v[142:145], v153
	ds_read_b128 v[146:149], v153 offset:1024
	ds_read_b128 v[154:157], v153 offset:2048
	ds_read_b128 v[158:161], v153 offset:3072
	v_add_u32_e32 v153, s58, v150
	ds_read_b128 v[180:183], v153
	ds_read_b128 v[184:187], v153 offset:1024
	ds_read_b128 v[188:191], v153 offset:2048
	ds_read_b128 v[192:195], v153 offset:3072
	s_add_u32 s40, s40, 0x80000
	s_addc_u32 s41, s41, 0
	s_mov_b32 m0, s45
	v_lshl_add_u64 v[166:167], s[40:41], 0, v[136:137]
	ds_read_b128 v[196:199], v152 offset:32768
	ds_read_b128 v[220:223], v152 offset:33792
	ds_read_b128 v[224:227], v152 offset:34816
	ds_read_b128 v[228:231], v152 offset:35840
	ds_read_b128 v[232:235], v152 offset:36864
	ds_read_b128 v[236:239], v152 offset:37888
	ds_read_b128 v[240:243], v152 offset:38912
	ds_read_b128 v[244:247], v152 offset:39936
	global_load_lds_dwordx4 v[166:167], off
	v_lshl_add_u64 v[166:167], s[40:41], 0, v[132:133]
	s_mov_b32 m0, s46
	s_nop 0
	global_load_lds_dwordx4 v[166:167], off
	s_waitcnt vmcnt(8)
	s_waitcnt lgkmcnt(0)
	s_barrier
	s_setprio 1
	s_waitcnt lgkmcnt(0)
	v_mfma_f32_16x16x32_bf16 v[126:129], v[142:145], v[196:199], v[126:129]
	v_mfma_f32_16x16x32_bf16 v[122:125], v[154:157], v[196:199], v[122:125]
	v_mfma_f32_16x16x32_bf16 v[110:113], v[142:145], v[224:227], v[110:113]
	v_mfma_f32_16x16x32_bf16 v[106:109], v[154:157], v[224:227], v[106:109]
	v_mfma_f32_16x16x32_bf16 v[94:97], v[142:145], v[232:235], v[94:97]
	v_mfma_f32_16x16x32_bf16 v[90:93], v[154:157], v[232:235], v[90:93]
	v_mfma_f32_16x16x32_bf16 v[78:81], v[142:145], v[240:243], v[78:81]
	v_mfma_f32_16x16x32_bf16 v[74:77], v[154:157], v[240:243], v[74:77]
	v_mfma_f32_16x16x32_bf16 v[126:129], v[146:149], v[220:223], v[126:129]
	v_mfma_f32_16x16x32_bf16 v[122:125], v[158:161], v[220:223], v[122:125]
	v_mfma_f32_16x16x32_bf16 v[110:113], v[146:149], v[228:231], v[110:113]
	v_mfma_f32_16x16x32_bf16 v[106:109], v[158:161], v[228:231], v[106:109]
	v_mfma_f32_16x16x32_bf16 v[94:97], v[146:149], v[236:239], v[94:97]
	v_mfma_f32_16x16x32_bf16 v[90:93], v[158:161], v[236:239], v[90:93]
	v_mfma_f32_16x16x32_bf16 v[78:81], v[146:149], v[244:247], v[78:81]
	v_mfma_f32_16x16x32_bf16 v[74:77], v[158:161], v[244:247], v[74:77]
	s_setprio 0
	s_setprio 1
	v_mfma_f32_16x16x32_bf16 v[118:121], v[180:183], v[196:199], v[118:121]
	v_mfma_f32_16x16x32_bf16 v[114:117], v[188:191], v[196:199], v[114:117]
	v_mfma_f32_16x16x32_bf16 v[102:105], v[180:183], v[224:227], v[102:105]
	v_mfma_f32_16x16x32_bf16 v[98:101], v[188:191], v[224:227], v[98:101]
	v_mfma_f32_16x16x32_bf16 v[86:89], v[180:183], v[232:235], v[86:89]
	v_mfma_f32_16x16x32_bf16 v[82:85], v[188:191], v[232:235], v[82:85]
	v_mfma_f32_16x16x32_bf16 v[70:73], v[180:183], v[240:243], v[70:73]
	v_mfma_f32_16x16x32_bf16 v[66:69], v[188:191], v[240:243], v[66:69]
	v_mfma_f32_16x16x32_bf16 v[118:121], v[184:187], v[220:223], v[118:121]
	v_mfma_f32_16x16x32_bf16 v[114:117], v[192:195], v[220:223], v[114:117]
	v_mfma_f32_16x16x32_bf16 v[102:105], v[184:187], v[228:231], v[102:105]
	v_mfma_f32_16x16x32_bf16 v[98:101], v[192:195], v[228:231], v[98:101]
	v_mfma_f32_16x16x32_bf16 v[86:89], v[184:187], v[236:239], v[86:89]
	v_mfma_f32_16x16x32_bf16 v[82:85], v[192:195], v[236:239], v[82:85]
	v_mfma_f32_16x16x32_bf16 v[70:73], v[184:187], v[244:247], v[70:73]
	v_mfma_f32_16x16x32_bf16 v[66:69], v[192:195], v[244:247], v[66:69]
	s_setprio 0
	s_barrier
; #define PG8_STAGE(bufoff, gbase, voff) do { _Pragma("unroll") for (int _i = 0; _i < 2; ++_i) \
;         __builtin_amdgcn_global_load_lds((const unsigned*)((const char*)(gbase) + (voff)[_i]), (PG8_LAS unsigned*)(lds + (bufoff) + ldsw + _i * 8192), 16, 0, 0); } while (0)
; #define PG8_WAIT_V(n) asm volatile("s_waitcnt vmcnt(" #n ")" ::: "memory")
; #define PG8_WAIT_L(n) asm volatile("s_waitcnt lgkmcnt(" #n ")" ::: "memory")
; #define PG8_BAR __builtin_amdgcn_s_barrier()
; #define PG8_SCHED __builtin_amdgcn_sched_barrier(0)
;     __device__ __forceinline__ void operator()(const f32x4 (&acc)[2][2][4][2], const Unit& u, int wr, int wc, int fr, int fq) const {
;     ...
;             for (int m = 0; m < 4; ++m) { const int row = row0 + ai * HALF + m * 16; const float rs = __builtin_amdgcn_rsqf((float)ss[row] * (SS_INV / 2048.0f) + RMS_EPS) * osc;
; template <class Epi, class Sched, bool ALIGN_EPI = false, bool SP2 = false, bool FP8 = false>
; __device__ __forceinline__ void gemm_phase(PG8_LAS unsigned char* lds, const Gemm g, const Sched& S, const Epi& E, const int tid) {
;     ...
;             PG8_WAIT_V(8); PG8_WAIT_L(0); PG8_BAR; PG8_MMA(0, 0, At, B0); PG8_MMA(0, 1, At, B1); PG8_BAR; PG8_SCHED;
;             PG8_LDA(At, 1, 1); PG8_STAGE(PG8_SB(1, 0), b3, voffB); PG8_STAGE(PG8_SB(1, 1), b3 + hstepB, voffB); PG8_STAGE(PG8_SA(1, 0), a3, voffA);
;             PG8_WAIT_V(8); PG8_WAIT_L(0); PG8_BAR; PG8_MMA(1, 0, At, B0); PG8_MMA(1, 1, At, B1); PG8_BAR; PG8_SCHED;
	s_add_i32 s40, s57, s42
	v_lshl_add_u64 v[166:167], v[200:201], 0, s[38:39]
	s_mov_b32 m0, s40
	ds_read_b128 v[196:199], v152 offset:49152
	ds_read_b128 v[220:223], v152 offset:50176
	ds_read_b128 v[224:227], v152 offset:51200
	ds_read_b128 v[228:231], v152 offset:52224
	ds_read_b128 v[232:235], v152 offset:53248
	ds_read_b128 v[236:239], v152 offset:54272
	ds_read_b128 v[240:243], v152 offset:55296
	ds_read_b128 v[244:247], v152 offset:56320
	global_load_lds_dwordx4 v[166:167], off
	s_add_i32 m0, s40, 0x2000
	s_add_u32 s36, s36, 0x80080
	v_lshl_add_u64 v[166:167], v[248:249], 0, s[38:39]
	s_addc_u32 s37, s37, 0
	s_add_i32 s40, s58, s42
	global_load_lds_dwordx4 v[166:167], off
	v_lshl_add_u64 v[166:167], s[36:37], 0, v[134:135]
	s_mov_b32 m0, s40
	v_lshl_add_u64 v[164:165], v[164:165], 0, s[38:39]
	global_load_lds_dwordx4 v[166:167], off
	v_lshl_add_u64 v[166:167], s[36:37], 0, v[130:131]
	s_add_i32 m0, s40, 0x2000
	s_nop 0
	global_load_lds_dwordx4 v[166:167], off
	v_lshl_add_u64 v[166:167], v[250:251], 0, s[38:39]
	s_mov_b32 m0, s47
	s_nop 0
	global_load_lds_dwordx4 v[166:167], off
	s_mov_b32 m0, s48
	s_nop 0
	global_load_lds_dwordx4 v[164:165], off
	s_waitcnt vmcnt(8)
	s_waitcnt lgkmcnt(0)
	s_barrier
	s_setprio 1
	s_waitcnt lgkmcnt(0)
	v_mfma_f32_16x16x32_bf16 v[62:65], v[142:145], v[196:199], v[62:65]
	v_mfma_f32_16x16x32_bf16 v[58:61], v[154:157], v[196:199], v[58:61]
	v_mfma_f32_16x16x32_bf16 v[46:49], v[142:145], v[224:227], v[46:49]
	v_mfma_f32_16x16x32_bf16 v[42:45], v[154:157], v[224:227], v[42:45]
	v_mfma_f32_16x16x32_bf16 v[28:31], v[142:145], v[232:235], v[28:31]
	v_mfma_f32_16x16x32_bf16 v[24:27], v[154:157], v[232:235], v[24:27]
	v_mfma_f32_16x16x32_bf16 v[12:15], v[142:145], v[240:243], v[12:15]
	v_mfma_f32_16x16x32_bf16 v[8:11], v[154:157], v[240:243], v[8:11]
	v_mfma_f32_16x16x32_bf16 v[62:65], v[146:149], v[220:223], v[62:65]
	v_mfma_f32_16x16x32_bf16 v[58:61], v[158:161], v[220:223], v[58:61]
	v_mfma_f32_16x16x32_bf16 v[46:49], v[146:149], v[228:231], v[46:49]
	v_mfma_f32_16x16x32_bf16 v[42:45], v[158:161], v[228:231], v[42:45]
	v_mfma_f32_16x16x32_bf16 v[28:31], v[146:149], v[236:239], v[28:31]
	v_mfma_f32_16x16x32_bf16 v[24:27], v[158:161], v[236:239], v[24:27]
	v_mfma_f32_16x16x32_bf16 v[12:15], v[146:149], v[244:247], v[12:15]
	v_mfma_f32_16x16x32_bf16 v[8:11], v[158:161], v[244:247], v[8:11]
	s_setprio 0
	s_setprio 1
	v_mfma_f32_16x16x32_bf16 v[54:57], v[180:183], v[196:199], v[54:57]
	v_mfma_f32_16x16x32_bf16 v[50:53], v[188:191], v[196:199], v[50:53]
	v_mfma_f32_16x16x32_bf16 v[38:41], v[180:183], v[224:227], v[38:41]
	v_mfma_f32_16x16x32_bf16 v[34:37], v[188:191], v[224:227], v[34:37]
	v_mfma_f32_16x16x32_bf16 v[20:23], v[180:183], v[232:235], v[20:23]
	v_mfma_f32_16x16x32_bf16 v[16:19], v[188:191], v[232:235], v[16:19]
	v_mfma_f32_16x16x32_bf16 v[4:7], v[180:183], v[240:243], v[4:7]
	v_mfma_f32_16x16x32_bf16 v[0:3], v[188:191], v[240:243], v[0:3]
	v_mfma_f32_16x16x32_bf16 v[54:57], v[184:187], v[220:223], v[54:57]
	v_mfma_f32_16x16x32_bf16 v[50:53], v[192:195], v[220:223], v[50:53]
	v_mfma_f32_16x16x32_bf16 v[38:41], v[184:187], v[228:231], v[38:41]
	v_mfma_f32_16x16x32_bf16 v[34:37], v[192:195], v[228:231], v[34:37]
	v_mfma_f32_16x16x32_bf16 v[20:23], v[184:187], v[236:239], v[20:23]
	v_mfma_f32_16x16x32_bf16 v[16:19], v[192:195], v[236:239], v[16:19]
	v_mfma_f32_16x16x32_bf16 v[4:7], v[184:187], v[244:247], v[4:7]
	v_mfma_f32_16x16x32_bf16 v[0:3], v[192:195], v[244:247], v[0:3]
	s_setprio 0
	s_barrier
	s_add_i32 s56, s56, 2
	s_add_u32 s34, s34, 0x100
	s_addc_u32 s35, s35, 0
	s_add_u32 s54, s54, 0x100
	s_addc_u32 s55, s55, 0
	s_cmp_gt_u32 s56, 29
	s_cbranch_scc0 .LBB0_98
	v_lshl_add_u32 v142, s51, 8, v33
	v_ashrrev_i32_e32 v143, 31, v142
	v_lshl_add_u64 v[148:149], v[142:143], 3, s[8:9]
	global_load_dwordx2 v[220:221], v[148:149], off
	global_load_dwordx2 v[222:223], v[148:149], off offset:128
	global_load_dwordx2 v[224:225], v[148:149], off offset:256
	global_load_dwordx2 v[226:227], v[148:149], off offset:384
	global_load_dwordx2 v[228:229], v[148:149], off offset:1024
	global_load_dwordx2 v[230:231], v[148:149], off offset:1152
	global_load_dwordx2 v[232:233], v[148:149], off offset:1280
	global_load_dwordx2 v[234:235], v[148:149], off offset:1408
	s_and_b64 vcc, exec, s[16:17]
	s_cbranch_vccz .LBB0_101
	s_barrier

; #define PG8_STAGE(bufoff, gbase, voff) do { _Pragma("unroll") for (int _i = 0; _i < 2; ++_i) \
;         __builtin_amdgcn_global_load_lds((const unsigned*)((const char*)(gbase) + (voff)[_i]), (PG8_LAS unsigned*)(lds + (bufoff) + ldsw + _i * 8192), 16, 0, 0); } while (0)
; #define PG8_WAIT_V(n) asm volatile("s_waitcnt vmcnt(" #n ")" ::: "memory")
; #define PG8_BAR __builtin_amdgcn_s_barrier()
; template <class Epi, class Sched, bool ALIGN_EPI = false, bool SP2 = false, bool FP8 = false>
; __device__ __forceinline__ void gemm_phase(PG8_LAS unsigned char* lds, const Gemm g, const Sched& S, const Epi& E, const int tid) {
;     ...
;         PG8_STAGE(PG8_SB(0, 0), cB, voffB); PG8_STAGE(PG8_SA(0, 0), cA, voffA); PG8_STAGE(PG8_SB(0, 1), cB + hstepB, voffB); PG8_STAGE(PG8_SA(0, 1), cA + hstepA, voffA);
;         if (wr == 1) PG8_BAR;
;         PG8_WAIT_V(4); PG8_BAR;
;         PG8_STAGE(PG8_SB(1, 0), cB + kstep, voffB); PG8_STAGE(PG8_SA(1, 0), cA + kstep, voffA); PG8_STAGE(PG8_SB(1, 1), cB + hstepB + kstep, voffB);
;         PG8_WAIT_V(6); PG8_BAR;
.LBB0_108:
	s_lshl_b32 s5, s5, 5
	s_and_b32 s5, s5, 0x60
	s_lshl_b32 s16, s4, 13
	s_lshl_b32 s17, s5, 7
	s_add_u32 s12, s12, 0x10800000
	s_addc_u32 s13, s13, 0
	s_add_i32 m0, s45, 0x18000
	v_lshl_add_u64 v[6:7], v[6:7], 0, s[38:39]
	s_waitcnt vmcnt(2)
	s_barrier
	global_load_lds_dwordx4 v[6:7], off
	v_lshl_add_u64 v[4:5], v[4:5], 0, s[38:39]
	s_add_i32 m0, s45, 0x1a000
	s_add_i32 s49, s45, 0x8000
	s_add_i32 s50, s45, 0xa000
	global_load_lds_dwordx4 v[4:5], off
	v_lshl_add_u64 v[0:1], v[0:1], 0, s[38:39]
	s_mov_b32 m0, s49
	s_add_u32 s14, s34, 0x40080
	global_load_lds_dwordx4 v[0:1], off
	v_lshl_add_u64 v[0:1], v[2:3], 0, s[38:39]
	s_mov_b32 m0, s50
	s_addc_u32 s15, s35, 0
	global_load_lds_dwordx4 v[0:1], off
	s_add_i32 m0, s45, 0x1c000
	v_lshl_add_u64 v[0:1], s[14:15], 0, v[184:185]
	global_load_lds_dwordx4 v[0:1], off
	v_lshl_add_u64 v[0:1], s[14:15], 0, v[180:181]
	s_add_i32 m0, s45, 0x1e000
	s_cmpk_lt_u32 s0, 0x100
	global_load_lds_dwordx4 v[0:1], off
	v_lshrrev_b32_e32 v1, 1, v8
	v_and_b32_e32 v1, 24, v1
	v_and_b32_e32 v0, 15, v8
	v_lshlrev_b32_e32 v2, 1, v1
	v_lshl_or_b32 v33, s4, 6, v0
	v_lshl_or_b32 v0, v0, 6, v2
	v_lshlrev_b32_e32 v2, 2, v8
	v_and_b32_e32 v2, 32, v2
	v_bitop3_b32 v3, v0, s16, v2 bitop3:0xde
	v_bitop3_b32 v163, s17, v0, v2 bitop3:0xf6
	v_lshlrev_b32_e32 v0, 14, v13
	v_and_b32_e32 v0, 0xffff8000, v0
	v_or_b32_e32 v171, s5, v1
	v_lshl_add_u32 v0, v12, 11, v0
	v_and_b32_e32 v1, 1, v13
	v_lshl_or_b32 v0, v1, 6, v0
	v_lshl_add_u32 v188, v14, 1, v0
	v_lshlrev_b32_e32 v0, 14, v9
	v_and_b32_e32 v0, 0xffff8000, v0
	s_waitcnt vmcnt(0)
	v_lshl_add_u32 v0, v10, 11, v0
	v_and_b32_e32 v1, 1, v9
	v_lshl_or_b32 v0, v1, 6, v0
	v_readlane_b32 s4, v254, 15
	s_cselect_b64 s[14:15], -1, 0
	v_mov_b32_e32 v189, v32
	v_lshl_add_u32 v190, v11, 1, v0
	v_mov_b32_e32 v191, v32
	s_mov_b32 s51, 0
	v_add_u32_e32 v200, 0, v3
	v_readlane_b32 s0, v254, 14
	s_mov_b32 s20, s4
	s_barrier
	v_readlane_b32 s5, v254, 16
	s_branch .LBB0_111

; #define PG8_STAGE(bufoff, gbase, voff) do { _Pragma("unroll") for (int _i = 0; _i < 2; ++_i) \
;         __builtin_amdgcn_global_load_lds((const unsigned*)((const char*)(gbase) + (voff)[_i]), (PG8_LAS unsigned*)(lds + (bufoff) + ldsw + _i * 8192), 16, 0, 0); } while (0)
; #define PG8_WAIT_V(n) asm volatile("s_waitcnt vmcnt(" #n ")" ::: "memory")
; #define PG8_WAIT_L(n) asm volatile("s_waitcnt lgkmcnt(" #n ")" ::: "memory")
; #define PG8_BAR __builtin_amdgcn_s_barrier()
; #define PG8_SCHED __builtin_amdgcn_sched_barrier(0)
; template <class Epi, class Sched, bool ALIGN_EPI = false, bool SP2 = false, bool FP8 = false>
; __device__ __forceinline__ void gemm_phase(PG8_LAS unsigned char* lds, const Gemm g, const Sched& S, const Epi& E, const int tid) {
;     ...
;             PG8_LDB(B0, 0, 0); PG8_LDB(B1, 0, 1); PG8_SCHED; PG8_LDA(At, 0, 0); PG8_STAGE(PG8_SA(1, 1), a1 + hstepA, voffA);
;             PG8_WAIT_V(8); PG8_WAIT_L(0); PG8_BAR; PG8_MMA(0, 0, At, B0); PG8_MMA(0, 1, At, B1); PG8_BAR; PG8_SCHED;
;             PG8_LDA(At, 0, 1); PG8_STAGE(PG8_SB(0, 0), b2, voffB); PG8_STAGE(PG8_SB(0, 1), b2 + hstepB, voffB); PG8_STAGE(PG8_SA(0, 0), a2, voffA);
;             PG8_WAIT_V(8); PG8_WAIT_L(0); PG8_BAR; PG8_MMA(1, 0, At, B0); PG8_MMA(1, 1, At, B1); PG8_BAR; PG8_SCHED;
.LBB0_114:
	s_add_u32 s34, s30, 0xfffc0080
	s_addc_u32 s35, s31, -1
	s_add_i32 s55, 0, 0x10000
	s_cmp_eq_u32 s54, 12
	s_cselect_b32 s37, s22, s35
	s_cselect_b32 s36, s25, s34
	s_cselect_b32 s35, s17, s53
	s_cselect_b32 s34, s33, s52
	s_add_i32 s56, 0, 0x14000
	v_add_u32_e32 v0, s55, v163
	v_add_u32_e32 v12, s56, v163
	ds_read_b128 v[16:19], v0
	ds_read_b128 v[20:23], v0 offset:1024
	ds_read_b128 v[24:27], v0 offset:2048
	ds_read_b128 v[28:31], v0 offset:3072
	ds_read_b128 v[0:3], v12
	ds_read_b128 v[4:7], v12 offset:1024
	ds_read_b128 v[8:11], v12 offset:2048
	ds_read_b128 v[12:15], v12 offset:3072
	v_lshl_add_u64 v[164:165], s[30:31], 0, v[188:189]
	s_add_i32 m0, s45, 0xc000
	ds_read_b128 v[192:195], v200
	ds_read_b128 v[196:199], v200 offset:1024
	ds_read_b128 v[220:223], v200 offset:2048
	ds_read_b128 v[224:227], v200 offset:3072
	ds_read_b128 v[228:231], v200 offset:4096
	ds_read_b128 v[232:235], v200 offset:5120
	ds_read_b128 v[236:239], v200 offset:6144
	ds_read_b128 v[240:243], v200 offset:7168
	global_load_lds_dwordx4 v[164:165], off
	v_lshl_add_u64 v[164:165], s[30:31], 0, v[190:191]
	s_add_i32 m0, s45, 0xe000
	s_nop 0
	global_load_lds_dwordx4 v[164:165], off
	s_cmp_eq_i32 s54, -2
	s_cbranch_scc1 .Lskw_1_0
	s_waitcnt vmcnt(8)
.Lskw_1_0:
	s_waitcnt lgkmcnt(0)
	s_barrier
	s_setprio 1
	s_waitcnt lgkmcnt(0)
	v_mfma_f32_16x16x128_f8f6f4 v[158:161], v[16:23], v[192:199], v[158:161]
	v_mfma_f32_16x16x128_f8f6f4 v[154:157], v[24:31], v[192:199], v[154:157]
	v_mfma_f32_16x16x128_f8f6f4 v[142:145], v[16:23], v[220:227], v[142:145]
	v_mfma_f32_16x16x128_f8f6f4 v[138:141], v[24:31], v[220:227], v[138:141]
	v_mfma_f32_16x16x128_f8f6f4 v[126:129], v[16:23], v[228:235], v[126:129]
	v_mfma_f32_16x16x128_f8f6f4 v[122:125], v[24:31], v[228:235], v[122:125]
	v_mfma_f32_16x16x128_f8f6f4 v[110:113], v[16:23], v[236:243], v[110:113]
	v_mfma_f32_16x16x128_f8f6f4 v[106:109], v[24:31], v[236:243], v[106:109]
	s_setprio 0
	s_setprio 1
	v_mfma_f32_16x16x128_f8f6f4 v[150:153], v[0:7], v[192:199], v[150:153]
	v_mfma_f32_16x16x128_f8f6f4 v[146:149], v[8:15], v[192:199], v[146:149]
	v_mfma_f32_16x16x128_f8f6f4 v[134:137], v[0:7], v[220:227], v[134:137]
	v_mfma_f32_16x16x128_f8f6f4 v[130:133], v[8:15], v[220:227], v[130:133]
	v_mfma_f32_16x16x128_f8f6f4 v[118:121], v[0:7], v[228:235], v[118:121]
	v_mfma_f32_16x16x128_f8f6f4 v[114:117], v[8:15], v[228:235], v[114:117]
	v_mfma_f32_16x16x128_f8f6f4 v[102:105], v[0:7], v[236:243], v[102:105]
	v_mfma_f32_16x16x128_f8f6f4 v[98:101], v[8:15], v[236:243], v[98:101]
	s_setprio 0
	s_barrier
	s_add_i32 s55, s55, s44
	v_lshl_add_u64 v[192:193], s[34:35], 0, v[184:185]
	s_mov_b32 m0, s55
	ds_read_b128 v[220:223], v200 offset:16384
	ds_read_b128 v[224:227], v200 offset:17408
	ds_read_b128 v[228:231], v200 offset:18432
	ds_read_b128 v[232:235], v200 offset:19456
	ds_read_b128 v[236:239], v200 offset:20480
	ds_read_b128 v[240:243], v200 offset:21504
	ds_read_b128 v[244:247], v200 offset:22528
	ds_read_b128 v[248:251], v200 offset:23552
	global_load_lds_dwordx4 v[192:193], off
	s_add_i32 m0, s55, 0x2000
	s_add_u32 s58, s34, 0x40000
	v_lshl_add_u64 v[194:195], s[34:35], 0, v[180:181]
	s_addc_u32 s59, s35, 0
	s_add_i32 s55, s56, s44
	global_load_lds_dwordx4 v[194:195], off
	v_lshl_add_u64 v[164:165], s[58:59], 0, v[184:185]
	s_mov_b32 m0, s55
	v_lshl_add_u64 v[196:197], s[36:37], 0, v[186:187]
	global_load_lds_dwordx4 v[164:165], off
	v_lshl_add_u64 v[164:165], s[58:59], 0, v[180:181]
	s_add_i32 m0, s55, 0x2000
	v_lshl_add_u64 v[198:199], s[36:37], 0, v[182:183]
	global_load_lds_dwordx4 v[164:165], off
	s_mov_b32 m0, s45
	s_nop 0
	global_load_lds_dwordx4 v[196:197], off
	s_mov_b32 m0, s46
	s_nop 0
	global_load_lds_dwordx4 v[198:199], off
	s_cmp_eq_i32 s54, -2
	s_cbranch_scc1 .Lskw_1_1
	s_waitcnt vmcnt(8)
; #define PG8_STAGE(bufoff, gbase, voff) do { _Pragma("unroll") for (int _i = 0; _i < 2; ++_i) \
;         __builtin_amdgcn_global_load_lds((const unsigned*)((const char*)(gbase) + (voff)[_i]), (PG8_LAS unsigned*)(lds + (bufoff) + ldsw + _i * 8192), 16, 0, 0); } while (0)
; #define PG8_WAIT_V(n) asm volatile("s_waitcnt vmcnt(" #n ")" ::: "memory")
; #define PG8_WAIT_L(n) asm volatile("s_waitcnt lgkmcnt(" #n ")" ::: "memory")
; #define PG8_BAR __builtin_amdgcn_s_barrier()
; #define PG8_SCHED __builtin_amdgcn_sched_barrier(0)
;     __device__ __forceinline__ void operator()(const f32x4 (&acc)[2][2][4][2], const Unit& u, int wr, int wc, int fr, int fq) const {
;     ...
;             for (int m = 0; m < 4; ++m) { const int row = row0 + ai * HALF + m * 16; const float rs = __builtin_amdgcn_rsqf((float)ss[row] * (SS_INV / 2048.0f) + RMS_EPS) * osc;
; template <class Epi, class Sched, bool ALIGN_EPI = false, bool SP2 = false, bool FP8 = false>
; __device__ __forceinline__ void gemm_phase(PG8_LAS unsigned char* lds, const Gemm g, const Sched& S, const Epi& E, const int tid) {
;     ...
;             PG8_WAIT_V(8); PG8_WAIT_L(0); PG8_BAR; PG8_MMA(1, 0, At, B0); PG8_MMA(1, 1, At, B1); PG8_BAR; PG8_SCHED;
;             PG8_LDB(B0, 1, 0); PG8_LDB(B1, 1, 1); PG8_SCHED; PG8_LDA(At, 1, 0); PG8_STAGE(PG8_SA(0, 1), a2 + hstepA, voffA);
;             PG8_WAIT_V(8); PG8_WAIT_L(0); PG8_BAR; PG8_MMA(0, 0, At, B0); PG8_MMA(0, 1, At, B1); PG8_BAR; PG8_SCHED;
;             PG8_LDA(At, 1, 1); PG8_STAGE(PG8_SB(1, 0), b3, voffB); PG8_STAGE(PG8_SB(1, 1), b3 + hstepB, voffB); PG8_STAGE(PG8_SA(1, 0), a3, voffA);
;             PG8_WAIT_V(8); PG8_WAIT_L(0); PG8_BAR; PG8_MMA(1, 0, At, B0); PG8_MMA(1, 1, At, B1); PG8_BAR; PG8_SCHED;
.Lskw_1_1:
	s_waitcnt lgkmcnt(0)
	s_barrier
	s_setprio 1
	s_waitcnt lgkmcnt(0)
	v_mfma_f32_16x16x128_f8f6f4 v[94:97], v[16:23], v[220:227], v[94:97]
	v_mfma_f32_16x16x128_f8f6f4 v[90:93], v[24:31], v[220:227], v[90:93]
	v_mfma_f32_16x16x128_f8f6f4 v[78:81], v[16:23], v[228:235], v[78:81]
	v_mfma_f32_16x16x128_f8f6f4 v[74:77], v[24:31], v[228:235], v[74:77]
	v_mfma_f32_16x16x128_f8f6f4 v[62:65], v[16:23], v[236:243], v[62:65]
	v_mfma_f32_16x16x128_f8f6f4 v[58:61], v[24:31], v[236:243], v[58:61]
	v_mfma_f32_16x16x128_f8f6f4 v[46:49], v[16:23], v[244:251], v[46:49]
	v_mfma_f32_16x16x128_f8f6f4 v[42:45], v[24:31], v[244:251], v[42:45]
	s_setprio 0
	s_setprio 1
	v_mfma_f32_16x16x128_f8f6f4 v[86:89], v[0:7], v[220:227], v[86:89]
	v_mfma_f32_16x16x128_f8f6f4 v[82:85], v[8:15], v[220:227], v[82:85]
	v_mfma_f32_16x16x128_f8f6f4 v[70:73], v[0:7], v[228:235], v[70:73]
	v_mfma_f32_16x16x128_f8f6f4 v[66:69], v[8:15], v[228:235], v[66:69]
	v_mfma_f32_16x16x128_f8f6f4 v[54:57], v[0:7], v[236:243], v[54:57]
	v_mfma_f32_16x16x128_f8f6f4 v[50:53], v[8:15], v[236:243], v[50:53]
	v_mfma_f32_16x16x128_f8f6f4 v[38:41], v[0:7], v[244:251], v[38:41]
	v_mfma_f32_16x16x128_f8f6f4 v[34:37], v[8:15], v[244:251], v[34:37]
	s_setprio 0
	s_barrier
	s_add_i32 s55, 0, 0x18000
	s_add_i32 s56, 0, 0x1c000
	v_add_u32_e32 v12, s55, v163
	v_add_u32_e32 v28, s56, v163
	ds_read_b128 v[0:3], v12
	ds_read_b128 v[4:7], v12 offset:1024
	ds_read_b128 v[8:11], v12 offset:2048
	ds_read_b128 v[12:15], v12 offset:3072
	ds_read_b128 v[16:19], v28
	ds_read_b128 v[20:23], v28 offset:1024
	ds_read_b128 v[24:27], v28 offset:2048
	ds_read_b128 v[28:31], v28 offset:3072
	s_add_u32 s36, s36, 0x40000
	s_addc_u32 s37, s37, 0
	s_mov_b32 m0, s47
	v_lshl_add_u64 v[164:165], s[36:37], 0, v[186:187]
	ds_read_b128 v[220:223], v200 offset:32768
	ds_read_b128 v[224:227], v200 offset:33792
	ds_read_b128 v[228:231], v200 offset:34816
	ds_read_b128 v[232:235], v200 offset:35840
	ds_read_b128 v[236:239], v200 offset:36864
	ds_read_b128 v[240:243], v200 offset:37888
	ds_read_b128 v[244:247], v200 offset:38912
	ds_read_b128 v[248:251], v200 offset:39936
	global_load_lds_dwordx4 v[164:165], off
	v_lshl_add_u64 v[164:165], s[36:37], 0, v[182:183]
	s_mov_b32 m0, s48
	s_nop 0
	global_load_lds_dwordx4 v[164:165], off
	s_waitcnt vmcnt(8)
	s_waitcnt lgkmcnt(0)
	s_barrier
	s_setprio 1
	s_waitcnt lgkmcnt(0)
	v_mfma_f32_16x16x128_f8f6f4 v[158:161], v[0:7], v[220:227], v[158:161]
	v_mfma_f32_16x16x128_f8f6f4 v[154:157], v[8:15], v[220:227], v[154:157]
	v_mfma_f32_16x16x128_f8f6f4 v[142:145], v[0:7], v[228:235], v[142:145]
	v_mfma_f32_16x16x128_f8f6f4 v[138:141], v[8:15], v[228:235], v[138:141]
	v_mfma_f32_16x16x128_f8f6f4 v[126:129], v[0:7], v[236:243], v[126:129]
	v_mfma_f32_16x16x128_f8f6f4 v[122:125], v[8:15], v[236:243], v[122:125]
	v_mfma_f32_16x16x128_f8f6f4 v[110:113], v[0:7], v[244:251], v[110:113]
	v_mfma_f32_16x16x128_f8f6f4 v[106:109], v[8:15], v[244:251], v[106:109]
	s_setprio 0
	s_setprio 1
	v_mfma_f32_16x16x128_f8f6f4 v[150:153], v[16:23], v[220:227], v[150:153]
	v_mfma_f32_16x16x128_f8f6f4 v[146:149], v[24:31], v[220:227], v[146:149]
	v_mfma_f32_16x16x128_f8f6f4 v[134:137], v[16:23], v[228:235], v[134:137]
	v_mfma_f32_16x16x128_f8f6f4 v[130:133], v[24:31], v[228:235], v[130:133]
	v_mfma_f32_16x16x128_f8f6f4 v[118:121], v[16:23], v[236:243], v[118:121]
	v_mfma_f32_16x16x128_f8f6f4 v[114:117], v[24:31], v[236:243], v[114:117]
	v_mfma_f32_16x16x128_f8f6f4 v[102:105], v[16:23], v[244:251], v[102:105]
	v_mfma_f32_16x16x128_f8f6f4 v[98:101], v[24:31], v[244:251], v[98:101]
	s_setprio 0
	s_barrier
	s_add_i32 s36, s55, s44
	v_lshl_add_u64 v[164:165], v[192:193], 0, s[38:39]
	s_mov_b32 m0, s36
	ds_read_b128 v[220:223], v200 offset:49152
	ds_read_b128 v[224:227], v200 offset:50176
	ds_read_b128 v[228:231], v200 offset:51200
	ds_read_b128 v[232:235], v200 offset:52224
	ds_read_b128 v[236:239], v200 offset:53248
	ds_read_b128 v[240:243], v200 offset:54272
	ds_read_b128 v[244:247], v200 offset:55296
	ds_read_b128 v[248:251], v200 offset:56320
	global_load_lds_dwordx4 v[164:165], off
	s_add_i32 m0, s36, 0x2000
	s_add_u32 s34, s34, 0x40080
	v_lshl_add_u64 v[164:165], v[194:195], 0, s[38:39]
	s_addc_u32 s35, s35, 0
	s_add_i32 s36, s56, s44
	global_load_lds_dwordx4 v[164:165], off
	v_lshl_add_u64 v[164:165], s[34:35], 0, v[184:185]
	s_mov_b32 m0, s36
	s_nop 0
	global_load_lds_dwordx4 v[164:165], off
	v_lshl_add_u64 v[164:165], s[34:35], 0, v[180:181]
	s_add_i32 m0, s36, 0x2000
	s_nop 0
	global_load_lds_dwordx4 v[164:165], off
	v_lshl_add_u64 v[164:165], v[196:197], 0, s[38:39]
	s_mov_b32 m0, s49
	s_nop 0
	global_load_lds_dwordx4 v[164:165], off
	v_lshl_add_u64 v[164:165], v[198:199], 0, s[38:39]
	s_mov_b32 m0, s50
	s_nop 0
	global_load_lds_dwordx4 v[164:165], off
	s_waitcnt vmcnt(8)
	s_waitcnt lgkmcnt(0)
	s_barrier
	s_setprio 1
	s_waitcnt lgkmcnt(0)
	v_mfma_f32_16x16x128_f8f6f4 v[94:97], v[0:7], v[220:227], v[94:97]
	v_mfma_f32_16x16x128_f8f6f4 v[90:93], v[8:15], v[220:227], v[90:93]
	v_mfma_f32_16x16x128_f8f6f4 v[78:81], v[0:7], v[228:235], v[78:81]
	v_mfma_f32_16x16x128_f8f6f4 v[74:77], v[8:15], v[228:235], v[74:77]
	v_mfma_f32_16x16x128_f8f6f4 v[62:65], v[0:7], v[236:243], v[62:65]
	v_mfma_f32_16x16x128_f8f6f4 v[58:61], v[8:15], v[236:243], v[58:61]
	v_mfma_f32_16x16x128_f8f6f4 v[46:49], v[0:7], v[244:251], v[46:49]
	v_mfma_f32_16x16x128_f8f6f4 v[42:45], v[8:15], v[244:251], v[42:45]
	s_setprio 0
	s_setprio 1
	v_mfma_f32_16x16x128_f8f6f4 v[86:89], v[16:23], v[220:227], v[86:89]
	v_mfma_f32_16x16x128_f8f6f4 v[82:85], v[24:31], v[220:227], v[82:85]
	v_mfma_f32_16x16x128_f8f6f4 v[70:73], v[16:23], v[228:235], v[70:73]
	v_mfma_f32_16x16x128_f8f6f4 v[66:69], v[24:31], v[228:235], v[66:69]
	v_mfma_f32_16x16x128_f8f6f4 v[54:57], v[16:23], v[236:243], v[54:57]
	v_mfma_f32_16x16x128_f8f6f4 v[50:53], v[24:31], v[236:243], v[50:53]
	v_mfma_f32_16x16x128_f8f6f4 v[38:41], v[16:23], v[244:251], v[38:41]
	v_mfma_f32_16x16x128_f8f6f4 v[34:37], v[24:31], v[244:251], v[34:37]
	s_setprio 0
	s_barrier
	s_add_i32 s54, s54, 2
	s_add_u32 s30, s30, 0x100
	s_addc_u32 s31, s31, 0
	s_add_u32 s52, s52, 0x100
	s_addc_u32 s53, s53, 0
	s_cmp_gt_u32 s54, 13
	s_cbranch_scc0 .LBB0_114
	v_lshl_add_u32 v0, s20, 8, v33
	v_ashrrev_i32_e32 v1, 31, v0
	v_lshl_add_u64 v[2:3], v[0:1], 3, s[8:9]
	global_load_dwordx2 v[220:221], v[2:3], off
	global_load_dwordx2 v[222:223], v[2:3], off offset:128
	global_load_dwordx2 v[224:225], v[2:3], off offset:256
	global_load_dwordx2 v[226:227], v[2:3], off offset:384
	global_load_dwordx2 v[228:229], v[2:3], off offset:1024
	global_load_dwordx2 v[230:231], v[2:3], off offset:1152
	global_load_dwordx2 v[232:233], v[2:3], off offset:1280
	global_load_dwordx2 v[234:235], v[2:3], off offset:1408
	s_and_b64 vcc, exec, s[14:15]
	s_cbranch_vccz .LBB0_117
	s_barrier

; __device__ __forceinline__ void attn_compute(LAS unsigned char* lds, const AttnJob& J, int tid) {
;     ...
;     const int dbase = 144 + l15 - quad * 4;
;     if (J.blk != 0) {
; #pragma unroll
;         for (int j = 0; j < 4; ++j) { if (dbase - 16 - j > J.maxdist) st[1][j] = NEG_BIG; if (dbase - 144 - j < 0) st[9][j] = NEG_BIG; }
;     } else {
;         const int kbase = idxk0 + 16 * w + quad * 4;
; #pragma unroll
;         for (int t = 1; t < 10; ++t)
; #pragma unroll
;             for (int j = 0; j < 4; ++j) { const int dist = dbase - 16 * t - j; const int kidx = kbase + 16 * t + j;
;                 const bool ok = (dist >= 0) && (dist <= J.maxdist) && (kidx >= 0); if (!ok) st[t][j] = NEG_BIG; }
; __global__ void __launch_bounds__(NTHR, 2) mk_fwd(Args args_unused) {
;     ...
;                 float gq[8], gk[8];
; #pragma unroll
;                 for (int t = 0; t < 8; ++t) { gq[t] = args.a_q_norm[l * 64 + c8 + t] * (0.125f * 1.4426950408889634f); gk[t] = args.a_k_norm[l * 64 + c8 + t]; }
;                 int u = vcu;
;                 if (u < 2304) { AttnJob J = make_job_a(u, OAG, LSE); AttnPre P; attn_prefetch(P, PROJ, cAB, sAB, J, tq);
.LBB0_184:
	s_or_b64 exec, exec, s[16:17]
	v_and_b32_e32 v35, 64, v207
	v_xor_b32_e32 v34, 1, v207
	v_add_u32_e32 v35, 64, v35
	v_cmp_lt_i32_e32 vcc, v34, v35
	v_readlane_b32 s16, v252, 42
	v_readlane_b32 s17, v252, 43
	v_cndmask_b32_e32 v34, v207, v34, vcc
	v_lshlrev_b32_e32 v144, 2, v34
	v_xor_b32_e32 v34, 2, v207
	v_cmp_lt_i32_e32 vcc, v34, v35
	s_add_u32 s0, s16, 0x30c00000
	s_addc_u32 s33, s17, 0
	v_cndmask_b32_e32 v34, v207, v34, vcc
	v_lshlrev_b32_e32 v145, 2, v34
	v_xor_b32_e32 v34, 4, v207
	s_add_u32 s96, s16, 0x2e800000
	v_cmp_lt_i32_e32 vcc, v34, v35
	s_addc_u32 s97, s17, 0
	v_and_b32_e32 v33, 7, v128
	v_cndmask_b32_e32 v34, v207, v34, vcc
	s_movk_i32 s17, 0x90
	v_readlane_b32 s16, v254, 61
	s_waitcnt vmcnt(5)
	v_mul_f32_e32 v142, 0x3e38aa3b, v70
	v_lshl_add_u32 v33, v33, 4, 0
	v_lshlrev_b32_e32 v146, 2, v34
	v_mul_lo_u32 v34, v130, s17
	v_ashrrev_i32_e32 v70, 6, v128
	s_add_u32 s26, s96, s16
	v_readlane_b32 s16, v254, 60
	s_waitcnt vmcnt(4)
	v_mul_f32_e32 v136, 0x3e38aa3b, v72
	v_mul_f32_e32 v140, 0x3e38aa3b, v68
	v_mul_f32_e32 v143, 0x3e38aa3b, v71
	v_add_u32_e32 v68, 0x2400, v34
	v_add_u32_e32 v147, v33, v34
	v_and_b32_e32 v34, 15, v128
	v_bfe_u32 v71, v128, 4, 2
	v_lshlrev_b32_e32 v72, 4, v70
	s_addc_u32 s27, s97, s16
	v_readlane_b32 s16, v254, 63
	v_or_b32_e32 v149, v72, v34
	v_or_b32_e32 v85, 0x90, v34
	v_lshlrev_b32_e32 v34, 2, v71
	s_add_u32 s24, s0, s16
	v_readlane_b32 s16, v254, 62
	v_sub_u32_e32 v85, v85, v34
	s_addc_u32 s25, s33, s16
	s_movk_i32 s16, 0x80
	v_subrev_u32_e32 v86, 17, v85
	s_movk_i32 s20, 0x91
	v_cmp_gt_i32_e64 s[28:29], s16, v128
	v_subrev_co_u32_e32 v87, vcc, s20, v85
	s_movk_i32 s22, 0xff7f
	v_cmp_lt_u32_e64 s[44:45], s16, v86
	s_movk_i32 s16, 0x93
	v_cmp_gt_u32_e64 s[42:43], s22, v87
	v_subrev_co_u32_e64 v87, s[46:47], s16, v85
	v_cmp_gt_u32_e64 s[48:49], s22, v87
	v_add_u32_e32 v87, 0xffffff6c, v85
	v_cmp_gt_u32_e64 s[50:51], s22, v87
	v_add_u32_e32 v87, -16, v85
	s_movk_i32 s16, 0x81
	v_writelane_b32 v252, s28, 46
	v_cmp_lt_i32_e64 s[58:59], 7, v70
	v_cmp_gt_u32_e64 s[52:53], s16, v87
	v_writelane_b32 v252, s29, 47
	s_and_b64 s[30:31], s[58:59], s[52:53]
	v_writelane_b32 v252, s30, 48
	v_cmp_gt_u32_e64 s[54:55], s16, v86
	v_subrev_u32_e32 v86, 18, v85
	v_writelane_b32 v252, s31, 49
	s_and_b64 s[30:31], s[58:59], s[54:55]
	v_writelane_b32 v252, s30, 50
	v_cmp_gt_u32_e64 s[56:57], s16, v86
	v_subrev_u32_e32 v86, 19, v85
	v_writelane_b32 v252, s31, 51
	s_and_b64 s[30:31], s[58:59], s[56:57]
	v_writelane_b32 v252, s30, 52
	v_cmp_gt_u32_e64 s[60:61], s16, v86
	s_movk_i32 s28, 0x92
	v_writelane_b32 v252, s31, 53
	s_and_b64 s[30:31], s[58:59], s[60:61]
	s_movk_i32 s16, 0x8f
	v_writelane_b32 v252, s30, 54
	v_cmp_lt_i32_e64 s[60:61], 6, v70
	v_cmp_lt_i32_e64 s[62:63], 5, v70
	v_cmp_lt_i32_e64 s[64:65], 4, v70
	v_cmp_lt_i32_e64 s[66:67], 3, v70
	v_cmp_lt_i32_e64 s[68:69], 2, v70
	v_cmp_lt_i32_e64 s[70:71], 1, v70
	v_cmp_lt_i32_e64 s[72:73], 0, v70
	v_cmp_lt_i32_e64 s[80:81], -1, v70
	v_cmp_lt_u32_e64 s[74:75], s16, v85
	v_cmp_lt_u32_e64 s[76:77], s17, v85
	v_cmp_lt_u32_e64 s[78:79], s20, v85
	v_cmp_lt_u32_e64 s[82:83], s28, v85
	v_xor_b32_e32 v70, 16, v207
	v_writelane_b32 v252, s31, 55
	s_and_b64 s[30:31], s[80:81], s[74:75]
	s_and_b64 s[76:77], s[80:81], s[76:77]
	s_and_b64 s[78:79], s[80:81], s[78:79]
	s_and_b64 s[80:81], s[80:81], s[82:83]
	v_cmp_lt_i32_e64 s[82:83], v70, v35
	v_cmp_gt_u32_e64 s[84:85], s28, v85
	v_mul_f32_e32 v137, 0x3e38aa3b, v73
	v_cndmask_b32_e64 v70, v207, v70, s[82:83]
	v_lshlrev_b32_e32 v150, 2, v70
	v_xor_b32_e32 v70, 32, v207
	v_cmp_lt_i32_e64 s[82:83], v70, v35
	v_mul_f32_e32 v139, 0x3e38aa3b, v75
	v_mul_lo_u32 v73, v149, s17
	v_cndmask_b32_e64 v35, v207, v70, s[82:83]
	v_lshlrev_b32_e32 v151, 2, v35
	v_bfe_u32 v35, v128, 2, 2
	v_or3_b32 v35, v72, v35, v34
	v_lshlrev_b32_e32 v75, 4, v71
	v_writelane_b32 v252, s30, 56
	v_and_b32_e32 v70, 24, v129
	v_mul_lo_u32 v35, v35, s17
	s_and_b64 s[84:85], s[46:47], s[84:85]
	v_readlane_b32 s16, v254, 24
	v_mul_f32_e32 v138, 0x3e38aa3b, v74
	v_mul_f32_e32 v141, 0x3e38aa3b, v69
	v_mul_lo_u32 v69, v128, s17
	v_add_u32_e32 v74, 0, v73
	v_add_u32_e32 v76, 0, v75
	v_add_u32_e32 v77, 0x900, v73
	v_add_u32_e32 v78, 0x1200, v73
	v_add_u32_e32 v79, 0x1b00, v73
	v_add_u32_e32 v80, 0x2400, v73
	v_add_u32_e32 v81, 0x2d00, v73
	v_add_u32_e32 v82, 0x3600, v73
	v_add_u32_e32 v83, 0x3f00, v73
	v_add_u32_e32 v84, 0x4800, v73
	v_add_u32_e32 v73, 0x5100, v73
	v_cmp_gt_u32_e64 s[88:89], s17, v85
	v_writelane_b32 v252, s31, 57
	v_add3_u32 v152, 0, v70, v35
	s_and_b64 s[86:87], s[84:85], vcc
	s_mov_b32 s34, s16
	v_readlane_b32 s16, v254, 23
	v_add_u32_e32 v148, 0xe100, v147
	v_add_u32_e32 v153, 0xe100, v152
	v_cmp_eq_u32_e64 s[82:83], 0, v71
	v_add_u32_e32 v154, v33, v68
	v_add_u32_e32 v155, 0, v69
	v_add_u32_e32 v156, v74, v75
	v_add_u32_e32 v157, v76, v77
	v_add_u32_e32 v158, v76, v78
	v_add_u32_e32 v159, v76, v79
	v_add_u32_e32 v160, v76, v80
	v_add_u32_e32 v161, v76, v81
	v_add_u32_e32 v163, v76, v82
	v_add_u32_e32 v171, v76, v83
	v_add_u32_e32 v180, v76, v84
	v_add_u32_e32 v181, v76, v73
	v_lshlrev_b32_e32 v118, 1, v34
	s_and_b64 s[88:89], s[86:87], s[88:89]
	v_readlane_b32 s58, v254, 25
	v_readlane_b32 s56, v252, 0
	v_readlane_b32 s52, v252, 7
	s_mov_b32 s36, s16
	v_readlane_b32 s54, v254, 45
	s_waitcnt vmcnt(0)
	s_branch .LBB0_186

; #define LAS __attribute__((address_space(3)))
; __device__ __forceinline__ void unpack8(const u32x4 r, float (&v)[8]) { v[0] = bf_lo(r.x); v[1] = bf_hi(r.x); v[2] = bf_lo(r.y); v[3] = bf_hi(r.y); v[4] = bf_lo(r.z); v[5] = bf_hi(r.z); v[6] = bf_lo(r.w); v[7] = bf_hi(r.w); }
; __device__ __forceinline__ u32x4 pack8(const float (&v)[8]) { u32x4 w; w.x = cvt_pk_bf16(v[0], v[1]); w.y = cvt_pk_bf16(v[2], v[3]); w.z = cvt_pk_bf16(v[4], v[5]); w.w = cvt_pk_bf16(v[6], v[7]); return w; }
; __device__ __forceinline__ void norm_store(LAS bf16_t* dst, const u32x4 raw, const float (&g)[8]) {
;     float v[8]; unpack8(raw, v); float ss = 0.f;
; #pragma unroll
;     for (int t = 0; t < 8; ++t) ss += v[t] * v[t];
;     ss += __shfl_xor(ss, 1); ss += __shfl_xor(ss, 2); ss += __shfl_xor(ss, 4);
;     const float rs = __builtin_amdgcn_rsqf(ss * (1.0f / 64.0f) + EPS);
;     float o[8];
; #pragma unroll
;     for (int t = 0; t < 8; ++t) o[t] = v[t] * rs * g[t];
;     *(LAS u32x4*)dst = pack8(o);
; }
; __device__ __forceinline__ void attn_stage(LAS unsigned char* lds, const AttnPre& P, const float (&gq)[8], const float (&gk)[8], int tid) {
;     LAS bf16_t* Qs = (LAS bf16_t*)(lds + A_QS); LAS bf16_t* Ks = (LAS bf16_t*)(lds + A_KS); LAS bf16_t* Vs = (LAS bf16_t*)(lds + A_VS);
;     const int c = tid & 7, i0 = tid >> 3;
; #pragma unroll
;     for (int it = 0; it < 2; ++it) norm_store(Qs + (i0 + 64 * it) * AQP + 8 * c, P.q[it], gq);
.LBB0_186:
	v_and_b32_e32 v70, 0xffff0000, v8
	v_lshlrev_b32_e32 v33, 16, v8
	v_mul_f32_e32 v75, v70, v70
	v_lshlrev_b32_e32 v71, 16, v9
	v_fmac_f32_e32 v75, v33, v33
	v_and_b32_e32 v72, 0xffff0000, v9
	v_fmac_f32_e32 v75, v71, v71
	v_lshlrev_b32_e32 v73, 16, v10
	v_fmac_f32_e32 v75, v72, v72
	v_and_b32_e32 v74, 0xffff0000, v10
	v_fmac_f32_e32 v75, v73, v73
	v_and_b32_e32 v34, 0xffff0000, v11
	v_lshlrev_b32_e32 v35, 16, v11
	v_fmac_f32_e32 v75, v74, v74
	v_pk_mul_f32 v[68:69], v[34:35], v[34:35]
	s_nop 0
	v_add_f32_e32 v69, v69, v75
	v_add_f32_e32 v68, v68, v69
	ds_bpermute_b32 v69, v144, v68
	s_waitcnt lgkmcnt(0)
	v_add_f32_e32 v68, v68, v69
	ds_bpermute_b32 v69, v145, v68
	s_waitcnt lgkmcnt(0)
	v_add_f32_e32 v68, v68, v69
	ds_bpermute_b32 v69, v146, v68
	s_waitcnt lgkmcnt(0)
	v_add_f32_e32 v68, v68, v69
	v_fmamk_f32 v68, v68, 0x3c800000, v204
	v_rsq_f32_e32 v68, v68
	s_nop 0
	v_mul_f32_e32 v69, v68, v70
	v_mul_f32_e32 v70, v68, v71
	v_mul_f32_e32 v33, v68, v33
	v_mul_f32_e32 v69, v137, v69
	v_mul_f32_e32 v70, v138, v70
	v_mul_f32_e32 v71, v68, v72
	v_mul_f32_e32 v72, v68, v73
	v_mul_f32_e32 v73, v68, v74
	v_mul_f32_e32 v33, v136, v33
	v_mul_f32_e32 v71, v139, v71
	v_mul_f32_e32 v72, v140, v72
	v_mul_f32_e32 v73, v141, v73
	v_mul_f32_e32 v35, v68, v35
	v_mul_f32_e32 v34, v68, v34
	v_cvt_pk_bf16_f32 v68, v33, v69
	v_cvt_pk_bf16_f32 v69, v70, v71
	v_cvt_pk_bf16_f32 v70, v72, v73
	v_mul_f32_e32 v35, v142, v35
	v_mul_f32_e32 v34, v143, v34
	v_cvt_pk_bf16_f32 v71, v35, v34
	ds_write_b128 v147, v[68:71]
	v_and_b32_e32 v70, 0xffff0000, v12
	v_lshlrev_b32_e32 v33, 16, v12
	v_mul_f32_e32 v75, v70, v70
	v_lshlrev_b32_e32 v71, 16, v13
	v_fmac_f32_e32 v75, v33, v33
	v_and_b32_e32 v72, 0xffff0000, v13
	v_fmac_f32_e32 v75, v71, v71
	v_lshlrev_b32_e32 v73, 16, v14
	v_fmac_f32_e32 v75, v72, v72
	v_and_b32_e32 v74, 0xffff0000, v14
	v_fmac_f32_e32 v75, v73, v73
	v_and_b32_e32 v34, 0xffff0000, v15
	v_lshlrev_b32_e32 v35, 16, v15
	v_fmac_f32_e32 v75, v74, v74
	v_pk_mul_f32 v[68:69], v[34:35], v[34:35]
	s_nop 0
	v_add_f32_e32 v69, v69, v75
	v_add_f32_e32 v68, v68, v69
	ds_bpermute_b32 v69, v144, v68
	s_waitcnt lgkmcnt(0)
	v_add_f32_e32 v68, v68, v69
	ds_bpermute_b32 v69, v145, v68
	s_waitcnt lgkmcnt(0)
	v_add_f32_e32 v68, v68, v69
	ds_bpermute_b32 v69, v146, v68
	s_waitcnt lgkmcnt(0)
	v_add_f32_e32 v68, v68, v69
	v_fmamk_f32 v68, v68, 0x3c800000, v204
	v_rsq_f32_e32 v68, v68
	s_nop 0
	v_mul_f32_e32 v69, v68, v70
	v_mul_f32_e32 v70, v68, v71
	v_mul_f32_e32 v71, v68, v72
	v_mul_f32_e32 v33, v68, v33
	v_mul_f32_e32 v69, v137, v69
	v_mul_f32_e32 v70, v138, v70
	v_mul_f32_e32 v71, v139, v71
	v_mul_f32_e32 v72, v68, v73
	v_mul_f32_e32 v73, v68, v74
	v_mul_f32_e32 v35, v68, v35
	v_mul_f32_e32 v34, v68, v34
	v_mul_f32_e32 v33, v136, v33
	v_mul_f32_e32 v72, v140, v72
	v_mul_f32_e32 v73, v141, v73
	v_mul_f32_e32 v35, v142, v35
	v_mul_f32_e32 v34, v143, v34
	v_cvt_pk_bf16_f32 v68, v33, v69
	v_cvt_pk_bf16_f32 v69, v70, v71
	v_cvt_pk_bf16_f32 v70, v72, v73
	v_cvt_pk_bf16_f32 v71, v35, v34
	ds_write_b128 v147, v[68:71] offset:9216
	s_and_saveexec_b64 s[28:29], s[4:5]
	s_cbranch_execnz .LBB0_213
	s_or_b64 exec, exec, s[28:29]
	s_and_saveexec_b64 s[28:29], s[6:7]
	s_cbranch_execnz .LBB0_214

; #define LAS __attribute__((address_space(3)))
; __device__ __forceinline__ f32x4 mfma16(bf16x8 a, bf16x8 b, f32x4 c) { return __builtin_amdgcn_mfma_f32_16x16x32_bf16(a, b, c, 0, 0, 0); }
; __device__ __forceinline__ void attn_compute(LAS unsigned char* lds, const AttnJob& J, int tid) {
;     LAS bf16_t* Qs = (LAS bf16_t*)(lds + A_QS); LAS bf16_t* Ks = (LAS bf16_t*)(lds + A_KS); LAS bf16_t* Vs = (LAS bf16_t*)(lds + A_VS);
;     const int idxq0 = J.blk * 128, idxk0 = J.blk * 128 - 144;
;     const int w = tid >> 6, lane = tid & 63, l15 = lane & 15, quad = lane >> 4;
;     bf16x8 qf[2];
; #pragma unroll
;     for (int kk = 0; kk < 2; ++kk) qf[kk] = *(const LAS bf16x8*)(Qs + (16 * w + l15) * AQP + kk * 32 + quad * 8);
;     f32x4 st[10];
;     st[0] = (f32x4){0.f, 0.f, 0.f, 0.f};
; #pragma unroll
;     for (int t = 1; t < 10; ++t) { const LAS bf16_t* kp = Ks + (16 * w + 16 * t + l15) * AQP + quad * 8;
;         const bf16x8 a0 = *(const LAS bf16x8*)kp, a1 = *(const LAS bf16x8*)(kp + 32);
;         f32x4 z = (f32x4){0.f, 0.f, 0.f, 0.f}; z = mfma16(a0, qf[0], z); st[t] = mfma16(a1, qf[1], z); }
;     const int dbase = 144 + l15 - quad * 4;
;     if (J.blk != 0) {
; #pragma unroll
;         for (int j = 0; j < 4; ++j) { if (dbase - 16 - j > J.maxdist) st[1][j] = NEG_BIG; if (dbase - 144 - j < 0) st[9][j] = NEG_BIG; }
;     } else {
;         const int kbase = idxk0 + 16 * w + quad * 4;
; #pragma unroll
;         for (int t = 1; t < 10; ++t)
; #pragma unroll
;             for (int j = 0; j < 4; ++j) { const int dist = dbase - 16 * t - j; const int kidx = kbase + 16 * t + j;
;                 const bool ok = (dist >= 0) && (dist <= J.maxdist) && (kidx >= 0); if (!ok) st[t][j] = NEG_BIG; }
; __global__ void __launch_bounds__(NTHR, 2) mk_fwd(Args args_unused) {
;     ...
;                 for (int t = 0; t < 8; ++t) { gq[t] = args.a_q_norm[l * 64 + c8 + t] * (0.125f * 1.4426950408889634f); gk[t] = args.a_k_norm[l * 64 + c8 + t]; }
;                 int u = vcu;
;                 if (u < 2304) { AttnJob J = make_job_a(u, OAG, LSE); AttnPre P; attn_prefetch(P, PROJ, cAB, sAB, J, tq);
.LBB0_240:
	s_or_b64 exec, exec, s[16:17]
	v_and_b32_e32 v35, 64, v207
	v_xor_b32_e32 v34, 1, v207
	v_add_u32_e32 v35, 64, v35
	v_cmp_lt_i32_e32 vcc, v34, v35
	v_and_b32_e32 v33, 7, v128
	s_movk_i32 s24, 0x90
	v_cndmask_b32_e32 v34, v207, v34, vcc
	v_lshlrev_b32_e32 v143, 2, v34
	v_xor_b32_e32 v34, 2, v207
	v_cmp_lt_i32_e32 vcc, v34, v35
	s_waitcnt vmcnt(6)
	v_mul_f32_e32 v141, 0x3e38aa3b, v70
	v_lshl_add_u32 v33, v33, 4, 0
	v_cndmask_b32_e32 v34, v207, v34, vcc
	v_lshlrev_b32_e32 v144, 2, v34
	v_xor_b32_e32 v34, 4, v207
	v_cmp_lt_i32_e32 vcc, v34, v35
	v_ashrrev_i32_e32 v70, 6, v128
	s_waitcnt vmcnt(5)
	v_mul_f32_e32 v134, 0x3e38aa3b, v72
	v_cndmask_b32_e32 v34, v207, v34, vcc
	v_lshlrev_b32_e32 v145, 2, v34
	v_mul_lo_u32 v34, v130, s24
	v_mul_f32_e32 v139, 0x3e38aa3b, v68
	v_mul_f32_e32 v142, 0x3e38aa3b, v71
	v_add_u32_e32 v68, 0x2400, v34
	v_add_u32_e32 v146, v33, v34
	v_and_b32_e32 v34, 15, v128
	v_bfe_u32 v71, v128, 4, 2
	v_lshlrev_b32_e32 v72, 4, v70
	v_or_b32_e32 v148, v72, v34
	v_or_b32_e32 v85, 0x90, v34
	v_lshlrev_b32_e32 v34, 2, v71
	v_mul_f32_e32 v138, 0x3e38aa3b, v75
	v_lshlrev_b32_e32 v75, 4, v71
	v_sub_u32_e32 v71, v85, v34
	v_subrev_co_u32_e32 v86, vcc, s24, v71
	s_movk_i32 s20, 0xff80
	s_movk_i32 s27, 0x92
	s_movk_i32 s22, 0x80
	v_subrev_u32_e32 v85, 17, v71
	v_cmp_gt_u32_e64 s[42:43], s20, v86
	s_movk_i32 s25, 0x7f
	v_subrev_co_u32_e64 v86, s[82:83], s27, v71
	s_movk_i32 s26, 0x93
	v_cmp_lt_u32_e64 s[44:45], s25, v85
	v_cmp_gt_u32_e64 s[46:47], s20, v86
	v_subrev_co_u32_e64 v86, s[48:49], s26, v71
	v_cmp_gt_u32_e64 s[54:55], s22, v85
	v_subrev_u32_e32 v85, 18, v71
	v_cmp_gt_u32_e64 s[50:51], s20, v86
	v_add_u32_e32 v86, -16, v71
	v_cmp_gt_u32_e64 s[56:57], s22, v85
	v_subrev_u32_e32 v85, 19, v71
	s_movk_i32 s25, 0x91
	v_cmp_lt_i32_e64 s[58:59], 7, v70
	v_cmp_gt_u32_e64 s[52:53], s22, v86
	v_cmp_gt_u32_e64 s[60:61], s22, v85
	s_movk_i32 s20, 0x8f
	s_and_b64 s[52:53], s[58:59], s[52:53]
	s_and_b64 s[54:55], s[58:59], s[54:55]
	s_and_b64 s[56:57], s[58:59], s[56:57]
	s_and_b64 s[58:59], s[58:59], s[60:61]
	v_cmp_lt_i32_e64 s[60:61], 6, v70
	v_cmp_lt_i32_e64 s[62:63], 5, v70
	v_cmp_lt_i32_e64 s[64:65], 4, v70
	v_cmp_lt_i32_e64 s[66:67], 3, v70
	v_cmp_lt_i32_e64 s[68:69], 2, v70
	v_cmp_lt_i32_e64 s[70:71], 1, v70
	v_cmp_lt_i32_e64 s[72:73], 0, v70
	v_cmp_lt_i32_e64 s[80:81], -1, v70
	v_cmp_lt_u32_e64 s[74:75], s20, v71
	v_cmp_lt_u32_e64 s[76:77], s24, v71
	v_cmp_lt_u32_e64 s[78:79], s25, v71
	v_cmp_lt_u32_e64 s[86:87], s27, v71
	v_xor_b32_e32 v70, 16, v207
	s_and_b64 s[74:75], s[80:81], s[74:75]
	s_and_b64 s[76:77], s[80:81], s[76:77]
	s_and_b64 s[78:79], s[80:81], s[78:79]
	s_and_b64 s[80:81], s[80:81], s[86:87]
	v_cmp_lt_i32_e64 s[86:87], v70, v35
	v_mul_f32_e32 v135, 0x3e38aa3b, v73
	v_mul_lo_u32 v73, v148, s24
	v_cndmask_b32_e64 v70, v207, v70, s[86:87]
	v_lshlrev_b32_e32 v149, 2, v70
	v_xor_b32_e32 v70, 32, v207
	v_cmp_lt_i32_e64 s[86:87], v70, v35
	v_cmp_gt_u32_e64 s[84:85], s25, v71
	s_and_b64 s[82:83], s[48:49], s[82:83]
	v_cndmask_b32_e64 v35, v207, v70, s[86:87]
	v_lshlrev_b32_e32 v150, 2, v35
	v_bfe_u32 v35, v128, 2, 2
	v_or3_b32 v35, v72, v35, v34
	v_and_b32_e32 v70, 24, v129
	v_mul_lo_u32 v35, v35, s24
	s_waitcnt vmcnt(2)
	v_mul_f32_e32 v136, 0x3fb8aa3b, v76
	v_mul_f32_e32 v137, 0x3e38aa3b, v74
	v_mul_f32_e32 v140, 0x3e38aa3b, v69
	v_mul_lo_u32 v69, v128, s24
	v_add_u32_e32 v74, 0, v73
	v_add_u32_e32 v76, 0, v75
	v_add_u32_e32 v77, 0x900, v73
	v_add_u32_e32 v78, 0x1200, v73
	v_add_u32_e32 v79, 0x1b00, v73
	v_add_u32_e32 v80, 0x2400, v73
	v_add_u32_e32 v81, 0x2d00, v73
	v_add_u32_e32 v82, 0x3600, v73
	v_add_u32_e32 v83, 0x3f00, v73
	v_add_u32_e32 v84, 0x4800, v73
	v_add_u32_e32 v73, 0x5100, v73
	v_add3_u32 v151, 0, v70, v35
	s_and_b64 s[84:85], s[82:83], s[84:85]
	v_add_u32_e32 v147, 0xe100, v146
	v_cmp_gt_i32_e64 s[16:17], s22, v128
	v_add_u32_e32 v152, 0xe100, v151
	v_add_u32_e32 v153, v33, v68
	v_add_u32_e32 v154, 0, v69
	v_add_u32_e32 v155, v74, v75
	v_add_u32_e32 v156, v76, v77
	v_add_u32_e32 v157, v76, v78
	v_add_u32_e32 v158, v76, v79
	v_add_u32_e32 v159, v76, v80
	v_add_u32_e32 v160, v76, v81
	v_add_u32_e32 v161, v76, v82
	v_add_u32_e32 v163, v76, v83
	v_add_u32_e32 v171, v76, v84
	v_add_u32_e32 v180, v76, v73
	v_lshlrev_b32_e32 v116, 1, v34
	s_and_b64 s[86:87], s[84:85], vcc
	v_readlane_b32 s24, v252, 18
	v_readlane_b32 s20, v254, 46
	v_readlane_b32 s22, v254, 45
	v_readlane_b32 s25, v252, 19
	s_waitcnt vmcnt(0)
	s_branch .LBB0_242

; #define LAS __attribute__((address_space(3)))
; __device__ __forceinline__ void unpack8(const u32x4 r, float (&v)[8]) { v[0] = bf_lo(r.x); v[1] = bf_hi(r.x); v[2] = bf_lo(r.y); v[3] = bf_hi(r.y); v[4] = bf_lo(r.z); v[5] = bf_hi(r.z); v[6] = bf_lo(r.w); v[7] = bf_hi(r.w); }
; __device__ __forceinline__ u32x4 pack8(const float (&v)[8]) { u32x4 w; w.x = cvt_pk_bf16(v[0], v[1]); w.y = cvt_pk_bf16(v[2], v[3]); w.z = cvt_pk_bf16(v[4], v[5]); w.w = cvt_pk_bf16(v[6], v[7]); return w; }
; __device__ __forceinline__ void norm_store(LAS bf16_t* dst, const u32x4 raw, const float (&g)[8]) {
;     float v[8]; unpack8(raw, v); float ss = 0.f;
; #pragma unroll
;     for (int t = 0; t < 8; ++t) ss += v[t] * v[t];
;     ss += __shfl_xor(ss, 1); ss += __shfl_xor(ss, 2); ss += __shfl_xor(ss, 4);
;     const float rs = __builtin_amdgcn_rsqf(ss * (1.0f / 64.0f) + EPS);
;     float o[8];
; #pragma unroll
;     for (int t = 0; t < 8; ++t) o[t] = v[t] * rs * g[t];
;     *(LAS u32x4*)dst = pack8(o);
; }
; __device__ __forceinline__ void attn_stage(LAS unsigned char* lds, const AttnPre& P, const float (&gq)[8], const float (&gk)[8], int tid) {
;     LAS bf16_t* Qs = (LAS bf16_t*)(lds + A_QS); LAS bf16_t* Ks = (LAS bf16_t*)(lds + A_KS); LAS bf16_t* Vs = (LAS bf16_t*)(lds + A_VS);
;     const int c = tid & 7, i0 = tid >> 3;
; #pragma unroll
;     for (int it = 0; it < 2; ++it) norm_store(Qs + (i0 + 64 * it) * AQP + 8 * c, P.q[it], gq);
.LBB0_242:
	v_and_b32_e32 v70, 0xffff0000, v8
	v_lshlrev_b32_e32 v33, 16, v8
	v_mul_f32_e32 v75, v70, v70
	v_lshlrev_b32_e32 v71, 16, v9
	v_fmac_f32_e32 v75, v33, v33
	v_and_b32_e32 v72, 0xffff0000, v9
	v_fmac_f32_e32 v75, v71, v71
	v_lshlrev_b32_e32 v73, 16, v10
	v_fmac_f32_e32 v75, v72, v72
	v_and_b32_e32 v74, 0xffff0000, v10
	v_fmac_f32_e32 v75, v73, v73
	v_and_b32_e32 v34, 0xffff0000, v11
	v_lshlrev_b32_e32 v35, 16, v11
	v_fmac_f32_e32 v75, v74, v74
	v_pk_mul_f32 v[68:69], v[34:35], v[34:35]
	s_nop 0
	v_add_f32_e32 v69, v69, v75
	v_add_f32_e32 v68, v68, v69
	ds_bpermute_b32 v69, v143, v68
	s_waitcnt lgkmcnt(0)
	v_add_f32_e32 v68, v68, v69
	ds_bpermute_b32 v69, v144, v68
	s_waitcnt lgkmcnt(0)
	v_add_f32_e32 v68, v68, v69
	ds_bpermute_b32 v69, v145, v68
	s_waitcnt lgkmcnt(0)
	v_add_f32_e32 v68, v68, v69
	v_fmamk_f32 v68, v68, 0x3c800000, v204
	v_rsq_f32_e32 v68, v68
	s_nop 0
	v_mul_f32_e32 v69, v68, v70
	v_mul_f32_e32 v70, v68, v71
	v_mul_f32_e32 v33, v68, v33
	v_mul_f32_e32 v69, v135, v69
	v_mul_f32_e32 v70, v137, v70
	v_mul_f32_e32 v71, v68, v72
	v_mul_f32_e32 v72, v68, v73
	v_mul_f32_e32 v73, v68, v74
	v_mul_f32_e32 v33, v134, v33
	v_mul_f32_e32 v71, v138, v71
	v_mul_f32_e32 v72, v139, v72
	v_mul_f32_e32 v73, v140, v73
	v_mul_f32_e32 v35, v68, v35
	v_mul_f32_e32 v34, v68, v34
	v_cvt_pk_bf16_f32 v68, v33, v69
	v_cvt_pk_bf16_f32 v69, v70, v71
	v_cvt_pk_bf16_f32 v70, v72, v73
	v_mul_f32_e32 v35, v141, v35
	v_mul_f32_e32 v34, v142, v34
	v_cvt_pk_bf16_f32 v71, v35, v34
	ds_write_b128 v146, v[68:71]
	v_and_b32_e32 v70, 0xffff0000, v12
	v_lshlrev_b32_e32 v33, 16, v12
	v_mul_f32_e32 v75, v70, v70
	v_lshlrev_b32_e32 v71, 16, v13
	v_fmac_f32_e32 v75, v33, v33
	v_and_b32_e32 v72, 0xffff0000, v13
	v_fmac_f32_e32 v75, v71, v71
	v_lshlrev_b32_e32 v73, 16, v14
	v_fmac_f32_e32 v75, v72, v72
	v_and_b32_e32 v74, 0xffff0000, v14
	v_fmac_f32_e32 v75, v73, v73
	v_and_b32_e32 v34, 0xffff0000, v15
	v_lshlrev_b32_e32 v35, 16, v15
	v_fmac_f32_e32 v75, v74, v74
	v_pk_mul_f32 v[68:69], v[34:35], v[34:35]
	s_nop 0
	v_add_f32_e32 v69, v69, v75
	v_add_f32_e32 v68, v68, v69
	ds_bpermute_b32 v69, v143, v68
	s_waitcnt lgkmcnt(0)
	v_add_f32_e32 v68, v68, v69
	ds_bpermute_b32 v69, v144, v68
	s_waitcnt lgkmcnt(0)
	v_add_f32_e32 v68, v68, v69
	ds_bpermute_b32 v69, v145, v68
	s_waitcnt lgkmcnt(0)
	v_add_f32_e32 v68, v68, v69
	v_fmamk_f32 v68, v68, 0x3c800000, v204
	v_rsq_f32_e32 v68, v68
	s_nop 0
	v_mul_f32_e32 v69, v68, v70
	v_mul_f32_e32 v70, v68, v71
	v_mul_f32_e32 v71, v68, v72
	v_mul_f32_e32 v33, v68, v33
	v_mul_f32_e32 v69, v135, v69
	v_mul_f32_e32 v70, v137, v70
	v_mul_f32_e32 v71, v138, v71
	v_mul_f32_e32 v72, v68, v73
	v_mul_f32_e32 v73, v68, v74
	v_mul_f32_e32 v35, v68, v35
	v_mul_f32_e32 v34, v68, v34
	v_mul_f32_e32 v33, v134, v33
	v_mul_f32_e32 v72, v139, v72
	v_mul_f32_e32 v73, v140, v73
	v_mul_f32_e32 v35, v141, v35
	v_mul_f32_e32 v34, v142, v34
	v_cvt_pk_bf16_f32 v68, v33, v69
	v_cvt_pk_bf16_f32 v69, v70, v71
	v_cvt_pk_bf16_f32 v70, v72, v73
	v_cvt_pk_bf16_f32 v71, v35, v34
	ds_write_b128 v146, v[68:71] offset:9216
	s_and_saveexec_b64 s[26:27], s[4:5]
	s_cbranch_execnz .LBB0_271
	s_or_b64 exec, exec, s[26:27]
	s_and_saveexec_b64 s[26:27], s[6:7]
	s_cbranch_execnz .LBB0_272

;     __device__ __forceinline__ const char* a_base(const Gemm& g, const Unit& u, size_t tstepA) const { return (const char*)g.A + (size_t)u.pm * tstepA; }
;     __device__ __forceinline__ const char* b_base(const Gemm& g, const Unit& u, size_t tstepB) const { return (const char*)g.Bt + (size_t)u.pn * tstepB; }
; #define PG8_STAGE(bufoff, gbase, voff) do { _Pragma("unroll") for (int _i = 0; _i < 2; ++_i) \
;         __builtin_amdgcn_global_load_lds((const unsigned*)((const char*)(gbase) + (voff)[_i]), (PG8_LAS unsigned*)(lds + (bufoff) + ldsw + _i * 8192), 16, 0, 0); } while (0)
; #define PG8_WAIT_V(n) asm volatile("s_waitcnt vmcnt(" #n ")" ::: "memory")
; #define PG8_BAR __builtin_amdgcn_s_barrier()
; template <class Epi, class Sched, bool ALIGN_EPI = false, bool SP2 = false, bool FP8 = false>
; __device__ __forceinline__ void gemm_phase(PG8_LAS unsigned char* lds, const Gemm g, const Sched& S, const Epi& E, const int tid) {
;     ...
;     f32x4 acc[2][2][4][2];
; #pragma unroll
;     for (int a = 0; a < 2; ++a)
; #pragma unroll
;         for (int b = 0; b < 2; ++b)
; #pragma unroll
;             for (int m = 0; m < 4; ++m)
; #pragma unroll
;                 for (int n = 0; n < 2; ++n) acc[a][b][m][n] = (f32x4){0.f, 0.f, 0.f, 0.f};
;     bf16x8 At[4][2], B0[2][2], B1[2][2]; v8i32 At8[4], B08[2], B18[2];
;     const char* cA = S.a_base(g, cur, tstepA); const char* cB = S.b_base(g, cur, tstepB);
;     S.a_ready(cur);
;     if constexpr (SP2) {
;         PG8_STAGE(PG8_SB(0, 0), cB, voffB); PG8_STAGE(PG8_SB(0, 1), cB + hstepB, voffB); PG8_STAGE(PG8_SA(0, 0), cA, voffA); PG8_STAGE(PG8_SA(0, 1), cA + hstepA, voffA);
;         if (wr == 1) PG8_BAR;
;         PG8_WAIT_V(2); PG8_BAR;
;         PG8_STAGE(PG8_SB(1, 0), cB + kstep, voffB); PG8_STAGE(PG8_SA(1, 0), cA + kstep, voffA); PG8_STAGE(PG8_SB(1, 1), cB + hstepB + kstep, voffB);
;         PG8_WAIT_V(6); PG8_BAR;
.LBB0_443:
	s_add_u32 s16, s4, 0x2e800000
	v_lshrrev_b32_e32 v18, 1, v11
	s_addc_u32 s17, s5, 0
	v_and_b32_e32 v18, 24, v18
	s_add_u32 s50, s4, 0x10804700
	v_and_b32_e32 v17, 15, v11
	v_lshlrev_b32_e32 v19, 1, v18
	v_lshlrev_b32_e32 v11, 2, v11
	s_addc_u32 s51, s5, 0
	v_lshl_or_b32 v33, s10, 6, v17
	v_lshl_or_b32 v17, v17, 6, v19
	s_lshl_b32 s4, s10, 13
	v_and_b32_e32 v11, 32, v11
	v_bitop3_b32 v19, v17, s4, v11 bitop3:0xde
	s_lshl_b32 s4, s7, 5
	s_and_b32 s7, s4, 0x60
	s_add_i32 m0, s46, 0x18000
	v_lshl_add_u64 v[6:7], v[6:7], 0, s[38:39]
	s_lshl_b32 s4, s7, 7
	s_waitcnt vmcnt(2)
	s_barrier
	global_load_lds_dwordx4 v[6:7], off
	v_lshl_add_u64 v[4:5], v[4:5], 0, s[38:39]
	s_add_i32 m0, s46, 0x1a000
	s_add_i32 s52, s46, 0x8000
	s_add_i32 s53, s46, 0xa000
	v_bitop3_b32 v163, s4, v17, v11 bitop3:0xf6
	global_load_lds_dwordx4 v[4:5], off
	v_lshl_add_u64 v[0:1], v[0:1], 0, s[38:39]
	s_mov_b32 m0, s52
	s_add_u32 s4, s34, 0x40080
	global_load_lds_dwordx4 v[0:1], off
	v_lshl_add_u64 v[0:1], v[2:3], 0, s[38:39]
	s_mov_b32 m0, s53
	s_addc_u32 s5, s35, 0
	global_load_lds_dwordx4 v[0:1], off
	s_add_i32 m0, s46, 0x1c000
	v_lshl_add_u64 v[0:1], s[4:5], 0, v[184:185]
	global_load_lds_dwordx4 v[0:1], off
	v_lshl_add_u64 v[0:1], s[4:5], 0, v[180:181]
	s_add_i32 m0, s46, 0x1e000
	s_cmpk_lt_u32 s6, 0x100
	global_load_lds_dwordx4 v[0:1], off
	s_movk_i32 s6, 0x3c00
	v_or_b32_e32 v171, s7, v18
	v_lshrrev_b32_e32 v1, 1, v14
	v_mul_lo_u32 v0, v13, s6
	s_mov_b32 s7, 0x3c000
	v_mad_u64_u32 v[0:1], s[4:5], v1, s7, v[0:1]
	v_or_b32_e32 v0, v0, v15
	v_add_lshl_u32 v0, v0, v16, 1
	v_mov_b32_e32 v1, v32
	s_mov_b64 s[10:11], 0x3c0080
	v_lshl_add_u64 v[188:189], v[0:1], 0, s[10:11]
	v_lshrrev_b32_e32 v1, 1, v8
	v_mul_lo_u32 v0, v9, s6
	v_mad_u64_u32 v[0:1], s[4:5], v1, s7, v[0:1]
	v_or_b32_e32 v0, v0, v10
	s_waitcnt vmcnt(0)
	v_add_lshl_u32 v0, v0, v12, 1
	v_mov_b32_e32 v1, v32
	v_lshl_add_u64 v[190:191], v[0:1], 0, s[10:11]
	v_mov_b32_e32 v0, 0
	v_readlane_b32 s4, v254, 55
	s_cselect_b64 s[24:25], -1, 0
	s_movk_i32 s63, 0x3c00
	s_mov_b32 s20, 0
	v_add_u32_e32 v198, 0, v19
	v_readlane_b32 s22, v254, 38
	s_mov_b32 s33, s4
	s_mov_b32 s54, 0
	v_mov_b32_e32 v1, v0
	v_mov_b32_e32 v2, v0
	v_mov_b32_e32 v3, v0
	v_mov_b32_e32 v4, v0
	v_mov_b32_e32 v5, v0
	v_mov_b32_e32 v6, v0
	v_mov_b32_e32 v7, v0
	v_mov_b32_e32 v8, v0
	v_mov_b32_e32 v9, v0
	v_mov_b32_e32 v10, v0
	v_mov_b32_e32 v11, v0
	v_mov_b32_e32 v12, v0
	v_mov_b32_e32 v13, v0
	v_mov_b32_e32 v14, v0
	v_mov_b32_e32 v15, v0
	v_mov_b32_e32 v16, v0
	v_mov_b32_e32 v17, v0
	v_mov_b32_e32 v18, v0
	v_mov_b32_e32 v19, v0
	v_mov_b32_e32 v20, v0
	v_mov_b32_e32 v21, v0
	v_mov_b32_e32 v22, v0
	v_mov_b32_e32 v23, v0
	v_mov_b32_e32 v24, v0
	v_mov_b32_e32 v25, v0
	v_mov_b32_e32 v26, v0
	v_mov_b32_e32 v27, v0
	v_mov_b32_e32 v28, v0
	v_mov_b32_e32 v29, v0
	v_mov_b32_e32 v30, v0
	v_mov_b32_e32 v31, v0
	v_mov_b32_e32 v34, v0
	v_mov_b32_e32 v35, v0
	v_mov_b32_e32 v36, v0
	v_mov_b32_e32 v37, v0
	v_mov_b32_e32 v38, v0
	v_mov_b32_e32 v39, v0
	v_mov_b32_e32 v40, v0
	v_mov_b32_e32 v41, v0
	v_mov_b32_e32 v42, v0
	v_mov_b32_e32 v43, v0
	v_mov_b32_e32 v44, v0
	v_mov_b32_e32 v45, v0
	v_mov_b32_e32 v46, v0
	v_mov_b32_e32 v47, v0
	v_mov_b32_e32 v48, v0
	v_mov_b32_e32 v49, v0
	v_mov_b32_e32 v50, v0
	v_mov_b32_e32 v51, v0
	v_mov_b32_e32 v52, v0
	v_mov_b32_e32 v53, v0
	v_mov_b32_e32 v54, v0
	v_mov_b32_e32 v55, v0
	v_mov_b32_e32 v56, v0
	v_mov_b32_e32 v57, v0
	v_mov_b32_e32 v58, v0
	v_mov_b32_e32 v59, v0
	v_mov_b32_e32 v60, v0
	v_mov_b32_e32 v61, v0
	v_mov_b32_e32 v62, v0
	v_mov_b32_e32 v63, v0
	v_mov_b32_e32 v64, v0
	v_mov_b32_e32 v65, v0
	v_mov_b32_e32 v66, v0
	v_mov_b32_e32 v67, v0
	v_mov_b32_e32 v68, v0
	v_mov_b32_e32 v69, v0
	v_mov_b32_e32 v70, v0
	v_mov_b32_e32 v71, v0
	v_mov_b32_e32 v72, v0
	v_mov_b32_e32 v73, v0
	v_mov_b32_e32 v74, v0
	v_mov_b32_e32 v75, v0
	v_mov_b32_e32 v76, v0
	v_mov_b32_e32 v77, v0
	v_mov_b32_e32 v78, v0
	v_mov_b32_e32 v79, v0
	v_mov_b32_e32 v80, v0
	v_mov_b32_e32 v81, v0
	v_mov_b32_e32 v82, v0
	v_mov_b32_e32 v83, v0
	v_mov_b32_e32 v84, v0
	v_mov_b32_e32 v85, v0
	v_mov_b32_e32 v86, v0
	v_mov_b32_e32 v87, v0
	v_mov_b32_e32 v88, v0
	v_mov_b32_e32 v89, v0
	v_mov_b32_e32 v90, v0
	v_mov_b32_e32 v91, v0
	v_mov_b32_e32 v92, v0
	v_mov_b32_e32 v93, v0
	v_mov_b32_e32 v94, v0
	v_mov_b32_e32 v95, v0
	v_mov_b32_e32 v96, v0
	v_mov_b32_e32 v97, v0
	v_mov_b32_e32 v98, v0
	v_mov_b32_e32 v99, v0
	v_mov_b32_e32 v100, v0
	v_mov_b32_e32 v101, v0
	v_mov_b32_e32 v102, v0
	v_mov_b32_e32 v103, v0
	v_mov_b32_e32 v104, v0
	v_mov_b32_e32 v105, v0
	v_mov_b32_e32 v106, v0
	v_mov_b32_e32 v107, v0
	v_mov_b32_e32 v108, v0
	v_mov_b32_e32 v109, v0
	v_mov_b32_e32 v110, v0
	v_mov_b32_e32 v111, v0
	v_mov_b32_e32 v112, v0
	v_mov_b32_e32 v113, v0
	v_mov_b32_e32 v114, v0
	v_mov_b32_e32 v115, v0
	v_mov_b32_e32 v116, v0
	v_mov_b32_e32 v117, v0
	v_mov_b32_e32 v118, v0
	v_mov_b32_e32 v119, v0
	v_mov_b32_e32 v120, v0
	v_mov_b32_e32 v121, v0
	v_mov_b32_e32 v122, v0
	v_mov_b32_e32 v123, v0
	v_mov_b32_e32 v124, v0
	v_mov_b32_e32 v125, v0
	v_mov_b32_e32 v126, v0
	v_mov_b32_e32 v127, v0
	v_mov_b32_e32 v128, v0
	v_mov_b32_e32 v129, v0
	s_barrier
	v_readlane_b32 s5, v254, 56
	s_branch .LBB0_446

; #define PG8_STAGE(bufoff, gbase, voff) do { _Pragma("unroll") for (int _i = 0; _i < 2; ++_i) \
;         __builtin_amdgcn_global_load_lds((const unsigned*)((const char*)(gbase) + (voff)[_i]), (PG8_LAS unsigned*)(lds + (bufoff) + ldsw + _i * 8192), 16, 0, 0); } while (0)
; #define PG8_WAIT_V(n) asm volatile("s_waitcnt vmcnt(" #n ")" ::: "memory")
; #define PG8_WAIT_L(n) asm volatile("s_waitcnt lgkmcnt(" #n ")" ::: "memory")
; #define PG8_BAR __builtin_amdgcn_s_barrier()
; #define PG8_SCHED __builtin_amdgcn_sched_barrier(0)
; template <class Epi, class Sched, bool ALIGN_EPI = false, bool SP2 = false, bool FP8 = false>
; __device__ __forceinline__ void gemm_phase(PG8_LAS unsigned char* lds, const Gemm g, const Sched& S, const Epi& E, const int tid) {
;     ...
;             if constexpr (SP2) {
;             PG8_LDB(B0, 0, 0); PG8_LDB(B1, 0, 1); PG8_SCHED; PG8_LDA(At, 0, 0); PG8_STAGE(PG8_SA(1, 1), a1 + hstepA, voffA);
;             PG8_WAIT_V(8); PG8_WAIT_L(0); PG8_BAR; PG8_MMA(0, 0, At, B0); PG8_MMA(0, 1, At, B1); PG8_BAR; PG8_SCHED;
;             PG8_LDA(At, 0, 1); PG8_STAGE(PG8_SB(0, 0), b2, voffB); PG8_STAGE(PG8_SB(0, 1), b2 + hstepB, voffB); PG8_STAGE(PG8_SA(0, 0), a2, voffA);
;             PG8_WAIT_V(8); PG8_WAIT_L(0); PG8_BAR; PG8_MMA(1, 0, At, B0); PG8_MMA(1, 1, At, B1); PG8_BAR; PG8_SCHED;
.LBB0_457:
	s_add_i32 s60, s36, 2
	s_add_u32 s6, s8, 0x100
	s_addc_u32 s7, s9, 0
	s_add_i32 s61, 0, 0x10000
	s_cmp_eq_u32 s57, s36
	s_cselect_b32 s37, s29, s7
	s_cselect_b32 s36, s28, s6
	s_cselect_b32 s35, s31, s59
	s_cselect_b32 s34, s30, s58
	s_add_i32 s62, 0, 0x14000
	v_add_u32_e32 v142, s61, v163
	v_add_u32_e32 v158, s62, v163
	ds_read_b128 v[130:133], v142
	ds_read_b128 v[134:137], v142 offset:1024
	ds_read_b128 v[138:141], v142 offset:2048
	ds_read_b128 v[142:145], v142 offset:3072
	ds_read_b128 v[146:149], v158
	ds_read_b128 v[150:153], v158 offset:1024
	ds_read_b128 v[154:157], v158 offset:2048
	ds_read_b128 v[158:161], v158 offset:3072
	v_lshl_add_u64 v[164:165], s[8:9], 0, v[188:189]
	s_add_i32 m0, s46, 0xc000
	ds_read_b128 v[192:195], v198
	ds_read_b128 v[220:223], v198 offset:1024
	ds_read_b128 v[224:227], v198 offset:2048
	ds_read_b128 v[228:231], v198 offset:3072
	ds_read_b128 v[232:235], v198 offset:4096
	ds_read_b128 v[236:239], v198 offset:5120
	ds_read_b128 v[240:243], v198 offset:6144
	ds_read_b128 v[244:247], v198 offset:7168
	global_load_lds_dwordx4 v[164:165], off
	v_lshl_add_u64 v[164:165], s[8:9], 0, v[190:191]
	s_add_i32 m0, s46, 0xe000
	s_nop 0
	global_load_lds_dwordx4 v[164:165], off
	s_cmp_eq_i32 s60, 2
	s_cbranch_scc1 .Lskw_2_0
	s_waitcnt vmcnt(8)
.Lskw_2_0:
	s_waitcnt lgkmcnt(0)
	s_barrier
	s_setprio 1
	s_waitcnt lgkmcnt(0)
	v_mfma_f32_16x16x32_bf16 v[126:129], v[130:133], v[192:195], v[126:129]
	v_mfma_f32_16x16x32_bf16 v[122:125], v[138:141], v[192:195], v[122:125]
	v_mfma_f32_16x16x32_bf16 v[118:121], v[130:133], v[224:227], v[118:121]
	v_mfma_f32_16x16x32_bf16 v[114:117], v[138:141], v[224:227], v[114:117]
	v_mfma_f32_16x16x32_bf16 v[110:113], v[130:133], v[232:235], v[110:113]
	v_mfma_f32_16x16x32_bf16 v[106:109], v[138:141], v[232:235], v[106:109]
	v_mfma_f32_16x16x32_bf16 v[102:105], v[130:133], v[240:243], v[102:105]
	v_mfma_f32_16x16x32_bf16 v[98:101], v[138:141], v[240:243], v[98:101]
	v_mfma_f32_16x16x32_bf16 v[126:129], v[134:137], v[220:223], v[126:129]
	v_mfma_f32_16x16x32_bf16 v[122:125], v[142:145], v[220:223], v[122:125]
	v_mfma_f32_16x16x32_bf16 v[118:121], v[134:137], v[228:231], v[118:121]
	v_mfma_f32_16x16x32_bf16 v[114:117], v[142:145], v[228:231], v[114:117]
	v_mfma_f32_16x16x32_bf16 v[110:113], v[134:137], v[236:239], v[110:113]
	v_mfma_f32_16x16x32_bf16 v[106:109], v[142:145], v[236:239], v[106:109]
	v_mfma_f32_16x16x32_bf16 v[102:105], v[134:137], v[244:247], v[102:105]
	v_mfma_f32_16x16x32_bf16 v[98:101], v[142:145], v[244:247], v[98:101]
	s_setprio 0
	s_setprio 1
	v_mfma_f32_16x16x32_bf16 v[94:97], v[146:149], v[192:195], v[94:97]
	v_mfma_f32_16x16x32_bf16 v[90:93], v[154:157], v[192:195], v[90:93]
	v_mfma_f32_16x16x32_bf16 v[86:89], v[146:149], v[224:227], v[86:89]
	v_mfma_f32_16x16x32_bf16 v[82:85], v[154:157], v[224:227], v[82:85]
	v_mfma_f32_16x16x32_bf16 v[78:81], v[146:149], v[232:235], v[78:81]
	v_mfma_f32_16x16x32_bf16 v[74:77], v[154:157], v[232:235], v[74:77]
	v_mfma_f32_16x16x32_bf16 v[70:73], v[146:149], v[240:243], v[70:73]
	v_mfma_f32_16x16x32_bf16 v[66:69], v[154:157], v[240:243], v[66:69]
	v_mfma_f32_16x16x32_bf16 v[94:97], v[150:153], v[220:223], v[94:97]
	v_mfma_f32_16x16x32_bf16 v[90:93], v[158:161], v[220:223], v[90:93]
	v_mfma_f32_16x16x32_bf16 v[86:89], v[150:153], v[228:231], v[86:89]
	v_mfma_f32_16x16x32_bf16 v[82:85], v[158:161], v[228:231], v[82:85]
	v_mfma_f32_16x16x32_bf16 v[78:81], v[150:153], v[236:239], v[78:81]
	v_mfma_f32_16x16x32_bf16 v[74:77], v[158:161], v[236:239], v[74:77]
	v_mfma_f32_16x16x32_bf16 v[70:73], v[150:153], v[244:247], v[70:73]
	v_mfma_f32_16x16x32_bf16 v[66:69], v[158:161], v[244:247], v[66:69]
	s_setprio 0
	s_barrier
	s_add_i32 s8, s61, s45
	v_lshl_add_u64 v[164:165], s[34:35], 0, v[184:185]
	s_mov_b32 m0, s8
	ds_read_b128 v[192:195], v198 offset:16384
	ds_read_b128 v[220:223], v198 offset:17408
	ds_read_b128 v[224:227], v198 offset:18432
	ds_read_b128 v[228:231], v198 offset:19456
	ds_read_b128 v[232:235], v198 offset:20480
	ds_read_b128 v[236:239], v198 offset:21504
	ds_read_b128 v[240:243], v198 offset:22528
	ds_read_b128 v[244:247], v198 offset:23552
	global_load_lds_dwordx4 v[164:165], off
	s_add_i32 m0, s8, 0x2000
	s_add_u32 s8, s34, 0x40000
	v_lshl_add_u64 v[166:167], s[34:35], 0, v[180:181]
	s_addc_u32 s9, s35, 0
	s_add_i32 s61, s62, s45
	global_load_lds_dwordx4 v[166:167], off
	v_lshl_add_u64 v[196:197], s[8:9], 0, v[184:185]
	s_mov_b32 m0, s61
	v_lshl_add_u64 v[200:201], s[36:37], 0, v[182:183]
	global_load_lds_dwordx4 v[196:197], off
	v_lshl_add_u64 v[196:197], s[8:9], 0, v[180:181]
	s_add_i32 m0, s61, 0x2000
	s_nop 0
	global_load_lds_dwordx4 v[196:197], off
	v_lshl_add_u64 v[196:197], s[36:37], 0, v[186:187]
	s_mov_b32 m0, s46
	s_nop 0
	global_load_lds_dwordx4 v[196:197], off
	s_mov_b32 m0, s47
	s_nop 0
	global_load_lds_dwordx4 v[200:201], off
	s_cmp_eq_i32 s60, 2
	s_cbranch_scc1 .Lskw_2_1
	s_waitcnt vmcnt(8)
; #define PG8_STAGE(bufoff, gbase, voff) do { _Pragma("unroll") for (int _i = 0; _i < 2; ++_i) \
;         __builtin_amdgcn_global_load_lds((const unsigned*)((const char*)(gbase) + (voff)[_i]), (PG8_LAS unsigned*)(lds + (bufoff) + ldsw + _i * 8192), 16, 0, 0); } while (0)
; #define PG8_WAIT_V(n) asm volatile("s_waitcnt vmcnt(" #n ")" ::: "memory")
; #define PG8_WAIT_L(n) asm volatile("s_waitcnt lgkmcnt(" #n ")" ::: "memory")
; #define PG8_BAR __builtin_amdgcn_s_barrier()
; #define PG8_SCHED __builtin_amdgcn_sched_barrier(0)
; template <class Epi, class Sched, bool ALIGN_EPI = false, bool SP2 = false, bool FP8 = false>
; __device__ __forceinline__ void gemm_phase(PG8_LAS unsigned char* lds, const Gemm g, const Sched& S, const Epi& E, const int tid) {
;     ...
;             PG8_WAIT_V(8); PG8_WAIT_L(0); PG8_BAR; PG8_MMA(1, 0, At, B0); PG8_MMA(1, 1, At, B1); PG8_BAR; PG8_SCHED;
;             PG8_LDB(B0, 1, 0); PG8_LDB(B1, 1, 1); PG8_SCHED; PG8_LDA(At, 1, 0); PG8_STAGE(PG8_SA(0, 1), a2 + hstepA, voffA);
;             PG8_WAIT_V(8); PG8_WAIT_L(0); PG8_BAR; PG8_MMA(0, 0, At, B0); PG8_MMA(0, 1, At, B1); PG8_BAR; PG8_SCHED;
.Lskw_2_1:
	s_waitcnt lgkmcnt(0)
	s_barrier
	s_setprio 1
	s_waitcnt lgkmcnt(0)
	v_mfma_f32_16x16x32_bf16 v[62:65], v[130:133], v[192:195], v[62:65]
	v_mfma_f32_16x16x32_bf16 v[58:61], v[138:141], v[192:195], v[58:61]
	v_mfma_f32_16x16x32_bf16 v[54:57], v[130:133], v[224:227], v[54:57]
	v_mfma_f32_16x16x32_bf16 v[50:53], v[138:141], v[224:227], v[50:53]
	v_mfma_f32_16x16x32_bf16 v[46:49], v[130:133], v[232:235], v[46:49]
	v_mfma_f32_16x16x32_bf16 v[42:45], v[138:141], v[232:235], v[42:45]
	v_mfma_f32_16x16x32_bf16 v[38:41], v[130:133], v[240:243], v[38:41]
	v_mfma_f32_16x16x32_bf16 v[34:37], v[138:141], v[240:243], v[34:37]
	v_mfma_f32_16x16x32_bf16 v[62:65], v[134:137], v[220:223], v[62:65]
	v_mfma_f32_16x16x32_bf16 v[58:61], v[142:145], v[220:223], v[58:61]
	v_mfma_f32_16x16x32_bf16 v[54:57], v[134:137], v[228:231], v[54:57]
	v_mfma_f32_16x16x32_bf16 v[50:53], v[142:145], v[228:231], v[50:53]
	v_mfma_f32_16x16x32_bf16 v[46:49], v[134:137], v[236:239], v[46:49]
	v_mfma_f32_16x16x32_bf16 v[42:45], v[142:145], v[236:239], v[42:45]
	v_mfma_f32_16x16x32_bf16 v[38:41], v[134:137], v[244:247], v[38:41]
	v_mfma_f32_16x16x32_bf16 v[34:37], v[142:145], v[244:247], v[34:37]
	s_setprio 0
	s_setprio 1
	v_mfma_f32_16x16x32_bf16 v[28:31], v[146:149], v[192:195], v[28:31]
	v_mfma_f32_16x16x32_bf16 v[24:27], v[154:157], v[192:195], v[24:27]
	v_mfma_f32_16x16x32_bf16 v[20:23], v[146:149], v[224:227], v[20:23]
	v_mfma_f32_16x16x32_bf16 v[16:19], v[154:157], v[224:227], v[16:19]
	v_mfma_f32_16x16x32_bf16 v[12:15], v[146:149], v[232:235], v[12:15]
	v_mfma_f32_16x16x32_bf16 v[8:11], v[154:157], v[232:235], v[8:11]
	v_mfma_f32_16x16x32_bf16 v[4:7], v[146:149], v[240:243], v[4:7]
	v_mfma_f32_16x16x32_bf16 v[0:3], v[154:157], v[240:243], v[0:3]
	v_mfma_f32_16x16x32_bf16 v[28:31], v[150:153], v[220:223], v[28:31]
	v_mfma_f32_16x16x32_bf16 v[24:27], v[158:161], v[220:223], v[24:27]
	v_mfma_f32_16x16x32_bf16 v[20:23], v[150:153], v[228:231], v[20:23]
	v_mfma_f32_16x16x32_bf16 v[16:19], v[158:161], v[228:231], v[16:19]
	v_mfma_f32_16x16x32_bf16 v[12:15], v[150:153], v[236:239], v[12:15]
	v_mfma_f32_16x16x32_bf16 v[8:11], v[158:161], v[236:239], v[8:11]
	v_mfma_f32_16x16x32_bf16 v[4:7], v[150:153], v[244:247], v[4:7]
	v_mfma_f32_16x16x32_bf16 v[0:3], v[158:161], v[244:247], v[0:3]
	s_setprio 0
	s_barrier
	s_add_i32 s61, 0, 0x18000
	s_add_i32 s62, 0, 0x1c000
	v_add_u32_e32 v142, s61, v163
	v_add_u32_e32 v158, s62, v163
	ds_read_b128 v[130:133], v142
	ds_read_b128 v[134:137], v142 offset:1024
	ds_read_b128 v[138:141], v142 offset:2048
	ds_read_b128 v[142:145], v142 offset:3072
	ds_read_b128 v[146:149], v158
	ds_read_b128 v[150:153], v158 offset:1024
	ds_read_b128 v[154:157], v158 offset:2048
	ds_read_b128 v[158:161], v158 offset:3072
	s_add_u32 s8, s36, 0x3c0000
	s_addc_u32 s9, s37, 0
	s_mov_b32 m0, s48
	v_lshl_add_u64 v[248:249], s[8:9], 0, v[186:187]
	ds_read_b128 v[192:195], v198 offset:32768
	ds_read_b128 v[220:223], v198 offset:33792
	ds_read_b128 v[224:227], v198 offset:34816
	ds_read_b128 v[228:231], v198 offset:35840
	ds_read_b128 v[232:235], v198 offset:36864
	ds_read_b128 v[236:239], v198 offset:37888
	ds_read_b128 v[240:243], v198 offset:38912
	ds_read_b128 v[244:247], v198 offset:39936
	global_load_lds_dwordx4 v[248:249], off
	v_lshl_add_u64 v[248:249], s[8:9], 0, v[182:183]
	s_mov_b32 m0, s49
	s_nop 0
	global_load_lds_dwordx4 v[248:249], off
	s_waitcnt vmcnt(8)
	s_waitcnt lgkmcnt(0)
	s_barrier
	s_setprio 1
	s_waitcnt lgkmcnt(0)
	v_mfma_f32_16x16x32_bf16 v[126:129], v[130:133], v[192:195], v[126:129]
	v_mfma_f32_16x16x32_bf16 v[122:125], v[138:141], v[192:195], v[122:125]
	v_mfma_f32_16x16x32_bf16 v[118:121], v[130:133], v[224:227], v[118:121]
	v_mfma_f32_16x16x32_bf16 v[114:117], v[138:141], v[224:227], v[114:117]
	v_mfma_f32_16x16x32_bf16 v[110:113], v[130:133], v[232:235], v[110:113]
	v_mfma_f32_16x16x32_bf16 v[106:109], v[138:141], v[232:235], v[106:109]
	v_mfma_f32_16x16x32_bf16 v[102:105], v[130:133], v[240:243], v[102:105]
	v_mfma_f32_16x16x32_bf16 v[98:101], v[138:141], v[240:243], v[98:101]
	v_mfma_f32_16x16x32_bf16 v[126:129], v[134:137], v[220:223], v[126:129]
	v_mfma_f32_16x16x32_bf16 v[122:125], v[142:145], v[220:223], v[122:125]
	v_mfma_f32_16x16x32_bf16 v[118:121], v[134:137], v[228:231], v[118:121]
	v_mfma_f32_16x16x32_bf16 v[114:117], v[142:145], v[228:231], v[114:117]
	v_mfma_f32_16x16x32_bf16 v[110:113], v[134:137], v[236:239], v[110:113]
	v_mfma_f32_16x16x32_bf16 v[106:109], v[142:145], v[236:239], v[106:109]
	v_mfma_f32_16x16x32_bf16 v[102:105], v[134:137], v[244:247], v[102:105]
	v_mfma_f32_16x16x32_bf16 v[98:101], v[142:145], v[244:247], v[98:101]
	s_setprio 0
	s_setprio 1
	v_mfma_f32_16x16x32_bf16 v[94:97], v[146:149], v[192:195], v[94:97]
	v_mfma_f32_16x16x32_bf16 v[90:93], v[154:157], v[192:195], v[90:93]
	v_mfma_f32_16x16x32_bf16 v[86:89], v[146:149], v[224:227], v[86:89]
	v_mfma_f32_16x16x32_bf16 v[82:85], v[154:157], v[224:227], v[82:85]
	v_mfma_f32_16x16x32_bf16 v[78:81], v[146:149], v[232:235], v[78:81]
	v_mfma_f32_16x16x32_bf16 v[74:77], v[154:157], v[232:235], v[74:77]
	v_mfma_f32_16x16x32_bf16 v[70:73], v[146:149], v[240:243], v[70:73]
	v_mfma_f32_16x16x32_bf16 v[66:69], v[154:157], v[240:243], v[66:69]
	v_mfma_f32_16x16x32_bf16 v[94:97], v[150:153], v[220:223], v[94:97]
	v_mfma_f32_16x16x32_bf16 v[90:93], v[158:161], v[220:223], v[90:93]
	v_mfma_f32_16x16x32_bf16 v[86:89], v[150:153], v[228:231], v[86:89]
	v_mfma_f32_16x16x32_bf16 v[82:85], v[158:161], v[228:231], v[82:85]
	v_mfma_f32_16x16x32_bf16 v[78:81], v[150:153], v[236:239], v[78:81]
	v_mfma_f32_16x16x32_bf16 v[74:77], v[158:161], v[236:239], v[74:77]
	v_mfma_f32_16x16x32_bf16 v[70:73], v[150:153], v[244:247], v[70:73]
	v_mfma_f32_16x16x32_bf16 v[66:69], v[158:161], v[244:247], v[66:69]
	s_setprio 0
	s_barrier
; #define PG8_STAGE(bufoff, gbase, voff) do { _Pragma("unroll") for (int _i = 0; _i < 2; ++_i) \
;         __builtin_amdgcn_global_load_lds((const unsigned*)((const char*)(gbase) + (voff)[_i]), (PG8_LAS unsigned*)(lds + (bufoff) + ldsw + _i * 8192), 16, 0, 0); } while (0)
; #define PG8_WAIT_V(n) asm volatile("s_waitcnt vmcnt(" #n ")" ::: "memory")
; #define PG8_WAIT_L(n) asm volatile("s_waitcnt lgkmcnt(" #n ")" ::: "memory")
; #define PG8_BAR __builtin_amdgcn_s_barrier()
; #define PG8_SCHED __builtin_amdgcn_sched_barrier(0)
; template <class Epi, class Sched, bool ALIGN_EPI = false, bool SP2 = false, bool FP8 = false>
; __device__ __forceinline__ void gemm_phase(PG8_LAS unsigned char* lds, const Gemm g, const Sched& S, const Epi& E, const int tid) {
;     ...
;             PG8_LDA(At, 1, 1); PG8_STAGE(PG8_SB(1, 0), b3, voffB); PG8_STAGE(PG8_SB(1, 1), b3 + hstepB, voffB); PG8_STAGE(PG8_SA(1, 0), a3, voffA);
;             PG8_WAIT_V(8); PG8_WAIT_L(0); PG8_BAR; PG8_MMA(1, 0, At, B0); PG8_MMA(1, 1, At, B1); PG8_BAR; PG8_SCHED;
;     ...
;         if constexpr (ALIGN_EPI) { if (wr == 0) PG8_BAR; }
	s_add_i32 s8, s61, s45
	v_lshl_add_u64 v[164:165], v[164:165], 0, s[38:39]
	s_mov_b32 m0, s8
	ds_read_b128 v[192:195], v198 offset:49152
	ds_read_b128 v[220:223], v198 offset:50176
	ds_read_b128 v[224:227], v198 offset:51200
	ds_read_b128 v[228:231], v198 offset:52224
	ds_read_b128 v[232:235], v198 offset:53248
	ds_read_b128 v[236:239], v198 offset:54272
	ds_read_b128 v[240:243], v198 offset:55296
	ds_read_b128 v[244:247], v198 offset:56320
	global_load_lds_dwordx4 v[164:165], off
	s_add_i32 m0, s8, 0x2000
	s_add_u32 s8, s34, 0x40080
	v_lshl_add_u64 v[164:165], v[166:167], 0, s[38:39]
	s_addc_u32 s9, s35, 0
	s_add_i32 s34, s62, s45
	global_load_lds_dwordx4 v[164:165], off
	v_lshl_add_u64 v[164:165], s[8:9], 0, v[184:185]
	s_mov_b32 m0, s34
	s_nop 0
	global_load_lds_dwordx4 v[164:165], off
	v_lshl_add_u64 v[164:165], s[8:9], 0, v[180:181]
	s_add_i32 m0, s34, 0x2000
	s_nop 0
	global_load_lds_dwordx4 v[164:165], off
	v_lshl_add_u64 v[164:165], v[196:197], 0, s[38:39]
	s_mov_b32 m0, s52
	s_nop 0
	global_load_lds_dwordx4 v[164:165], off
	v_lshl_add_u64 v[164:165], v[200:201], 0, s[38:39]
	s_mov_b32 m0, s53
	s_nop 0
	global_load_lds_dwordx4 v[164:165], off
	s_waitcnt vmcnt(8)
	s_waitcnt lgkmcnt(0)
	s_barrier
	s_setprio 1
	s_waitcnt lgkmcnt(0)
	v_mfma_f32_16x16x32_bf16 v[62:65], v[130:133], v[192:195], v[62:65]
	v_mfma_f32_16x16x32_bf16 v[58:61], v[138:141], v[192:195], v[58:61]
	v_mfma_f32_16x16x32_bf16 v[54:57], v[130:133], v[224:227], v[54:57]
	v_mfma_f32_16x16x32_bf16 v[50:53], v[138:141], v[224:227], v[50:53]
	v_mfma_f32_16x16x32_bf16 v[46:49], v[130:133], v[232:235], v[46:49]
	v_mfma_f32_16x16x32_bf16 v[42:45], v[138:141], v[232:235], v[42:45]
	v_mfma_f32_16x16x32_bf16 v[38:41], v[130:133], v[240:243], v[38:41]
	v_mfma_f32_16x16x32_bf16 v[34:37], v[138:141], v[240:243], v[34:37]
	v_mfma_f32_16x16x32_bf16 v[62:65], v[134:137], v[220:223], v[62:65]
	v_mfma_f32_16x16x32_bf16 v[58:61], v[142:145], v[220:223], v[58:61]
	v_mfma_f32_16x16x32_bf16 v[54:57], v[134:137], v[228:231], v[54:57]
	v_mfma_f32_16x16x32_bf16 v[50:53], v[142:145], v[228:231], v[50:53]
	v_mfma_f32_16x16x32_bf16 v[46:49], v[134:137], v[236:239], v[46:49]
	v_mfma_f32_16x16x32_bf16 v[42:45], v[142:145], v[236:239], v[42:45]
	v_mfma_f32_16x16x32_bf16 v[38:41], v[134:137], v[244:247], v[38:41]
	v_mfma_f32_16x16x32_bf16 v[34:37], v[142:145], v[244:247], v[34:37]
	s_setprio 0
	s_setprio 1
	v_mfma_f32_16x16x32_bf16 v[28:31], v[146:149], v[192:195], v[28:31]
	v_mfma_f32_16x16x32_bf16 v[24:27], v[154:157], v[192:195], v[24:27]
	v_mfma_f32_16x16x32_bf16 v[20:23], v[146:149], v[224:227], v[20:23]
	v_mfma_f32_16x16x32_bf16 v[16:19], v[154:157], v[224:227], v[16:19]
	v_mfma_f32_16x16x32_bf16 v[12:15], v[146:149], v[232:235], v[12:15]
	v_mfma_f32_16x16x32_bf16 v[8:11], v[154:157], v[232:235], v[8:11]
	v_mfma_f32_16x16x32_bf16 v[4:7], v[146:149], v[240:243], v[4:7]
	v_mfma_f32_16x16x32_bf16 v[0:3], v[154:157], v[240:243], v[0:3]
	v_mfma_f32_16x16x32_bf16 v[28:31], v[150:153], v[220:223], v[28:31]
	v_mfma_f32_16x16x32_bf16 v[24:27], v[158:161], v[220:223], v[24:27]
	v_mfma_f32_16x16x32_bf16 v[20:23], v[150:153], v[228:231], v[20:23]
	v_mfma_f32_16x16x32_bf16 v[16:19], v[158:161], v[228:231], v[16:19]
	v_mfma_f32_16x16x32_bf16 v[12:15], v[150:153], v[236:239], v[12:15]
	v_mfma_f32_16x16x32_bf16 v[8:11], v[158:161], v[236:239], v[8:11]
	v_mfma_f32_16x16x32_bf16 v[4:7], v[150:153], v[244:247], v[4:7]
	v_mfma_f32_16x16x32_bf16 v[0:3], v[158:161], v[244:247], v[0:3]
	s_setprio 0
	s_barrier
	s_add_u32 s58, s58, 0x100
	s_addc_u32 s59, s59, 0
	s_cmp_ge_u32 s60, s27
	s_mov_b64 s[8:9], s[6:7]
	s_mov_b32 s36, s60
	s_cbranch_scc0 .LBB0_457
	s_and_b64 vcc, exec, s[24:25]
	s_cbranch_vccz .LBB0_460
	s_barrier

; #define PG8_STAGE(bufoff, gbase, voff) do { _Pragma("unroll") for (int _i = 0; _i < 2; ++_i) \
;         __builtin_amdgcn_global_load_lds((const unsigned*)((const char*)(gbase) + (voff)[_i]), (PG8_LAS unsigned*)(lds + (bufoff) + ldsw + _i * 8192), 16, 0, 0); } while (0)
; #define PG8_WAIT_V(n) asm volatile("s_waitcnt vmcnt(" #n ")" ::: "memory")
; #define PG8_BAR __builtin_amdgcn_s_barrier()
; template <class Epi, class Sched, bool ALIGN_EPI = false, bool SP2 = false, bool FP8 = false>
; __device__ __forceinline__ void gemm_phase(PG8_LAS unsigned char* lds, const Gemm g, const Sched& S, const Epi& E, const int tid) {
;     ...
;     if constexpr (SP2) {
;         PG8_STAGE(PG8_SB(0, 0), cB, voffB); PG8_STAGE(PG8_SB(0, 1), cB + hstepB, voffB); PG8_STAGE(PG8_SA(0, 0), cA, voffA); PG8_STAGE(PG8_SA(0, 1), cA + hstepA, voffA);
;         if (wr == 1) PG8_BAR;
;         PG8_WAIT_V(2); PG8_BAR;
;         PG8_STAGE(PG8_SB(1, 0), cB + kstep, voffB); PG8_STAGE(PG8_SA(1, 0), cA + kstep, voffA); PG8_STAGE(PG8_SB(1, 1), cB + hstepB + kstep, voffB);
;         PG8_WAIT_V(6); PG8_BAR;
.LBB0_579:
	v_readlane_b32 s14, v252, 22
	s_lshl_b32 s0, s14, 15
	v_readlane_b32 s15, v252, 23
	s_add_u32 s14, s4, 0xc800000
	v_readlane_b32 s16, v252, 16
	s_addc_u32 s15, s5, 0
	v_readlane_b32 s17, v252, 17
	s_and_b64 s[16:17], s[16:17], exec
	s_waitcnt lgkmcnt(0)
	s_cselect_b32 s17, s7, 0
	s_cselect_b32 s16, s6, 0
	s_lshl_b64 s[6:7], s[0:1], 3
	s_add_u32 s0, s4, s6
	s_addc_u32 s4, s5, s7
	s_add_u32 s24, s0, 0x32d40000
	s_addc_u32 s25, s4, 0
	s_lshl_b32 s0, s26, 5
	s_and_b32 s7, s0, 0x60
	s_add_i32 m0, s53, 0x18000
	v_lshl_add_u64 v[6:7], v[6:7], 0, s[38:39]
	s_lshl_b32 s6, s22, 13
	s_lshl_b32 s26, s7, 7
	s_waitcnt vmcnt(2)
	s_barrier
	global_load_lds_dwordx4 v[6:7], off
	v_lshl_add_u64 v[4:5], v[4:5], 0, s[38:39]
	s_add_i32 m0, s53, 0x1a000
	s_add_i32 s0, s53, 0x8000
	s_add_i32 s57, s53, 0xa000
	global_load_lds_dwordx4 v[4:5], off
	v_lshl_add_u64 v[0:1], v[0:1], 0, s[38:39]
	s_mov_b32 m0, s0
	s_add_u32 s4, s44, 0x80080
	global_load_lds_dwordx4 v[0:1], off
	v_lshl_add_u64 v[0:1], v[2:3], 0, s[38:39]
	s_mov_b32 m0, s57
	s_addc_u32 s5, s45, 0
	global_load_lds_dwordx4 v[0:1], off
	s_add_i32 m0, s53, 0x1c000
	v_lshl_add_u64 v[0:1], s[4:5], 0, v[184:185]
	global_load_lds_dwordx4 v[0:1], off
	v_lshl_add_u64 v[0:1], s[4:5], 0, v[180:181]
	s_add_i32 m0, s53, 0x1e000
	s_cmpk_lt_u32 s20, 0x100
	global_load_lds_dwordx4 v[0:1], off
	v_bfe_u32 v1, v8, 4, 2
	v_and_b32_e32 v0, 15, v8
	v_lshlrev_b32_e32 v2, 4, v1
	v_lshl_or_b32 v33, s22, 6, v0
	v_lshl_or_b32 v0, v0, 6, v2
	v_lshlrev_b32_e32 v2, 2, v8
	v_and_b32_e32 v2, 32, v2
	v_bitop3_b32 v3, v0, s6, v2 bitop3:0xde
	v_bitop3_b32 v163, s26, v0, v2 bitop3:0xf6
	v_lshlrev_b32_e32 v0, 15, v13
	v_and_b32_e32 v0, 0xffff0000, v0
	v_cmp_eq_u32_e64 s[4:5], 0, v1
	v_lshl_or_b32 v171, v1, 3, s7
	v_lshl_add_u32 v0, v12, 12, v0
	v_and_b32_e32 v1, 1, v13
	v_lshl_or_b32 v0, v1, 6, v0
	v_lshl_add_u32 v188, v14, 1, v0
	v_lshlrev_b32_e32 v0, 15, v9
	v_and_b32_e32 v0, 0xffff0000, v0
	s_waitcnt vmcnt(0)
	v_lshl_add_u32 v0, v10, 12, v0
	v_and_b32_e32 v1, 1, v9
	s_cselect_b64 s[26:27], -1, 0
	s_cmp_lg_u64 s[16:17], 0
	v_lshl_or_b32 v0, v1, 6, v0
	v_readlane_b32 s6, v254, 55
	s_mov_b32 s58, 0
	s_cselect_b64 s[28:29], -1, 0
	v_mov_b32_e32 v189, v32
	v_lshl_add_u32 v190, v11, 1, v0
	v_mov_b32_e32 v191, v32
	v_add_u32_e32 v220, 0, v3
	v_readlane_b32 s20, v254, 38
	s_mov_b32 s22, s6
	s_barrier
	v_readlane_b32 s7, v254, 56
	s_branch .LBB0_582

; #define PG8_STAGE(bufoff, gbase, voff) do { _Pragma("unroll") for (int _i = 0; _i < 2; ++_i) \
;         __builtin_amdgcn_global_load_lds((const unsigned*)((const char*)(gbase) + (voff)[_i]), (PG8_LAS unsigned*)(lds + (bufoff) + ldsw + _i * 8192), 16, 0, 0); } while (0)
; #define PG8_WAIT_V(n) asm volatile("s_waitcnt vmcnt(" #n ")" ::: "memory")
; #define PG8_WAIT_L(n) asm volatile("s_waitcnt lgkmcnt(" #n ")" ::: "memory")
; #define PG8_BAR __builtin_amdgcn_s_barrier()
; #define PG8_SCHED __builtin_amdgcn_sched_barrier(0)
; template <class Epi, class Sched, bool ALIGN_EPI = false, bool SP2 = false, bool FP8 = false>
; __device__ __forceinline__ void gemm_phase(PG8_LAS unsigned char* lds, const Gemm g, const Sched& S, const Epi& E, const int tid) {
;     ...
;             if constexpr (SP2) {
;             PG8_LDB(B0, 0, 0); PG8_LDB(B1, 0, 1); PG8_SCHED; PG8_LDA(At, 0, 0); PG8_STAGE(PG8_SA(1, 1), a1 + hstepA, voffA);
;             PG8_WAIT_V(8); PG8_WAIT_L(0); PG8_BAR; PG8_MMA(0, 0, At, B0); PG8_MMA(0, 1, At, B1); PG8_BAR; PG8_SCHED;
;             PG8_LDA(At, 0, 1); PG8_STAGE(PG8_SB(0, 0), b2, voffB); PG8_STAGE(PG8_SB(0, 1), b2 + hstepB, voffB); PG8_STAGE(PG8_SA(0, 0), a2, voffA);
;             PG8_WAIT_V(8); PG8_WAIT_L(0); PG8_BAR; PG8_MMA(1, 0, At, B0); PG8_MMA(1, 1, At, B1); PG8_BAR; PG8_SCHED;
.LBB0_589:
	s_add_u32 s44, s8, 0xfff80080
	s_addc_u32 s45, s9, -1
	s_add_i32 s63, 0, 0x10000
	s_cmp_eq_u32 s62, 28
	s_cselect_b32 s47, s33, s45
	s_cselect_b32 s46, s35, s44
	s_cselect_b32 s45, s31, s61
	s_cselect_b32 s44, s59, s60
	s_add_i32 s66, 0, 0x14000
	v_add_u32_e32 v142, s63, v163
	v_add_u32_e32 v158, s66, v163
	ds_read_b128 v[130:133], v142
	ds_read_b128 v[134:137], v142 offset:1024
	ds_read_b128 v[138:141], v142 offset:2048
	ds_read_b128 v[142:145], v142 offset:3072
	ds_read_b128 v[146:149], v158
	ds_read_b128 v[150:153], v158 offset:1024
	ds_read_b128 v[154:157], v158 offset:2048
	ds_read_b128 v[158:161], v158 offset:3072
	v_lshl_add_u64 v[164:165], s[8:9], 0, v[188:189]
	s_add_i32 m0, s53, 0xc000
	ds_read_b128 v[192:195], v220
	ds_read_b128 v[196:199], v220 offset:1024
	ds_read_b128 v[222:225], v220 offset:2048
	ds_read_b128 v[226:229], v220 offset:3072
	ds_read_b128 v[230:233], v220 offset:4096
	ds_read_b128 v[234:237], v220 offset:5120
	ds_read_b128 v[238:241], v220 offset:6144
	ds_read_b128 v[242:245], v220 offset:7168
	global_load_lds_dwordx4 v[164:165], off
	v_lshl_add_u64 v[164:165], s[8:9], 0, v[190:191]
	s_add_i32 m0, s53, 0xe000
	s_nop 0
	global_load_lds_dwordx4 v[164:165], off
	s_cmp_eq_i32 s62, -2
	s_cbranch_scc1 .Lskw_3_0
	s_waitcnt vmcnt(8)
.Lskw_3_0:
	s_waitcnt lgkmcnt(0)
	s_barrier
	s_setprio 1
	s_waitcnt lgkmcnt(0)
	v_mfma_f32_16x16x32_bf16 v[126:129], v[130:133], v[192:195], v[126:129]
	v_mfma_f32_16x16x32_bf16 v[122:125], v[138:141], v[192:195], v[122:125]
	v_mfma_f32_16x16x32_bf16 v[110:113], v[130:133], v[222:225], v[110:113]
	v_mfma_f32_16x16x32_bf16 v[106:109], v[138:141], v[222:225], v[106:109]
	v_mfma_f32_16x16x32_bf16 v[94:97], v[130:133], v[230:233], v[94:97]
	v_mfma_f32_16x16x32_bf16 v[90:93], v[138:141], v[230:233], v[90:93]
	v_mfma_f32_16x16x32_bf16 v[78:81], v[130:133], v[238:241], v[78:81]
	v_mfma_f32_16x16x32_bf16 v[74:77], v[138:141], v[238:241], v[74:77]
	v_mfma_f32_16x16x32_bf16 v[126:129], v[134:137], v[196:199], v[126:129]
	v_mfma_f32_16x16x32_bf16 v[122:125], v[142:145], v[196:199], v[122:125]
	v_mfma_f32_16x16x32_bf16 v[110:113], v[134:137], v[226:229], v[110:113]
	v_mfma_f32_16x16x32_bf16 v[106:109], v[142:145], v[226:229], v[106:109]
	v_mfma_f32_16x16x32_bf16 v[94:97], v[134:137], v[234:237], v[94:97]
	v_mfma_f32_16x16x32_bf16 v[90:93], v[142:145], v[234:237], v[90:93]
	v_mfma_f32_16x16x32_bf16 v[78:81], v[134:137], v[242:245], v[78:81]
	v_mfma_f32_16x16x32_bf16 v[74:77], v[142:145], v[242:245], v[74:77]
	s_setprio 0
	s_setprio 1
	v_mfma_f32_16x16x32_bf16 v[118:121], v[146:149], v[192:195], v[118:121]
	v_mfma_f32_16x16x32_bf16 v[114:117], v[154:157], v[192:195], v[114:117]
	v_mfma_f32_16x16x32_bf16 v[102:105], v[146:149], v[222:225], v[102:105]
	v_mfma_f32_16x16x32_bf16 v[98:101], v[154:157], v[222:225], v[98:101]
	v_mfma_f32_16x16x32_bf16 v[86:89], v[146:149], v[230:233], v[86:89]
	v_mfma_f32_16x16x32_bf16 v[82:85], v[154:157], v[230:233], v[82:85]
	v_mfma_f32_16x16x32_bf16 v[70:73], v[146:149], v[238:241], v[70:73]
	v_mfma_f32_16x16x32_bf16 v[66:69], v[154:157], v[238:241], v[66:69]
	v_mfma_f32_16x16x32_bf16 v[118:121], v[150:153], v[196:199], v[118:121]
	v_mfma_f32_16x16x32_bf16 v[114:117], v[158:161], v[196:199], v[114:117]
	v_mfma_f32_16x16x32_bf16 v[102:105], v[150:153], v[226:229], v[102:105]
	v_mfma_f32_16x16x32_bf16 v[98:101], v[158:161], v[226:229], v[98:101]
	v_mfma_f32_16x16x32_bf16 v[86:89], v[150:153], v[234:237], v[86:89]
	v_mfma_f32_16x16x32_bf16 v[82:85], v[158:161], v[234:237], v[82:85]
	v_mfma_f32_16x16x32_bf16 v[70:73], v[150:153], v[242:245], v[70:73]
	v_mfma_f32_16x16x32_bf16 v[66:69], v[158:161], v[242:245], v[66:69]
	s_setprio 0
	s_barrier
	s_add_i32 s63, s63, s52
	v_lshl_add_u64 v[164:165], s[44:45], 0, v[184:185]
	s_mov_b32 m0, s63
	ds_read_b128 v[192:195], v220 offset:16384
	ds_read_b128 v[196:199], v220 offset:17408
	ds_read_b128 v[222:225], v220 offset:18432
	ds_read_b128 v[226:229], v220 offset:19456
	ds_read_b128 v[230:233], v220 offset:20480
	ds_read_b128 v[234:237], v220 offset:21504
	ds_read_b128 v[238:241], v220 offset:22528
	ds_read_b128 v[242:245], v220 offset:23552
	global_load_lds_dwordx4 v[164:165], off
	s_add_i32 m0, s63, 0x2000
	s_add_u32 s64, s44, 0x80000
	v_lshl_add_u64 v[166:167], s[44:45], 0, v[180:181]
	s_addc_u32 s65, s45, 0
	s_add_i32 s63, s66, s52
	global_load_lds_dwordx4 v[166:167], off
	v_lshl_add_u64 v[200:201], s[64:65], 0, v[184:185]
	s_mov_b32 m0, s63
	v_lshl_add_u64 v[246:247], s[46:47], 0, v[182:183]
	global_load_lds_dwordx4 v[200:201], off
	v_lshl_add_u64 v[200:201], s[64:65], 0, v[180:181]
	s_add_i32 m0, s63, 0x2000
	s_nop 0
	global_load_lds_dwordx4 v[200:201], off
	v_lshl_add_u64 v[200:201], s[46:47], 0, v[186:187]
	s_mov_b32 m0, s53
	s_nop 0
	global_load_lds_dwordx4 v[200:201], off
	s_mov_b32 m0, s54
	s_nop 0
	global_load_lds_dwordx4 v[246:247], off
	s_cmp_eq_i32 s62, -2
	s_cbranch_scc1 .Lskw_3_1
	s_waitcnt vmcnt(8)
; #define PG8_STAGE(bufoff, gbase, voff) do { _Pragma("unroll") for (int _i = 0; _i < 2; ++_i) \
;         __builtin_amdgcn_global_load_lds((const unsigned*)((const char*)(gbase) + (voff)[_i]), (PG8_LAS unsigned*)(lds + (bufoff) + ldsw + _i * 8192), 16, 0, 0); } while (0)
; #define PG8_WAIT_V(n) asm volatile("s_waitcnt vmcnt(" #n ")" ::: "memory")
; #define PG8_WAIT_L(n) asm volatile("s_waitcnt lgkmcnt(" #n ")" ::: "memory")
; #define PG8_BAR __builtin_amdgcn_s_barrier()
; #define PG8_SCHED __builtin_amdgcn_sched_barrier(0)
; template <class Epi, class Sched, bool ALIGN_EPI = false, bool SP2 = false, bool FP8 = false>
; __device__ __forceinline__ void gemm_phase(PG8_LAS unsigned char* lds, const Gemm g, const Sched& S, const Epi& E, const int tid) {
;     ...
;             PG8_WAIT_V(8); PG8_WAIT_L(0); PG8_BAR; PG8_MMA(1, 0, At, B0); PG8_MMA(1, 1, At, B1); PG8_BAR; PG8_SCHED;
;             PG8_LDB(B0, 1, 0); PG8_LDB(B1, 1, 1); PG8_SCHED; PG8_LDA(At, 1, 0); PG8_STAGE(PG8_SA(0, 1), a2 + hstepA, voffA);
;             PG8_WAIT_V(8); PG8_WAIT_L(0); PG8_BAR; PG8_MMA(0, 0, At, B0); PG8_MMA(0, 1, At, B1); PG8_BAR; PG8_SCHED;
.Lskw_3_1:
	s_waitcnt lgkmcnt(0)
	s_barrier
	s_setprio 1
	s_waitcnt lgkmcnt(0)
	v_mfma_f32_16x16x32_bf16 v[62:65], v[130:133], v[192:195], v[62:65]
	v_mfma_f32_16x16x32_bf16 v[58:61], v[138:141], v[192:195], v[58:61]
	v_mfma_f32_16x16x32_bf16 v[46:49], v[130:133], v[222:225], v[46:49]
	v_mfma_f32_16x16x32_bf16 v[42:45], v[138:141], v[222:225], v[42:45]
	v_mfma_f32_16x16x32_bf16 v[28:31], v[130:133], v[230:233], v[28:31]
	v_mfma_f32_16x16x32_bf16 v[24:27], v[138:141], v[230:233], v[24:27]
	v_mfma_f32_16x16x32_bf16 v[12:15], v[130:133], v[238:241], v[12:15]
	v_mfma_f32_16x16x32_bf16 v[8:11], v[138:141], v[238:241], v[8:11]
	v_mfma_f32_16x16x32_bf16 v[62:65], v[134:137], v[196:199], v[62:65]
	v_mfma_f32_16x16x32_bf16 v[58:61], v[142:145], v[196:199], v[58:61]
	v_mfma_f32_16x16x32_bf16 v[46:49], v[134:137], v[226:229], v[46:49]
	v_mfma_f32_16x16x32_bf16 v[42:45], v[142:145], v[226:229], v[42:45]
	v_mfma_f32_16x16x32_bf16 v[28:31], v[134:137], v[234:237], v[28:31]
	v_mfma_f32_16x16x32_bf16 v[24:27], v[142:145], v[234:237], v[24:27]
	v_mfma_f32_16x16x32_bf16 v[12:15], v[134:137], v[242:245], v[12:15]
	v_mfma_f32_16x16x32_bf16 v[8:11], v[142:145], v[242:245], v[8:11]
	s_setprio 0
	s_setprio 1
	v_mfma_f32_16x16x32_bf16 v[54:57], v[146:149], v[192:195], v[54:57]
	v_mfma_f32_16x16x32_bf16 v[50:53], v[154:157], v[192:195], v[50:53]
	v_mfma_f32_16x16x32_bf16 v[38:41], v[146:149], v[222:225], v[38:41]
	v_mfma_f32_16x16x32_bf16 v[34:37], v[154:157], v[222:225], v[34:37]
	v_mfma_f32_16x16x32_bf16 v[20:23], v[146:149], v[230:233], v[20:23]
	v_mfma_f32_16x16x32_bf16 v[16:19], v[154:157], v[230:233], v[16:19]
	v_mfma_f32_16x16x32_bf16 v[4:7], v[146:149], v[238:241], v[4:7]
	v_mfma_f32_16x16x32_bf16 v[0:3], v[154:157], v[238:241], v[0:3]
	v_mfma_f32_16x16x32_bf16 v[54:57], v[150:153], v[196:199], v[54:57]
	v_mfma_f32_16x16x32_bf16 v[50:53], v[158:161], v[196:199], v[50:53]
	v_mfma_f32_16x16x32_bf16 v[38:41], v[150:153], v[226:229], v[38:41]
	v_mfma_f32_16x16x32_bf16 v[34:37], v[158:161], v[226:229], v[34:37]
	v_mfma_f32_16x16x32_bf16 v[20:23], v[150:153], v[234:237], v[20:23]
	v_mfma_f32_16x16x32_bf16 v[16:19], v[158:161], v[234:237], v[16:19]
	v_mfma_f32_16x16x32_bf16 v[4:7], v[150:153], v[242:245], v[4:7]
	v_mfma_f32_16x16x32_bf16 v[0:3], v[158:161], v[242:245], v[0:3]
	s_setprio 0
	s_barrier
	s_add_i32 s63, 0, 0x18000
	s_add_i32 s64, 0, 0x1c000
	v_add_u32_e32 v142, s63, v163
	v_add_u32_e32 v158, s64, v163
	ds_read_b128 v[130:133], v142
	ds_read_b128 v[134:137], v142 offset:1024
	ds_read_b128 v[138:141], v142 offset:2048
	ds_read_b128 v[142:145], v142 offset:3072
	ds_read_b128 v[146:149], v158
	ds_read_b128 v[150:153], v158 offset:1024
	ds_read_b128 v[154:157], v158 offset:2048
	ds_read_b128 v[158:161], v158 offset:3072
	s_add_u32 s46, s46, 0x80000
	s_addc_u32 s47, s47, 0
	s_mov_b32 m0, s55
	v_lshl_add_u64 v[248:249], s[46:47], 0, v[186:187]
	ds_read_b128 v[192:195], v220 offset:32768
	ds_read_b128 v[196:199], v220 offset:33792
	ds_read_b128 v[222:225], v220 offset:34816
	ds_read_b128 v[226:229], v220 offset:35840
	ds_read_b128 v[230:233], v220 offset:36864
	ds_read_b128 v[234:237], v220 offset:37888
	ds_read_b128 v[238:241], v220 offset:38912
	ds_read_b128 v[242:245], v220 offset:39936
	global_load_lds_dwordx4 v[248:249], off
	v_lshl_add_u64 v[248:249], s[46:47], 0, v[182:183]
	s_mov_b32 m0, s56
	s_nop 0
	global_load_lds_dwordx4 v[248:249], off
	s_waitcnt vmcnt(8)
	s_waitcnt lgkmcnt(0)
	s_barrier
	s_setprio 1
	s_waitcnt lgkmcnt(0)
	v_mfma_f32_16x16x32_bf16 v[126:129], v[130:133], v[192:195], v[126:129]
	v_mfma_f32_16x16x32_bf16 v[122:125], v[138:141], v[192:195], v[122:125]
	v_mfma_f32_16x16x32_bf16 v[110:113], v[130:133], v[222:225], v[110:113]
	v_mfma_f32_16x16x32_bf16 v[106:109], v[138:141], v[222:225], v[106:109]
	v_mfma_f32_16x16x32_bf16 v[94:97], v[130:133], v[230:233], v[94:97]
	v_mfma_f32_16x16x32_bf16 v[90:93], v[138:141], v[230:233], v[90:93]
	v_mfma_f32_16x16x32_bf16 v[78:81], v[130:133], v[238:241], v[78:81]
	v_mfma_f32_16x16x32_bf16 v[74:77], v[138:141], v[238:241], v[74:77]
	v_mfma_f32_16x16x32_bf16 v[126:129], v[134:137], v[196:199], v[126:129]
	v_mfma_f32_16x16x32_bf16 v[122:125], v[142:145], v[196:199], v[122:125]
	v_mfma_f32_16x16x32_bf16 v[110:113], v[134:137], v[226:229], v[110:113]
	v_mfma_f32_16x16x32_bf16 v[106:109], v[142:145], v[226:229], v[106:109]
	v_mfma_f32_16x16x32_bf16 v[94:97], v[134:137], v[234:237], v[94:97]
	v_mfma_f32_16x16x32_bf16 v[90:93], v[142:145], v[234:237], v[90:93]
	v_mfma_f32_16x16x32_bf16 v[78:81], v[134:137], v[242:245], v[78:81]
	v_mfma_f32_16x16x32_bf16 v[74:77], v[142:145], v[242:245], v[74:77]
	s_setprio 0
	s_setprio 1
	v_mfma_f32_16x16x32_bf16 v[118:121], v[146:149], v[192:195], v[118:121]
	v_mfma_f32_16x16x32_bf16 v[114:117], v[154:157], v[192:195], v[114:117]
	v_mfma_f32_16x16x32_bf16 v[102:105], v[146:149], v[222:225], v[102:105]
	v_mfma_f32_16x16x32_bf16 v[98:101], v[154:157], v[222:225], v[98:101]
	v_mfma_f32_16x16x32_bf16 v[86:89], v[146:149], v[230:233], v[86:89]
	v_mfma_f32_16x16x32_bf16 v[82:85], v[154:157], v[230:233], v[82:85]
	v_mfma_f32_16x16x32_bf16 v[70:73], v[146:149], v[238:241], v[70:73]
	v_mfma_f32_16x16x32_bf16 v[66:69], v[154:157], v[238:241], v[66:69]
	v_mfma_f32_16x16x32_bf16 v[118:121], v[150:153], v[196:199], v[118:121]
	v_mfma_f32_16x16x32_bf16 v[114:117], v[158:161], v[196:199], v[114:117]
	v_mfma_f32_16x16x32_bf16 v[102:105], v[150:153], v[226:229], v[102:105]
	v_mfma_f32_16x16x32_bf16 v[98:101], v[158:161], v[226:229], v[98:101]
	v_mfma_f32_16x16x32_bf16 v[86:89], v[150:153], v[234:237], v[86:89]
	v_mfma_f32_16x16x32_bf16 v[82:85], v[158:161], v[234:237], v[82:85]
	v_mfma_f32_16x16x32_bf16 v[70:73], v[150:153], v[242:245], v[70:73]
	v_mfma_f32_16x16x32_bf16 v[66:69], v[158:161], v[242:245], v[66:69]
	s_setprio 0
	s_barrier
; #define PG8_STAGE(bufoff, gbase, voff) do { _Pragma("unroll") for (int _i = 0; _i < 2; ++_i) \
;         __builtin_amdgcn_global_load_lds((const unsigned*)((const char*)(gbase) + (voff)[_i]), (PG8_LAS unsigned*)(lds + (bufoff) + ldsw + _i * 8192), 16, 0, 0); } while (0)
; #define PG8_WAIT_V(n) asm volatile("s_waitcnt vmcnt(" #n ")" ::: "memory")
; #define PG8_WAIT_L(n) asm volatile("s_waitcnt lgkmcnt(" #n ")" ::: "memory")
; #define PG8_BAR __builtin_amdgcn_s_barrier()
; #define PG8_SCHED __builtin_amdgcn_sched_barrier(0)
; template <class Epi, class Sched, bool ALIGN_EPI = false, bool SP2 = false, bool FP8 = false>
; __device__ __forceinline__ void gemm_phase(PG8_LAS unsigned char* lds, const Gemm g, const Sched& S, const Epi& E, const int tid) {
;     ...
;             PG8_LDA(At, 1, 1); PG8_STAGE(PG8_SB(1, 0), b3, voffB); PG8_STAGE(PG8_SB(1, 1), b3 + hstepB, voffB); PG8_STAGE(PG8_SA(1, 0), a3, voffA);
;             PG8_WAIT_V(8); PG8_WAIT_L(0); PG8_BAR; PG8_MMA(1, 0, At, B0); PG8_MMA(1, 1, At, B1); PG8_BAR; PG8_SCHED;
;     ...
;         if constexpr (ALIGN_EPI) { if (wr == 0) PG8_BAR; }
	s_add_i32 s46, s63, s52
	v_lshl_add_u64 v[164:165], v[164:165], 0, s[38:39]
	s_mov_b32 m0, s46
	ds_read_b128 v[192:195], v220 offset:49152
	ds_read_b128 v[196:199], v220 offset:50176
	ds_read_b128 v[222:225], v220 offset:51200
	ds_read_b128 v[226:229], v220 offset:52224
	ds_read_b128 v[230:233], v220 offset:53248
	ds_read_b128 v[234:237], v220 offset:54272
	ds_read_b128 v[238:241], v220 offset:55296
	ds_read_b128 v[242:245], v220 offset:56320
	global_load_lds_dwordx4 v[164:165], off
	s_add_i32 m0, s46, 0x2000
	s_add_u32 s44, s44, 0x80080
	v_lshl_add_u64 v[164:165], v[166:167], 0, s[38:39]
	s_addc_u32 s45, s45, 0
	s_add_i32 s46, s64, s52
	global_load_lds_dwordx4 v[164:165], off
	v_lshl_add_u64 v[164:165], s[44:45], 0, v[184:185]
	s_mov_b32 m0, s46
	s_nop 0
	global_load_lds_dwordx4 v[164:165], off
	v_lshl_add_u64 v[164:165], s[44:45], 0, v[180:181]
	s_add_i32 m0, s46, 0x2000
	s_nop 0
	global_load_lds_dwordx4 v[164:165], off
	v_lshl_add_u64 v[164:165], v[200:201], 0, s[38:39]
	s_mov_b32 m0, s0
	s_nop 0
	global_load_lds_dwordx4 v[164:165], off
	v_lshl_add_u64 v[164:165], v[246:247], 0, s[38:39]
	s_mov_b32 m0, s57
	s_nop 0
	global_load_lds_dwordx4 v[164:165], off
	s_waitcnt vmcnt(8)
	s_waitcnt lgkmcnt(0)
	s_barrier
	s_setprio 1
	s_waitcnt lgkmcnt(0)
	v_mfma_f32_16x16x32_bf16 v[62:65], v[130:133], v[192:195], v[62:65]
	v_mfma_f32_16x16x32_bf16 v[58:61], v[138:141], v[192:195], v[58:61]
	v_mfma_f32_16x16x32_bf16 v[46:49], v[130:133], v[222:225], v[46:49]
	v_mfma_f32_16x16x32_bf16 v[42:45], v[138:141], v[222:225], v[42:45]
	v_mfma_f32_16x16x32_bf16 v[28:31], v[130:133], v[230:233], v[28:31]
	v_mfma_f32_16x16x32_bf16 v[24:27], v[138:141], v[230:233], v[24:27]
	v_mfma_f32_16x16x32_bf16 v[12:15], v[130:133], v[238:241], v[12:15]
	v_mfma_f32_16x16x32_bf16 v[8:11], v[138:141], v[238:241], v[8:11]
	v_mfma_f32_16x16x32_bf16 v[62:65], v[134:137], v[196:199], v[62:65]
	v_mfma_f32_16x16x32_bf16 v[58:61], v[142:145], v[196:199], v[58:61]
	v_mfma_f32_16x16x32_bf16 v[46:49], v[134:137], v[226:229], v[46:49]
	v_mfma_f32_16x16x32_bf16 v[42:45], v[142:145], v[226:229], v[42:45]
	v_mfma_f32_16x16x32_bf16 v[28:31], v[134:137], v[234:237], v[28:31]
	v_mfma_f32_16x16x32_bf16 v[24:27], v[142:145], v[234:237], v[24:27]
	v_mfma_f32_16x16x32_bf16 v[12:15], v[134:137], v[242:245], v[12:15]
	v_mfma_f32_16x16x32_bf16 v[8:11], v[142:145], v[242:245], v[8:11]
	s_setprio 0
	s_setprio 1
	v_mfma_f32_16x16x32_bf16 v[54:57], v[146:149], v[192:195], v[54:57]
	v_mfma_f32_16x16x32_bf16 v[50:53], v[154:157], v[192:195], v[50:53]
	v_mfma_f32_16x16x32_bf16 v[38:41], v[146:149], v[222:225], v[38:41]
	v_mfma_f32_16x16x32_bf16 v[34:37], v[154:157], v[222:225], v[34:37]
	v_mfma_f32_16x16x32_bf16 v[20:23], v[146:149], v[230:233], v[20:23]
	v_mfma_f32_16x16x32_bf16 v[16:19], v[154:157], v[230:233], v[16:19]
	v_mfma_f32_16x16x32_bf16 v[4:7], v[146:149], v[238:241], v[4:7]
	v_mfma_f32_16x16x32_bf16 v[0:3], v[154:157], v[238:241], v[0:3]
	v_mfma_f32_16x16x32_bf16 v[54:57], v[150:153], v[196:199], v[54:57]
	v_mfma_f32_16x16x32_bf16 v[50:53], v[158:161], v[196:199], v[50:53]
	v_mfma_f32_16x16x32_bf16 v[38:41], v[150:153], v[226:229], v[38:41]
	v_mfma_f32_16x16x32_bf16 v[34:37], v[158:161], v[226:229], v[34:37]
	v_mfma_f32_16x16x32_bf16 v[20:23], v[150:153], v[234:237], v[20:23]
	v_mfma_f32_16x16x32_bf16 v[16:19], v[158:161], v[234:237], v[16:19]
	v_mfma_f32_16x16x32_bf16 v[4:7], v[150:153], v[242:245], v[4:7]
	v_mfma_f32_16x16x32_bf16 v[0:3], v[158:161], v[242:245], v[0:3]
	s_setprio 0
	s_barrier
	s_add_i32 s62, s62, 2
	s_add_u32 s8, s8, 0x100
	s_addc_u32 s9, s9, 0
	s_add_u32 s60, s60, 0x100
	s_addc_u32 s61, s61, 0
	s_cmp_gt_u32 s62, 29
	s_cbranch_scc0 .LBB0_589
	s_and_b64 vcc, exec, s[26:27]
	s_cbranch_vccz .LBB0_592
	s_barrier

; #define PG8_STAGE(bufoff, gbase, voff) do { _Pragma("unroll") for (int _i = 0; _i < 2; ++_i) \
;         __builtin_amdgcn_global_load_lds((const unsigned*)((const char*)(gbase) + (voff)[_i]), (PG8_LAS unsigned*)(lds + (bufoff) + ldsw + _i * 8192), 16, 0, 0); } while (0)
; #define PG8_WAIT_V(n) asm volatile("s_waitcnt vmcnt(" #n ")" ::: "memory")
; #define PG8_BAR __builtin_amdgcn_s_barrier()
; template <class Epi, class Sched, bool ALIGN_EPI = false, bool SP2 = false, bool FP8 = false>
; __device__ __forceinline__ void gemm_phase(PG8_LAS unsigned char* lds, const Gemm g, const Sched& S, const Epi& E, const int tid) {
;     ...
;     if constexpr (SP2) {
;         PG8_STAGE(PG8_SB(0, 0), cB, voffB); PG8_STAGE(PG8_SB(0, 1), cB + hstepB, voffB); PG8_STAGE(PG8_SA(0, 0), cA, voffA); PG8_STAGE(PG8_SA(0, 1), cA + hstepA, voffA);
;         if (wr == 1) PG8_BAR;
;         PG8_WAIT_V(2); PG8_BAR;
;         PG8_STAGE(PG8_SB(1, 0), cB + kstep, voffB); PG8_STAGE(PG8_SA(1, 0), cA + kstep, voffA); PG8_STAGE(PG8_SB(1, 1), cB + hstepB + kstep, voffB);
;         PG8_WAIT_V(6); PG8_BAR;
.LBB0_725:
	s_add_u32 s10, s4, 0x10800000
	v_readlane_b32 s12, v252, 22
	s_addc_u32 s11, s5, 0
	v_readlane_b32 s13, v252, 23
	s_lshl_b32 s0, s12, 15
	s_lshl_b64 s[12:13], s[0:1], 3
	s_add_u32 s0, s4, s12
	s_addc_u32 s4, s5, s13
	s_add_u32 s12, s0, 0x32d40000
	s_addc_u32 s13, s4, 0
	s_lshl_b32 s0, s16, 5
	s_and_b32 s16, s0, 0x60
	s_add_i32 m0, s47, 0x18000
	v_lshl_add_u64 v[6:7], v[6:7], 0, s[38:39]
	s_lshl_b32 s17, s15, 13
	s_lshl_b32 s20, s16, 7
	s_waitcnt vmcnt(2)
	s_barrier
	global_load_lds_dwordx4 v[6:7], off
	v_lshl_add_u64 v[4:5], v[4:5], 0, s[38:39]
	s_add_i32 m0, s47, 0x1a000
	s_add_i32 s0, s47, 0x8000
	s_add_i32 s51, s47, 0xa000
	global_load_lds_dwordx4 v[4:5], off
	v_lshl_add_u64 v[0:1], v[0:1], 0, s[38:39]
	s_mov_b32 m0, s0
	s_add_u32 s4, s34, 0x80080
	global_load_lds_dwordx4 v[0:1], off
	v_lshl_add_u64 v[0:1], v[2:3], 0, s[38:39]
	s_mov_b32 m0, s51
	s_addc_u32 s5, s35, 0
	global_load_lds_dwordx4 v[0:1], off
	s_add_i32 m0, s47, 0x1c000
	v_lshl_add_u64 v[0:1], s[4:5], 0, v[134:135]
	global_load_lds_dwordx4 v[0:1], off
	v_lshl_add_u64 v[0:1], s[4:5], 0, v[130:131]
	s_add_i32 m0, s47, 0x1e000
	s_cmpk_lt_u32 s14, 0x100
	global_load_lds_dwordx4 v[0:1], off
	v_lshrrev_b32_e32 v1, 1, v8
	v_and_b32_e32 v1, 24, v1
	v_and_b32_e32 v0, 15, v8
	v_lshlrev_b32_e32 v2, 1, v1
	v_lshl_or_b32 v33, s15, 6, v0
	v_lshl_or_b32 v0, v0, 6, v2
	v_lshlrev_b32_e32 v2, 2, v8
	v_and_b32_e32 v2, 32, v2
	v_bitop3_b32 v3, v0, s17, v2 bitop3:0xde
	v_bitop3_b32 v150, s20, v0, v2 bitop3:0xf6
	v_lshlrev_b32_e32 v0, 15, v13
	v_and_b32_e32 v0, 0xffff0000, v0
	v_or_b32_e32 v151, s16, v1
	v_lshl_add_u32 v0, v12, 12, v0
	v_and_b32_e32 v1, 1, v13
	v_lshl_or_b32 v0, v1, 6, v0
	v_lshl_add_u32 v138, v14, 1, v0
	v_lshlrev_b32_e32 v0, 15, v9
	v_and_b32_e32 v0, 0xffff0000, v0
	s_waitcnt vmcnt(0)
	v_lshl_add_u32 v0, v10, 12, v0
	v_and_b32_e32 v1, 1, v9
	v_lshl_or_b32 v0, v1, 6, v0
	v_readlane_b32 s4, v254, 49
	s_cselect_b64 s[14:15], -1, 0
	v_mov_b32_e32 v139, v32
	v_lshl_add_u32 v140, v11, 1, v0
	v_mov_b32_e32 v141, v32
	s_mov_b32 s52, 0
	v_add_u32_e32 v152, 0, v3
	v_readlane_b32 s20, v254, 35
	s_mov_b32 s22, s4
	s_barrier
	v_readlane_b32 s5, v254, 50
	s_branch .LBB0_728

; #define PG8_STAGE(bufoff, gbase, voff) do { _Pragma("unroll") for (int _i = 0; _i < 2; ++_i) \
;         __builtin_amdgcn_global_load_lds((const unsigned*)((const char*)(gbase) + (voff)[_i]), (PG8_LAS unsigned*)(lds + (bufoff) + ldsw + _i * 8192), 16, 0, 0); } while (0)
; #define PG8_WAIT_V(n) asm volatile("s_waitcnt vmcnt(" #n ")" ::: "memory")
; #define PG8_WAIT_L(n) asm volatile("s_waitcnt lgkmcnt(" #n ")" ::: "memory")
; #define PG8_BAR __builtin_amdgcn_s_barrier()
; #define PG8_SCHED __builtin_amdgcn_sched_barrier(0)
; template <class Epi, class Sched, bool ALIGN_EPI = false, bool SP2 = false, bool FP8 = false>
; __device__ __forceinline__ void gemm_phase(PG8_LAS unsigned char* lds, const Gemm g, const Sched& S, const Epi& E, const int tid) {
;     ...
;             if constexpr (SP2) {
;             PG8_LDB(B0, 0, 0); PG8_LDB(B1, 0, 1); PG8_SCHED; PG8_LDA(At, 0, 0); PG8_STAGE(PG8_SA(1, 1), a1 + hstepA, voffA);
;             PG8_WAIT_V(8); PG8_WAIT_L(0); PG8_BAR; PG8_MMA(0, 0, At, B0); PG8_MMA(0, 1, At, B1); PG8_BAR; PG8_SCHED;
;             PG8_LDA(At, 0, 1); PG8_STAGE(PG8_SB(0, 0), b2, voffB); PG8_STAGE(PG8_SB(0, 1), b2 + hstepB, voffB); PG8_STAGE(PG8_SA(0, 0), a2, voffA);
;             PG8_WAIT_V(8); PG8_WAIT_L(0); PG8_BAR; PG8_MMA(1, 0, At, B0); PG8_MMA(1, 1, At, B1); PG8_BAR; PG8_SCHED;
.LBB0_735:
	s_add_u32 s34, s30, 0xfff80080
	s_addc_u32 s35, s31, -1
	s_add_i32 s57, 0, 0x10000
	s_cmp_eq_u32 s56, 28
	s_cselect_b32 s37, s25, s35
	s_cselect_b32 s36, s33, s34
	v_add_u32_e32 v153, s57, v150
	s_cselect_b32 s35, s17, s55
	s_cselect_b32 s34, s53, s54
	s_add_i32 s60, 0, 0x14000
	ds_read_b128 v[142:145], v153
	ds_read_b128 v[146:149], v153 offset:1024
	ds_read_b128 v[154:157], v153 offset:2048
	ds_read_b128 v[158:161], v153 offset:3072
	v_add_u32_e32 v153, s60, v150
	ds_read_b128 v[180:183], v153
	ds_read_b128 v[184:187], v153 offset:1024
	ds_read_b128 v[188:191], v153 offset:2048
	ds_read_b128 v[192:195], v153 offset:3072
	v_lshl_add_u64 v[164:165], s[30:31], 0, v[138:139]
	s_add_i32 m0, s47, 0xc000
	ds_read_b128 v[196:199], v152
	ds_read_b128 v[220:223], v152 offset:1024
	ds_read_b128 v[224:227], v152 offset:2048
	ds_read_b128 v[228:231], v152 offset:3072
	ds_read_b128 v[232:235], v152 offset:4096
	ds_read_b128 v[236:239], v152 offset:5120
	ds_read_b128 v[240:243], v152 offset:6144
	ds_read_b128 v[244:247], v152 offset:7168
	global_load_lds_dwordx4 v[164:165], off
	v_lshl_add_u64 v[164:165], s[30:31], 0, v[140:141]
	s_add_i32 m0, s47, 0xe000
	s_nop 0
	global_load_lds_dwordx4 v[164:165], off
	s_cmp_eq_i32 s56, -2
	s_cbranch_scc1 .Lskw_4_0
	s_waitcnt vmcnt(8)
.Lskw_4_0:
	s_waitcnt lgkmcnt(0)
	s_barrier
	s_setprio 1
	s_waitcnt lgkmcnt(0)
	v_mfma_f32_16x16x32_bf16 v[126:129], v[142:145], v[196:199], v[126:129]
	v_mfma_f32_16x16x32_bf16 v[122:125], v[154:157], v[196:199], v[122:125]
	v_mfma_f32_16x16x32_bf16 v[110:113], v[142:145], v[224:227], v[110:113]
	v_mfma_f32_16x16x32_bf16 v[106:109], v[154:157], v[224:227], v[106:109]
	v_mfma_f32_16x16x32_bf16 v[94:97], v[142:145], v[232:235], v[94:97]
	v_mfma_f32_16x16x32_bf16 v[90:93], v[154:157], v[232:235], v[90:93]
	v_mfma_f32_16x16x32_bf16 v[78:81], v[142:145], v[240:243], v[78:81]
	v_mfma_f32_16x16x32_bf16 v[74:77], v[154:157], v[240:243], v[74:77]
	v_mfma_f32_16x16x32_bf16 v[126:129], v[146:149], v[220:223], v[126:129]
	v_mfma_f32_16x16x32_bf16 v[122:125], v[158:161], v[220:223], v[122:125]
	v_mfma_f32_16x16x32_bf16 v[110:113], v[146:149], v[228:231], v[110:113]
	v_mfma_f32_16x16x32_bf16 v[106:109], v[158:161], v[228:231], v[106:109]
	v_mfma_f32_16x16x32_bf16 v[94:97], v[146:149], v[236:239], v[94:97]
	v_mfma_f32_16x16x32_bf16 v[90:93], v[158:161], v[236:239], v[90:93]
	v_mfma_f32_16x16x32_bf16 v[78:81], v[146:149], v[244:247], v[78:81]
	v_mfma_f32_16x16x32_bf16 v[74:77], v[158:161], v[244:247], v[74:77]
	s_setprio 0
	s_setprio 1
	v_mfma_f32_16x16x32_bf16 v[118:121], v[180:183], v[196:199], v[118:121]
	v_mfma_f32_16x16x32_bf16 v[114:117], v[188:191], v[196:199], v[114:117]
	v_mfma_f32_16x16x32_bf16 v[102:105], v[180:183], v[224:227], v[102:105]
	v_mfma_f32_16x16x32_bf16 v[98:101], v[188:191], v[224:227], v[98:101]
	v_mfma_f32_16x16x32_bf16 v[86:89], v[180:183], v[232:235], v[86:89]
	v_mfma_f32_16x16x32_bf16 v[82:85], v[188:191], v[232:235], v[82:85]
	v_mfma_f32_16x16x32_bf16 v[70:73], v[180:183], v[240:243], v[70:73]
	v_mfma_f32_16x16x32_bf16 v[66:69], v[188:191], v[240:243], v[66:69]
	v_mfma_f32_16x16x32_bf16 v[118:121], v[184:187], v[220:223], v[118:121]
	v_mfma_f32_16x16x32_bf16 v[114:117], v[192:195], v[220:223], v[114:117]
	v_mfma_f32_16x16x32_bf16 v[102:105], v[184:187], v[228:231], v[102:105]
	v_mfma_f32_16x16x32_bf16 v[98:101], v[192:195], v[228:231], v[98:101]
	v_mfma_f32_16x16x32_bf16 v[86:89], v[184:187], v[236:239], v[86:89]
	v_mfma_f32_16x16x32_bf16 v[82:85], v[192:195], v[236:239], v[82:85]
	v_mfma_f32_16x16x32_bf16 v[70:73], v[184:187], v[244:247], v[70:73]
	v_mfma_f32_16x16x32_bf16 v[66:69], v[192:195], v[244:247], v[66:69]
	s_setprio 0
	s_barrier
	s_add_i32 s57, s57, s46
	v_lshl_add_u64 v[164:165], s[34:35], 0, v[134:135]
	s_mov_b32 m0, s57
	ds_read_b128 v[196:199], v152 offset:16384
	ds_read_b128 v[220:223], v152 offset:17408
	ds_read_b128 v[224:227], v152 offset:18432
	ds_read_b128 v[228:231], v152 offset:19456
	ds_read_b128 v[232:235], v152 offset:20480
	ds_read_b128 v[236:239], v152 offset:21504
	ds_read_b128 v[240:243], v152 offset:22528
	ds_read_b128 v[244:247], v152 offset:23552
	global_load_lds_dwordx4 v[164:165], off
	s_add_i32 m0, s57, 0x2000
	s_add_u32 s58, s34, 0x80000
	v_lshl_add_u64 v[166:167], s[34:35], 0, v[130:131]
	s_addc_u32 s59, s35, 0
	s_add_i32 s57, s60, s46
	global_load_lds_dwordx4 v[166:167], off
	v_lshl_add_u64 v[200:201], s[58:59], 0, v[134:135]
	s_mov_b32 m0, s57
	v_lshl_add_u64 v[248:249], s[36:37], 0, v[132:133]
	global_load_lds_dwordx4 v[200:201], off
	v_lshl_add_u64 v[200:201], s[58:59], 0, v[130:131]
	s_add_i32 m0, s57, 0x2000
	s_nop 0
	global_load_lds_dwordx4 v[200:201], off
	v_lshl_add_u64 v[200:201], s[36:37], 0, v[136:137]
	s_mov_b32 m0, s47
	s_nop 0
	global_load_lds_dwordx4 v[200:201], off
	s_mov_b32 m0, s48
	s_nop 0
	global_load_lds_dwordx4 v[248:249], off
	s_cmp_eq_i32 s56, -2
	s_cbranch_scc1 .Lskw_4_1
	s_waitcnt vmcnt(8)
; #define PG8_STAGE(bufoff, gbase, voff) do { _Pragma("unroll") for (int _i = 0; _i < 2; ++_i) \
;         __builtin_amdgcn_global_load_lds((const unsigned*)((const char*)(gbase) + (voff)[_i]), (PG8_LAS unsigned*)(lds + (bufoff) + ldsw + _i * 8192), 16, 0, 0); } while (0)
; #define PG8_WAIT_V(n) asm volatile("s_waitcnt vmcnt(" #n ")" ::: "memory")
; #define PG8_WAIT_L(n) asm volatile("s_waitcnt lgkmcnt(" #n ")" ::: "memory")
; #define PG8_BAR __builtin_amdgcn_s_barrier()
; #define PG8_SCHED __builtin_amdgcn_sched_barrier(0)
; template <class Epi, class Sched, bool ALIGN_EPI = false, bool SP2 = false, bool FP8 = false>
; __device__ __forceinline__ void gemm_phase(PG8_LAS unsigned char* lds, const Gemm g, const Sched& S, const Epi& E, const int tid) {
;     ...
;             PG8_WAIT_V(8); PG8_WAIT_L(0); PG8_BAR; PG8_MMA(1, 0, At, B0); PG8_MMA(1, 1, At, B1); PG8_BAR; PG8_SCHED;
;             PG8_LDB(B0, 1, 0); PG8_LDB(B1, 1, 1); PG8_SCHED; PG8_LDA(At, 1, 0); PG8_STAGE(PG8_SA(0, 1), a2 + hstepA, voffA);
;             PG8_WAIT_V(8); PG8_WAIT_L(0); PG8_BAR; PG8_MMA(0, 0, At, B0); PG8_MMA(0, 1, At, B1); PG8_BAR; PG8_SCHED;
.Lskw_4_1:
	s_waitcnt lgkmcnt(0)
	s_barrier
	s_setprio 1
	s_waitcnt lgkmcnt(0)
	v_mfma_f32_16x16x32_bf16 v[62:65], v[142:145], v[196:199], v[62:65]
	v_mfma_f32_16x16x32_bf16 v[58:61], v[154:157], v[196:199], v[58:61]
	v_mfma_f32_16x16x32_bf16 v[46:49], v[142:145], v[224:227], v[46:49]
	v_mfma_f32_16x16x32_bf16 v[42:45], v[154:157], v[224:227], v[42:45]
	v_mfma_f32_16x16x32_bf16 v[28:31], v[142:145], v[232:235], v[28:31]
	v_mfma_f32_16x16x32_bf16 v[24:27], v[154:157], v[232:235], v[24:27]
	v_mfma_f32_16x16x32_bf16 v[12:15], v[142:145], v[240:243], v[12:15]
	v_mfma_f32_16x16x32_bf16 v[8:11], v[154:157], v[240:243], v[8:11]
	v_mfma_f32_16x16x32_bf16 v[62:65], v[146:149], v[220:223], v[62:65]
	v_mfma_f32_16x16x32_bf16 v[58:61], v[158:161], v[220:223], v[58:61]
	v_mfma_f32_16x16x32_bf16 v[46:49], v[146:149], v[228:231], v[46:49]
	v_mfma_f32_16x16x32_bf16 v[42:45], v[158:161], v[228:231], v[42:45]
	v_mfma_f32_16x16x32_bf16 v[28:31], v[146:149], v[236:239], v[28:31]
	v_mfma_f32_16x16x32_bf16 v[24:27], v[158:161], v[236:239], v[24:27]
	v_mfma_f32_16x16x32_bf16 v[12:15], v[146:149], v[244:247], v[12:15]
	v_mfma_f32_16x16x32_bf16 v[8:11], v[158:161], v[244:247], v[8:11]
	s_setprio 0
	s_setprio 1
	v_mfma_f32_16x16x32_bf16 v[54:57], v[180:183], v[196:199], v[54:57]
	v_mfma_f32_16x16x32_bf16 v[50:53], v[188:191], v[196:199], v[50:53]
	v_mfma_f32_16x16x32_bf16 v[38:41], v[180:183], v[224:227], v[38:41]
	v_mfma_f32_16x16x32_bf16 v[34:37], v[188:191], v[224:227], v[34:37]
	v_mfma_f32_16x16x32_bf16 v[20:23], v[180:183], v[232:235], v[20:23]
	v_mfma_f32_16x16x32_bf16 v[16:19], v[188:191], v[232:235], v[16:19]
	v_mfma_f32_16x16x32_bf16 v[4:7], v[180:183], v[240:243], v[4:7]
	v_mfma_f32_16x16x32_bf16 v[0:3], v[188:191], v[240:243], v[0:3]
	v_mfma_f32_16x16x32_bf16 v[54:57], v[184:187], v[220:223], v[54:57]
	v_mfma_f32_16x16x32_bf16 v[50:53], v[192:195], v[220:223], v[50:53]
	v_mfma_f32_16x16x32_bf16 v[38:41], v[184:187], v[228:231], v[38:41]
	v_mfma_f32_16x16x32_bf16 v[34:37], v[192:195], v[228:231], v[34:37]
	v_mfma_f32_16x16x32_bf16 v[20:23], v[184:187], v[236:239], v[20:23]
	v_mfma_f32_16x16x32_bf16 v[16:19], v[192:195], v[236:239], v[16:19]
	v_mfma_f32_16x16x32_bf16 v[4:7], v[184:187], v[244:247], v[4:7]
	v_mfma_f32_16x16x32_bf16 v[0:3], v[192:195], v[244:247], v[0:3]
	s_setprio 0
	s_barrier
	s_add_i32 s57, 0, 0x18000
	v_add_u32_e32 v153, s57, v150
	s_add_i32 s58, 0, 0x1c000
	ds_read_b128 v[142:145], v153
	ds_read_b128 v[146:149], v153 offset:1024
	ds_read_b128 v[154:157], v153 offset:2048
	ds_read_b128 v[158:161], v153 offset:3072
	v_add_u32_e32 v153, s58, v150
	ds_read_b128 v[180:183], v153
	ds_read_b128 v[184:187], v153 offset:1024
	ds_read_b128 v[188:191], v153 offset:2048
	ds_read_b128 v[192:195], v153 offset:3072
	s_add_u32 s36, s36, 0x80000
	s_addc_u32 s37, s37, 0
	s_mov_b32 m0, s49
	v_lshl_add_u64 v[250:251], s[36:37], 0, v[136:137]
	ds_read_b128 v[196:199], v152 offset:32768
	ds_read_b128 v[220:223], v152 offset:33792
	ds_read_b128 v[224:227], v152 offset:34816
	ds_read_b128 v[228:231], v152 offset:35840
	ds_read_b128 v[232:235], v152 offset:36864
	ds_read_b128 v[236:239], v152 offset:37888
	ds_read_b128 v[240:243], v152 offset:38912
	ds_read_b128 v[244:247], v152 offset:39936
	global_load_lds_dwordx4 v[250:251], off
	v_lshl_add_u64 v[250:251], s[36:37], 0, v[132:133]
	s_mov_b32 m0, s50
	s_nop 0
	global_load_lds_dwordx4 v[250:251], off
	s_waitcnt vmcnt(8)
	s_waitcnt lgkmcnt(0)
	s_barrier
	s_setprio 1
	s_waitcnt lgkmcnt(0)
	v_mfma_f32_16x16x32_bf16 v[126:129], v[142:145], v[196:199], v[126:129]
	v_mfma_f32_16x16x32_bf16 v[122:125], v[154:157], v[196:199], v[122:125]
	v_mfma_f32_16x16x32_bf16 v[110:113], v[142:145], v[224:227], v[110:113]
	v_mfma_f32_16x16x32_bf16 v[106:109], v[154:157], v[224:227], v[106:109]
	v_mfma_f32_16x16x32_bf16 v[94:97], v[142:145], v[232:235], v[94:97]
	v_mfma_f32_16x16x32_bf16 v[90:93], v[154:157], v[232:235], v[90:93]
	v_mfma_f32_16x16x32_bf16 v[78:81], v[142:145], v[240:243], v[78:81]
	v_mfma_f32_16x16x32_bf16 v[74:77], v[154:157], v[240:243], v[74:77]
	v_mfma_f32_16x16x32_bf16 v[126:129], v[146:149], v[220:223], v[126:129]
	v_mfma_f32_16x16x32_bf16 v[122:125], v[158:161], v[220:223], v[122:125]
	v_mfma_f32_16x16x32_bf16 v[110:113], v[146:149], v[228:231], v[110:113]
	v_mfma_f32_16x16x32_bf16 v[106:109], v[158:161], v[228:231], v[106:109]
	v_mfma_f32_16x16x32_bf16 v[94:97], v[146:149], v[236:239], v[94:97]
	v_mfma_f32_16x16x32_bf16 v[90:93], v[158:161], v[236:239], v[90:93]
	v_mfma_f32_16x16x32_bf16 v[78:81], v[146:149], v[244:247], v[78:81]
	v_mfma_f32_16x16x32_bf16 v[74:77], v[158:161], v[244:247], v[74:77]
	s_setprio 0
	s_setprio 1
	v_mfma_f32_16x16x32_bf16 v[118:121], v[180:183], v[196:199], v[118:121]
	v_mfma_f32_16x16x32_bf16 v[114:117], v[188:191], v[196:199], v[114:117]
	v_mfma_f32_16x16x32_bf16 v[102:105], v[180:183], v[224:227], v[102:105]
	v_mfma_f32_16x16x32_bf16 v[98:101], v[188:191], v[224:227], v[98:101]
	v_mfma_f32_16x16x32_bf16 v[86:89], v[180:183], v[232:235], v[86:89]
	v_mfma_f32_16x16x32_bf16 v[82:85], v[188:191], v[232:235], v[82:85]
	v_mfma_f32_16x16x32_bf16 v[70:73], v[180:183], v[240:243], v[70:73]
	v_mfma_f32_16x16x32_bf16 v[66:69], v[188:191], v[240:243], v[66:69]
	v_mfma_f32_16x16x32_bf16 v[118:121], v[184:187], v[220:223], v[118:121]
	v_mfma_f32_16x16x32_bf16 v[114:117], v[192:195], v[220:223], v[114:117]
	v_mfma_f32_16x16x32_bf16 v[102:105], v[184:187], v[228:231], v[102:105]
	v_mfma_f32_16x16x32_bf16 v[98:101], v[192:195], v[228:231], v[98:101]
	v_mfma_f32_16x16x32_bf16 v[86:89], v[184:187], v[236:239], v[86:89]
	v_mfma_f32_16x16x32_bf16 v[82:85], v[192:195], v[236:239], v[82:85]
	v_mfma_f32_16x16x32_bf16 v[70:73], v[184:187], v[244:247], v[70:73]
	v_mfma_f32_16x16x32_bf16 v[66:69], v[192:195], v[244:247], v[66:69]
	s_setprio 0
	s_barrier
; #define PG8_STAGE(bufoff, gbase, voff) do { _Pragma("unroll") for (int _i = 0; _i < 2; ++_i) \
;         __builtin_amdgcn_global_load_lds((const unsigned*)((const char*)(gbase) + (voff)[_i]), (PG8_LAS unsigned*)(lds + (bufoff) + ldsw + _i * 8192), 16, 0, 0); } while (0)
; #define PG8_WAIT_V(n) asm volatile("s_waitcnt vmcnt(" #n ")" ::: "memory")
; #define PG8_WAIT_L(n) asm volatile("s_waitcnt lgkmcnt(" #n ")" ::: "memory")
; #define PG8_BAR __builtin_amdgcn_s_barrier()
; #define PG8_SCHED __builtin_amdgcn_sched_barrier(0)
;     __device__ __forceinline__ void operator()(const f32x4 (&acc)[2][2][4][2], const Unit& u, int wr, int wc, int fr, int fq) const {
;     ...
;             for (int m = 0; m < 4; ++m) { const int row = row0 + ai * HALF + m * 16; const float rs = __builtin_amdgcn_rsqf((float)ss[row] * (SS_INV / 2048.0f) + RMS_EPS) * osc;
; template <class Epi, class Sched, bool ALIGN_EPI = false, bool SP2 = false, bool FP8 = false>
; __device__ __forceinline__ void gemm_phase(PG8_LAS unsigned char* lds, const Gemm g, const Sched& S, const Epi& E, const int tid) {
;     ...
;             PG8_LDA(At, 1, 1); PG8_STAGE(PG8_SB(1, 0), b3, voffB); PG8_STAGE(PG8_SB(1, 1), b3 + hstepB, voffB); PG8_STAGE(PG8_SA(1, 0), a3, voffA);
;             PG8_WAIT_V(8); PG8_WAIT_L(0); PG8_BAR; PG8_MMA(1, 0, At, B0); PG8_MMA(1, 1, At, B1); PG8_BAR; PG8_SCHED;
	s_add_i32 s36, s57, s46
	v_lshl_add_u64 v[164:165], v[164:165], 0, s[38:39]
	s_mov_b32 m0, s36
	ds_read_b128 v[196:199], v152 offset:49152
	ds_read_b128 v[220:223], v152 offset:50176
	ds_read_b128 v[224:227], v152 offset:51200
	ds_read_b128 v[228:231], v152 offset:52224
	ds_read_b128 v[232:235], v152 offset:53248
	ds_read_b128 v[236:239], v152 offset:54272
	ds_read_b128 v[240:243], v152 offset:55296
	ds_read_b128 v[244:247], v152 offset:56320
	global_load_lds_dwordx4 v[164:165], off
	s_add_i32 m0, s36, 0x2000
	s_add_u32 s34, s34, 0x80080
	v_lshl_add_u64 v[164:165], v[166:167], 0, s[38:39]
	s_addc_u32 s35, s35, 0
	s_add_i32 s36, s58, s46
	global_load_lds_dwordx4 v[164:165], off
	v_lshl_add_u64 v[164:165], s[34:35], 0, v[134:135]
	s_mov_b32 m0, s36
	s_nop 0
	global_load_lds_dwordx4 v[164:165], off
	v_lshl_add_u64 v[164:165], s[34:35], 0, v[130:131]
	s_add_i32 m0, s36, 0x2000
	s_nop 0
	global_load_lds_dwordx4 v[164:165], off
	v_lshl_add_u64 v[164:165], v[200:201], 0, s[38:39]
	s_mov_b32 m0, s0
	s_nop 0
	global_load_lds_dwordx4 v[164:165], off
	v_lshl_add_u64 v[164:165], v[248:249], 0, s[38:39]
	s_mov_b32 m0, s51
	s_nop 0
	global_load_lds_dwordx4 v[164:165], off
	s_waitcnt vmcnt(8)
	s_waitcnt lgkmcnt(0)
	s_barrier
	s_setprio 1
	s_waitcnt lgkmcnt(0)
	v_mfma_f32_16x16x32_bf16 v[62:65], v[142:145], v[196:199], v[62:65]
	v_mfma_f32_16x16x32_bf16 v[58:61], v[154:157], v[196:199], v[58:61]
	v_mfma_f32_16x16x32_bf16 v[46:49], v[142:145], v[224:227], v[46:49]
	v_mfma_f32_16x16x32_bf16 v[42:45], v[154:157], v[224:227], v[42:45]
	v_mfma_f32_16x16x32_bf16 v[28:31], v[142:145], v[232:235], v[28:31]
	v_mfma_f32_16x16x32_bf16 v[24:27], v[154:157], v[232:235], v[24:27]
	v_mfma_f32_16x16x32_bf16 v[12:15], v[142:145], v[240:243], v[12:15]
	v_mfma_f32_16x16x32_bf16 v[8:11], v[154:157], v[240:243], v[8:11]
	v_mfma_f32_16x16x32_bf16 v[62:65], v[146:149], v[220:223], v[62:65]
	v_mfma_f32_16x16x32_bf16 v[58:61], v[158:161], v[220:223], v[58:61]
	v_mfma_f32_16x16x32_bf16 v[46:49], v[146:149], v[228:231], v[46:49]
	v_mfma_f32_16x16x32_bf16 v[42:45], v[158:161], v[228:231], v[42:45]
	v_mfma_f32_16x16x32_bf16 v[28:31], v[146:149], v[236:239], v[28:31]
	v_mfma_f32_16x16x32_bf16 v[24:27], v[158:161], v[236:239], v[24:27]
	v_mfma_f32_16x16x32_bf16 v[12:15], v[146:149], v[244:247], v[12:15]
	v_mfma_f32_16x16x32_bf16 v[8:11], v[158:161], v[244:247], v[8:11]
	s_setprio 0
	s_setprio 1
	v_mfma_f32_16x16x32_bf16 v[54:57], v[180:183], v[196:199], v[54:57]
	v_mfma_f32_16x16x32_bf16 v[50:53], v[188:191], v[196:199], v[50:53]
	v_mfma_f32_16x16x32_bf16 v[38:41], v[180:183], v[224:227], v[38:41]
	v_mfma_f32_16x16x32_bf16 v[34:37], v[188:191], v[224:227], v[34:37]
	v_mfma_f32_16x16x32_bf16 v[20:23], v[180:183], v[232:235], v[20:23]
	v_mfma_f32_16x16x32_bf16 v[16:19], v[188:191], v[232:235], v[16:19]
	v_mfma_f32_16x16x32_bf16 v[4:7], v[180:183], v[240:243], v[4:7]
	v_mfma_f32_16x16x32_bf16 v[0:3], v[188:191], v[240:243], v[0:3]
	v_mfma_f32_16x16x32_bf16 v[54:57], v[184:187], v[220:223], v[54:57]
	v_mfma_f32_16x16x32_bf16 v[50:53], v[192:195], v[220:223], v[50:53]
	v_mfma_f32_16x16x32_bf16 v[38:41], v[184:187], v[228:231], v[38:41]
	v_mfma_f32_16x16x32_bf16 v[34:37], v[192:195], v[228:231], v[34:37]
	v_mfma_f32_16x16x32_bf16 v[20:23], v[184:187], v[236:239], v[20:23]
	v_mfma_f32_16x16x32_bf16 v[16:19], v[192:195], v[236:239], v[16:19]
	v_mfma_f32_16x16x32_bf16 v[4:7], v[184:187], v[244:247], v[4:7]
	v_mfma_f32_16x16x32_bf16 v[0:3], v[192:195], v[244:247], v[0:3]
	s_setprio 0
	s_barrier
	s_add_i32 s56, s56, 2
	s_add_u32 s30, s30, 0x100
	s_addc_u32 s31, s31, 0
	s_add_u32 s54, s54, 0x100
	s_addc_u32 s55, s55, 0
	s_cmp_gt_u32 s56, 29
	s_cbranch_scc0 .LBB0_735
	v_lshl_add_u32 v148, s22, 8, v33
	v_ashrrev_i32_e32 v149, 31, v148
	v_lshl_add_u64 v[144:145], v[148:149], 3, s[12:13]
	global_load_dwordx2 v[220:221], v[144:145], off
	global_load_dwordx2 v[222:223], v[144:145], off offset:128
	global_load_dwordx2 v[224:225], v[144:145], off offset:256
	global_load_dwordx2 v[226:227], v[144:145], off offset:384
	global_load_dwordx2 v[228:229], v[144:145], off offset:1024
	global_load_dwordx2 v[230:231], v[144:145], off offset:1152
	global_load_dwordx2 v[232:233], v[144:145], off offset:1280
	global_load_dwordx2 v[234:235], v[144:145], off offset:1408
	s_and_b64 vcc, exec, s[14:15]
	s_cbranch_vccz .LBB0_738
	s_barrier

; #define PG8_STAGE(bufoff, gbase, voff) do { _Pragma("unroll") for (int _i = 0; _i < 2; ++_i) \
;         __builtin_amdgcn_global_load_lds((const unsigned*)((const char*)(gbase) + (voff)[_i]), (PG8_LAS unsigned*)(lds + (bufoff) + ldsw + _i * 8192), 16, 0, 0); } while (0)
; #define PG8_WAIT_V(n) asm volatile("s_waitcnt vmcnt(" #n ")" ::: "memory")
; #define PG8_BAR __builtin_amdgcn_s_barrier()
; template <class Epi, class Sched, bool ALIGN_EPI = false, bool SP2 = false, bool FP8 = false>
; __device__ __forceinline__ void gemm_phase(PG8_LAS unsigned char* lds, const Gemm g, const Sched& S, const Epi& E, const int tid) {
;     ...
;     if constexpr (SP2) {
;         PG8_STAGE(PG8_SB(0, 0), cB, voffB); PG8_STAGE(PG8_SB(0, 1), cB + hstepB, voffB); PG8_STAGE(PG8_SA(0, 0), cA, voffA); PG8_STAGE(PG8_SA(0, 1), cA + hstepA, voffA);
;         if (wr == 1) PG8_BAR;
;         PG8_WAIT_V(2); PG8_BAR;
;         PG8_STAGE(PG8_SB(1, 0), cB + kstep, voffB); PG8_STAGE(PG8_SA(1, 0), cA + kstep, voffA); PG8_STAGE(PG8_SB(1, 1), cB + hstepB + kstep, voffB);
;         PG8_WAIT_V(6); PG8_BAR;
.LBB0_791:
	s_add_u32 s16, s6, 0xc800000
	v_readlane_b32 s24, v252, 24
	s_addc_u32 s17, s7, 0
	v_readlane_b32 s25, v252, 25
	s_and_b64 s[24:25], s[24:25], exec
	s_cselect_b32 s25, s5, 0
	s_cselect_b32 s24, s4, 0
	s_add_u32 s26, s6, 0x32d60000
	s_addc_u32 s27, s7, 0
	s_add_u32 s28, s6, 0x362a4000
	s_addc_u32 s29, s7, 0
	s_lshl_b32 s4, s30, 5
	s_and_b32 s7, s4, 0x60
	s_add_i32 m0, s52, 0x18000
	v_lshl_add_u64 v[6:7], v[6:7], 0, s[38:39]
	s_lshl_b32 s6, s22, 13
	s_lshl_b32 s30, s7, 7
	s_waitcnt vmcnt(2)
	s_barrier
	global_load_lds_dwordx4 v[6:7], off
	v_lshl_add_u64 v[4:5], v[4:5], 0, s[38:39]
	s_add_i32 m0, s52, 0x1a000
	s_add_i32 s56, s52, 0x8000
	s_add_i32 s57, s52, 0xa000
	global_load_lds_dwordx4 v[4:5], off
	v_lshl_add_u64 v[0:1], v[0:1], 0, s[38:39]
	s_mov_b32 m0, s56
	s_add_u32 s4, s10, 0x200080
	global_load_lds_dwordx4 v[0:1], off
	v_lshl_add_u64 v[0:1], v[2:3], 0, s[38:39]
	s_mov_b32 m0, s57
	s_addc_u32 s5, s11, 0
	global_load_lds_dwordx4 v[0:1], off
	s_add_i32 m0, s52, 0x1c000
	v_lshl_add_u64 v[0:1], s[4:5], 0, v[146:147]
	global_load_lds_dwordx4 v[0:1], off
	v_lshl_add_u64 v[0:1], s[4:5], 0, v[142:143]
	s_add_i32 m0, s52, 0x1e000
	s_cmpk_lt_u32 s20, 0x100
	global_load_lds_dwordx4 v[0:1], off
	v_bfe_u32 v1, v8, 4, 2
	v_and_b32_e32 v0, 15, v8
	v_lshlrev_b32_e32 v2, 4, v1
	v_lshl_or_b32 v33, s22, 6, v0
	v_lshl_or_b32 v0, v0, 6, v2
	v_lshlrev_b32_e32 v2, 2, v8
	v_and_b32_e32 v2, 32, v2
	v_bitop3_b32 v3, v0, s6, v2 bitop3:0xde
	v_bitop3_b32 v163, s30, v0, v2 bitop3:0xf6
	v_lshlrev_b32_e32 v0, 17, v13
	v_and_b32_e32 v0, 0xfffc0000, v0
	v_cmp_eq_u32_e64 s[4:5], 0, v1
	v_lshl_or_b32 v171, v1, 3, s7
	v_lshl_add_u32 v0, v12, 14, v0
	v_and_b32_e32 v1, 1, v13
	v_lshl_or_b32 v0, v1, 6, v0
	v_lshl_add_u32 v150, v14, 1, v0
	v_lshlrev_b32_e32 v0, 17, v9
	v_and_b32_e32 v0, 0xfffc0000, v0
	s_waitcnt vmcnt(0)
	v_lshl_add_u32 v0, v10, 14, v0
	v_and_b32_e32 v1, 1, v9
	s_cselect_b64 s[30:31], -1, 0
	s_cmp_lg_u64 s[24:25], 0
	v_lshl_or_b32 v0, v1, 6, v0
	v_readlane_b32 s6, v254, 55
	s_mov_b32 s58, 0
	s_cselect_b64 s[34:35], -1, 0
	v_mov_b32_e32 v151, v32
	v_lshl_add_u32 v152, v11, 1, v0
	v_mov_b32_e32 v153, v32
	v_add_u32_e32 v188, 0, v3
	v_readlane_b32 s20, v254, 38
	s_mov_b32 s22, s6
	s_barrier
	v_readlane_b32 s7, v254, 56
	s_branch .LBB0_794

; #define PG8_STAGE(bufoff, gbase, voff) do { _Pragma("unroll") for (int _i = 0; _i < 2; ++_i) \
;         __builtin_amdgcn_global_load_lds((const unsigned*)((const char*)(gbase) + (voff)[_i]), (PG8_LAS unsigned*)(lds + (bufoff) + ldsw + _i * 8192), 16, 0, 0); } while (0)
; #define PG8_WAIT_V(n) asm volatile("s_waitcnt vmcnt(" #n ")" ::: "memory")
; #define PG8_WAIT_L(n) asm volatile("s_waitcnt lgkmcnt(" #n ")" ::: "memory")
; #define PG8_BAR __builtin_amdgcn_s_barrier()
; #define PG8_SCHED __builtin_amdgcn_sched_barrier(0)
; template <class Epi, class Sched, bool ALIGN_EPI = false, bool SP2 = false, bool FP8 = false>
; __device__ __forceinline__ void gemm_phase(PG8_LAS unsigned char* lds, const Gemm g, const Sched& S, const Epi& E, const int tid) {
;     ...
;             if constexpr (SP2) {
;             PG8_LDB(B0, 0, 0); PG8_LDB(B1, 0, 1); PG8_SCHED; PG8_LDA(At, 0, 0); PG8_STAGE(PG8_SA(1, 1), a1 + hstepA, voffA);
;             PG8_WAIT_V(8); PG8_WAIT_L(0); PG8_BAR; PG8_MMA(0, 0, At, B0); PG8_MMA(0, 1, At, B1); PG8_BAR; PG8_SCHED;
;             PG8_LDA(At, 0, 1); PG8_STAGE(PG8_SB(0, 0), b2, voffB); PG8_STAGE(PG8_SB(0, 1), b2 + hstepB, voffB); PG8_STAGE(PG8_SA(0, 0), a2, voffA);
;             PG8_WAIT_V(8); PG8_WAIT_L(0); PG8_BAR; PG8_MMA(1, 0, At, B0); PG8_MMA(1, 1, At, B1); PG8_BAR; PG8_SCHED;
.LBB0_801:
	s_add_u32 s10, s8, 0xffe00080
	s_addc_u32 s11, s9, -1
	s_add_i32 s63, 0, 0x10000
	s_cmpk_eq_i32 s62, 0x7c
	s_cselect_b32 s47, s33, s11
	s_cselect_b32 s46, s41, s10
	s_cselect_b32 s11, s37, s61
	s_cselect_b32 s10, s59, s60
	s_add_i32 s66, 0, 0x14000
	v_add_u32_e32 v154, s63, v163
	v_add_u32_e32 v164, s66, v163
	ds_read_b128 v[130:133], v154
	ds_read_b128 v[134:137], v154 offset:1024
	ds_read_b128 v[138:141], v154 offset:2048
	ds_read_b128 v[154:157], v154 offset:3072
	ds_read_b128 v[158:161], v164
	ds_read_b128 v[180:183], v164 offset:1024
	ds_read_b128 v[184:187], v164 offset:2048
	ds_read_b128 v[190:193], v164 offset:3072
	v_lshl_add_u64 v[164:165], s[8:9], 0, v[150:151]
	s_add_i32 m0, s52, 0xc000
	ds_read_b128 v[194:197], v188
	ds_read_b128 v[198:201], v188 offset:1024
	ds_read_b128 v[220:223], v188 offset:2048
	ds_read_b128 v[224:227], v188 offset:3072
	ds_read_b128 v[228:231], v188 offset:4096
	ds_read_b128 v[232:235], v188 offset:5120
	ds_read_b128 v[236:239], v188 offset:6144
	ds_read_b128 v[240:243], v188 offset:7168
	global_load_lds_dwordx4 v[164:165], off
	v_lshl_add_u64 v[164:165], s[8:9], 0, v[152:153]
	s_add_i32 m0, s52, 0xe000
	s_nop 0
	global_load_lds_dwordx4 v[164:165], off
	s_cmp_eq_i32 s62, -2
	s_cbranch_scc1 .Lskw_5_0
	s_waitcnt vmcnt(8)
.Lskw_5_0:
	s_waitcnt lgkmcnt(0)
	s_barrier
	s_setprio 1
	s_waitcnt lgkmcnt(0)
	v_mfma_f32_16x16x32_bf16 v[126:129], v[130:133], v[194:197], v[126:129]
	v_mfma_f32_16x16x32_bf16 v[122:125], v[138:141], v[194:197], v[122:125]
	v_mfma_f32_16x16x32_bf16 v[110:113], v[130:133], v[220:223], v[110:113]
	v_mfma_f32_16x16x32_bf16 v[106:109], v[138:141], v[220:223], v[106:109]
	v_mfma_f32_16x16x32_bf16 v[94:97], v[130:133], v[228:231], v[94:97]
	v_mfma_f32_16x16x32_bf16 v[90:93], v[138:141], v[228:231], v[90:93]
	v_mfma_f32_16x16x32_bf16 v[78:81], v[130:133], v[236:239], v[78:81]
	v_mfma_f32_16x16x32_bf16 v[74:77], v[138:141], v[236:239], v[74:77]
	v_mfma_f32_16x16x32_bf16 v[126:129], v[134:137], v[198:201], v[126:129]
	v_mfma_f32_16x16x32_bf16 v[122:125], v[154:157], v[198:201], v[122:125]
	v_mfma_f32_16x16x32_bf16 v[110:113], v[134:137], v[224:227], v[110:113]
	v_mfma_f32_16x16x32_bf16 v[106:109], v[154:157], v[224:227], v[106:109]
	v_mfma_f32_16x16x32_bf16 v[94:97], v[134:137], v[232:235], v[94:97]
	v_mfma_f32_16x16x32_bf16 v[90:93], v[154:157], v[232:235], v[90:93]
	v_mfma_f32_16x16x32_bf16 v[78:81], v[134:137], v[240:243], v[78:81]
	v_mfma_f32_16x16x32_bf16 v[74:77], v[154:157], v[240:243], v[74:77]
	s_setprio 0
	s_setprio 1
	v_mfma_f32_16x16x32_bf16 v[118:121], v[158:161], v[194:197], v[118:121]
	v_mfma_f32_16x16x32_bf16 v[114:117], v[184:187], v[194:197], v[114:117]
	v_mfma_f32_16x16x32_bf16 v[102:105], v[158:161], v[220:223], v[102:105]
	v_mfma_f32_16x16x32_bf16 v[98:101], v[184:187], v[220:223], v[98:101]
	v_mfma_f32_16x16x32_bf16 v[86:89], v[158:161], v[228:231], v[86:89]
	v_mfma_f32_16x16x32_bf16 v[82:85], v[184:187], v[228:231], v[82:85]
	v_mfma_f32_16x16x32_bf16 v[70:73], v[158:161], v[236:239], v[70:73]
	v_mfma_f32_16x16x32_bf16 v[66:69], v[184:187], v[236:239], v[66:69]
	v_mfma_f32_16x16x32_bf16 v[118:121], v[180:183], v[198:201], v[118:121]
	v_mfma_f32_16x16x32_bf16 v[114:117], v[190:193], v[198:201], v[114:117]
	v_mfma_f32_16x16x32_bf16 v[102:105], v[180:183], v[224:227], v[102:105]
	v_mfma_f32_16x16x32_bf16 v[98:101], v[190:193], v[224:227], v[98:101]
	v_mfma_f32_16x16x32_bf16 v[86:89], v[180:183], v[232:235], v[86:89]
	v_mfma_f32_16x16x32_bf16 v[82:85], v[190:193], v[232:235], v[82:85]
	v_mfma_f32_16x16x32_bf16 v[70:73], v[180:183], v[240:243], v[70:73]
	v_mfma_f32_16x16x32_bf16 v[66:69], v[190:193], v[240:243], v[66:69]
	s_setprio 0
	s_barrier
	s_add_i32 s63, s63, s51
	v_lshl_add_u64 v[164:165], s[10:11], 0, v[146:147]
	s_mov_b32 m0, s63
	ds_read_b128 v[194:197], v188 offset:16384
	ds_read_b128 v[198:201], v188 offset:17408
	ds_read_b128 v[220:223], v188 offset:18432
	ds_read_b128 v[224:227], v188 offset:19456
	ds_read_b128 v[228:231], v188 offset:20480
	ds_read_b128 v[232:235], v188 offset:21504
	ds_read_b128 v[236:239], v188 offset:22528
	ds_read_b128 v[240:243], v188 offset:23552
	global_load_lds_dwordx4 v[164:165], off
	s_add_i32 m0, s63, 0x2000
	s_add_u32 s64, s10, 0x200000
	v_lshl_add_u64 v[166:167], s[10:11], 0, v[142:143]
	s_addc_u32 s65, s11, 0
	s_add_i32 s63, s66, s51
	global_load_lds_dwordx4 v[166:167], off
	v_lshl_add_u64 v[244:245], s[64:65], 0, v[146:147]
	s_mov_b32 m0, s63
	v_lshl_add_u64 v[246:247], s[46:47], 0, v[144:145]
	global_load_lds_dwordx4 v[244:245], off
	v_lshl_add_u64 v[244:245], s[64:65], 0, v[142:143]
	s_add_i32 m0, s63, 0x2000
	s_nop 0
	global_load_lds_dwordx4 v[244:245], off
	v_lshl_add_u64 v[244:245], s[46:47], 0, v[148:149]
	s_mov_b32 m0, s52
	s_nop 0
	global_load_lds_dwordx4 v[244:245], off
	s_mov_b32 m0, s53
	s_nop 0
	global_load_lds_dwordx4 v[246:247], off
	s_cmp_eq_i32 s62, -2
	s_cbranch_scc1 .Lskw_5_1
	s_waitcnt vmcnt(8)
; #define PG8_STAGE(bufoff, gbase, voff) do { _Pragma("unroll") for (int _i = 0; _i < 2; ++_i) \
;         __builtin_amdgcn_global_load_lds((const unsigned*)((const char*)(gbase) + (voff)[_i]), (PG8_LAS unsigned*)(lds + (bufoff) + ldsw + _i * 8192), 16, 0, 0); } while (0)
; #define PG8_WAIT_V(n) asm volatile("s_waitcnt vmcnt(" #n ")" ::: "memory")
; #define PG8_WAIT_L(n) asm volatile("s_waitcnt lgkmcnt(" #n ")" ::: "memory")
; #define PG8_BAR __builtin_amdgcn_s_barrier()
; #define PG8_SCHED __builtin_amdgcn_sched_barrier(0)
; template <class Epi, class Sched, bool ALIGN_EPI = false, bool SP2 = false, bool FP8 = false>
; __device__ __forceinline__ void gemm_phase(PG8_LAS unsigned char* lds, const Gemm g, const Sched& S, const Epi& E, const int tid) {
;     ...
;             PG8_WAIT_V(8); PG8_WAIT_L(0); PG8_BAR; PG8_MMA(1, 0, At, B0); PG8_MMA(1, 1, At, B1); PG8_BAR; PG8_SCHED;
;             PG8_LDB(B0, 1, 0); PG8_LDB(B1, 1, 1); PG8_SCHED; PG8_LDA(At, 1, 0); PG8_STAGE(PG8_SA(0, 1), a2 + hstepA, voffA);
;             PG8_WAIT_V(8); PG8_WAIT_L(0); PG8_BAR; PG8_MMA(0, 0, At, B0); PG8_MMA(0, 1, At, B1); PG8_BAR; PG8_SCHED;
.Lskw_5_1:
	s_waitcnt lgkmcnt(0)
	s_barrier
	s_setprio 1
	s_waitcnt lgkmcnt(0)
	v_mfma_f32_16x16x32_bf16 v[62:65], v[130:133], v[194:197], v[62:65]
	v_mfma_f32_16x16x32_bf16 v[58:61], v[138:141], v[194:197], v[58:61]
	v_mfma_f32_16x16x32_bf16 v[46:49], v[130:133], v[220:223], v[46:49]
	v_mfma_f32_16x16x32_bf16 v[42:45], v[138:141], v[220:223], v[42:45]
	v_mfma_f32_16x16x32_bf16 v[28:31], v[130:133], v[228:231], v[28:31]
	v_mfma_f32_16x16x32_bf16 v[24:27], v[138:141], v[228:231], v[24:27]
	v_mfma_f32_16x16x32_bf16 v[12:15], v[130:133], v[236:239], v[12:15]
	v_mfma_f32_16x16x32_bf16 v[8:11], v[138:141], v[236:239], v[8:11]
	v_mfma_f32_16x16x32_bf16 v[62:65], v[134:137], v[198:201], v[62:65]
	v_mfma_f32_16x16x32_bf16 v[58:61], v[154:157], v[198:201], v[58:61]
	v_mfma_f32_16x16x32_bf16 v[46:49], v[134:137], v[224:227], v[46:49]
	v_mfma_f32_16x16x32_bf16 v[42:45], v[154:157], v[224:227], v[42:45]
	v_mfma_f32_16x16x32_bf16 v[28:31], v[134:137], v[232:235], v[28:31]
	v_mfma_f32_16x16x32_bf16 v[24:27], v[154:157], v[232:235], v[24:27]
	v_mfma_f32_16x16x32_bf16 v[12:15], v[134:137], v[240:243], v[12:15]
	v_mfma_f32_16x16x32_bf16 v[8:11], v[154:157], v[240:243], v[8:11]
	s_setprio 0
	s_setprio 1
	v_mfma_f32_16x16x32_bf16 v[54:57], v[158:161], v[194:197], v[54:57]
	v_mfma_f32_16x16x32_bf16 v[50:53], v[184:187], v[194:197], v[50:53]
	v_mfma_f32_16x16x32_bf16 v[38:41], v[158:161], v[220:223], v[38:41]
	v_mfma_f32_16x16x32_bf16 v[34:37], v[184:187], v[220:223], v[34:37]
	v_mfma_f32_16x16x32_bf16 v[20:23], v[158:161], v[228:231], v[20:23]
	v_mfma_f32_16x16x32_bf16 v[16:19], v[184:187], v[228:231], v[16:19]
	v_mfma_f32_16x16x32_bf16 v[4:7], v[158:161], v[236:239], v[4:7]
	v_mfma_f32_16x16x32_bf16 v[0:3], v[184:187], v[236:239], v[0:3]
	v_mfma_f32_16x16x32_bf16 v[54:57], v[180:183], v[198:201], v[54:57]
	v_mfma_f32_16x16x32_bf16 v[50:53], v[190:193], v[198:201], v[50:53]
	v_mfma_f32_16x16x32_bf16 v[38:41], v[180:183], v[224:227], v[38:41]
	v_mfma_f32_16x16x32_bf16 v[34:37], v[190:193], v[224:227], v[34:37]
	v_mfma_f32_16x16x32_bf16 v[20:23], v[180:183], v[232:235], v[20:23]
	v_mfma_f32_16x16x32_bf16 v[16:19], v[190:193], v[232:235], v[16:19]
	v_mfma_f32_16x16x32_bf16 v[4:7], v[180:183], v[240:243], v[4:7]
	v_mfma_f32_16x16x32_bf16 v[0:3], v[190:193], v[240:243], v[0:3]
	s_setprio 0
	s_barrier
	s_add_i32 s63, 0, 0x18000
	s_add_i32 s64, 0, 0x1c000
	v_add_u32_e32 v154, s63, v163
	v_add_u32_e32 v189, s64, v163
	ds_read_b128 v[130:133], v154
	ds_read_b128 v[134:137], v154 offset:1024
	ds_read_b128 v[138:141], v154 offset:2048
	ds_read_b128 v[154:157], v154 offset:3072
	ds_read_b128 v[158:161], v189
	ds_read_b128 v[180:183], v189 offset:1024
	ds_read_b128 v[184:187], v189 offset:2048
	ds_read_b128 v[190:193], v189 offset:3072
	s_add_u32 s46, s46, 0x200000
	s_addc_u32 s47, s47, 0
	s_mov_b32 m0, s54
	v_lshl_add_u64 v[248:249], s[46:47], 0, v[148:149]
	ds_read_b128 v[194:197], v188 offset:32768
	ds_read_b128 v[198:201], v188 offset:33792
	ds_read_b128 v[220:223], v188 offset:34816
	ds_read_b128 v[224:227], v188 offset:35840
	ds_read_b128 v[228:231], v188 offset:36864
	ds_read_b128 v[232:235], v188 offset:37888
	ds_read_b128 v[236:239], v188 offset:38912
	ds_read_b128 v[240:243], v188 offset:39936
	global_load_lds_dwordx4 v[248:249], off
	v_lshl_add_u64 v[248:249], s[46:47], 0, v[144:145]
	s_mov_b32 m0, s55
	s_nop 0
	global_load_lds_dwordx4 v[248:249], off
	s_waitcnt vmcnt(8)
	s_waitcnt lgkmcnt(0)
	s_barrier
	s_setprio 1
	s_waitcnt lgkmcnt(0)
	v_mfma_f32_16x16x32_bf16 v[126:129], v[130:133], v[194:197], v[126:129]
	v_mfma_f32_16x16x32_bf16 v[122:125], v[138:141], v[194:197], v[122:125]
	v_mfma_f32_16x16x32_bf16 v[110:113], v[130:133], v[220:223], v[110:113]
	v_mfma_f32_16x16x32_bf16 v[106:109], v[138:141], v[220:223], v[106:109]
	v_mfma_f32_16x16x32_bf16 v[94:97], v[130:133], v[228:231], v[94:97]
	v_mfma_f32_16x16x32_bf16 v[90:93], v[138:141], v[228:231], v[90:93]
	v_mfma_f32_16x16x32_bf16 v[78:81], v[130:133], v[236:239], v[78:81]
	v_mfma_f32_16x16x32_bf16 v[74:77], v[138:141], v[236:239], v[74:77]
	v_mfma_f32_16x16x32_bf16 v[126:129], v[134:137], v[198:201], v[126:129]
	v_mfma_f32_16x16x32_bf16 v[122:125], v[154:157], v[198:201], v[122:125]
	v_mfma_f32_16x16x32_bf16 v[110:113], v[134:137], v[224:227], v[110:113]
	v_mfma_f32_16x16x32_bf16 v[106:109], v[154:157], v[224:227], v[106:109]
	v_mfma_f32_16x16x32_bf16 v[94:97], v[134:137], v[232:235], v[94:97]
	v_mfma_f32_16x16x32_bf16 v[90:93], v[154:157], v[232:235], v[90:93]
	v_mfma_f32_16x16x32_bf16 v[78:81], v[134:137], v[240:243], v[78:81]
	v_mfma_f32_16x16x32_bf16 v[74:77], v[154:157], v[240:243], v[74:77]
	s_setprio 0
	s_setprio 1
	v_mfma_f32_16x16x32_bf16 v[118:121], v[158:161], v[194:197], v[118:121]
	v_mfma_f32_16x16x32_bf16 v[114:117], v[184:187], v[194:197], v[114:117]
	v_mfma_f32_16x16x32_bf16 v[102:105], v[158:161], v[220:223], v[102:105]
	v_mfma_f32_16x16x32_bf16 v[98:101], v[184:187], v[220:223], v[98:101]
	v_mfma_f32_16x16x32_bf16 v[86:89], v[158:161], v[228:231], v[86:89]
	v_mfma_f32_16x16x32_bf16 v[82:85], v[184:187], v[228:231], v[82:85]
	v_mfma_f32_16x16x32_bf16 v[70:73], v[158:161], v[236:239], v[70:73]
	v_mfma_f32_16x16x32_bf16 v[66:69], v[184:187], v[236:239], v[66:69]
	v_mfma_f32_16x16x32_bf16 v[118:121], v[180:183], v[198:201], v[118:121]
	v_mfma_f32_16x16x32_bf16 v[114:117], v[190:193], v[198:201], v[114:117]
	v_mfma_f32_16x16x32_bf16 v[102:105], v[180:183], v[224:227], v[102:105]
	v_mfma_f32_16x16x32_bf16 v[98:101], v[190:193], v[224:227], v[98:101]
	v_mfma_f32_16x16x32_bf16 v[86:89], v[180:183], v[232:235], v[86:89]
	v_mfma_f32_16x16x32_bf16 v[82:85], v[190:193], v[232:235], v[82:85]
	v_mfma_f32_16x16x32_bf16 v[70:73], v[180:183], v[240:243], v[70:73]
	v_mfma_f32_16x16x32_bf16 v[66:69], v[190:193], v[240:243], v[66:69]
	s_setprio 0
	s_barrier
; #define PG8_STAGE(bufoff, gbase, voff) do { _Pragma("unroll") for (int _i = 0; _i < 2; ++_i) \
;         __builtin_amdgcn_global_load_lds((const unsigned*)((const char*)(gbase) + (voff)[_i]), (PG8_LAS unsigned*)(lds + (bufoff) + ldsw + _i * 8192), 16, 0, 0); } while (0)
; #define PG8_WAIT_V(n) asm volatile("s_waitcnt vmcnt(" #n ")" ::: "memory")
; #define PG8_WAIT_L(n) asm volatile("s_waitcnt lgkmcnt(" #n ")" ::: "memory")
; #define PG8_BAR __builtin_amdgcn_s_barrier()
; #define PG8_SCHED __builtin_amdgcn_sched_barrier(0)
; template <class Epi, class Sched, bool ALIGN_EPI = false, bool SP2 = false, bool FP8 = false>
; __device__ __forceinline__ void gemm_phase(PG8_LAS unsigned char* lds, const Gemm g, const Sched& S, const Epi& E, const int tid) {
;     ...
;             PG8_LDA(At, 1, 1); PG8_STAGE(PG8_SB(1, 0), b3, voffB); PG8_STAGE(PG8_SB(1, 1), b3 + hstepB, voffB); PG8_STAGE(PG8_SA(1, 0), a3, voffA);
;             PG8_WAIT_V(8); PG8_WAIT_L(0); PG8_BAR; PG8_MMA(1, 0, At, B0); PG8_MMA(1, 1, At, B1); PG8_BAR; PG8_SCHED;
;     ...
;         if constexpr (ALIGN_EPI) { if (wr == 0) PG8_BAR; }
	s_add_i32 s46, s63, s51
	v_lshl_add_u64 v[164:165], v[164:165], 0, s[38:39]
	s_mov_b32 m0, s46
	ds_read_b128 v[194:197], v188 offset:49152
	ds_read_b128 v[198:201], v188 offset:50176
	ds_read_b128 v[220:223], v188 offset:51200
	ds_read_b128 v[224:227], v188 offset:52224
	ds_read_b128 v[228:231], v188 offset:53248
	ds_read_b128 v[232:235], v188 offset:54272
	ds_read_b128 v[236:239], v188 offset:55296
	ds_read_b128 v[240:243], v188 offset:56320
	global_load_lds_dwordx4 v[164:165], off
	s_add_i32 m0, s46, 0x2000
	s_add_u32 s10, s10, 0x200080
	v_lshl_add_u64 v[164:165], v[166:167], 0, s[38:39]
	s_addc_u32 s11, s11, 0
	s_add_i32 s46, s64, s51
	global_load_lds_dwordx4 v[164:165], off
	v_lshl_add_u64 v[164:165], s[10:11], 0, v[146:147]
	s_mov_b32 m0, s46
	s_nop 0
	global_load_lds_dwordx4 v[164:165], off
	v_lshl_add_u64 v[164:165], s[10:11], 0, v[142:143]
	s_add_i32 m0, s46, 0x2000
	s_nop 0
	global_load_lds_dwordx4 v[164:165], off
	v_lshl_add_u64 v[164:165], v[244:245], 0, s[38:39]
	s_mov_b32 m0, s56
	s_nop 0
	global_load_lds_dwordx4 v[164:165], off
	v_lshl_add_u64 v[164:165], v[246:247], 0, s[38:39]
	s_mov_b32 m0, s57
	s_nop 0
	global_load_lds_dwordx4 v[164:165], off
	s_waitcnt vmcnt(8)
	s_waitcnt lgkmcnt(0)
	s_barrier
	s_setprio 1
	s_waitcnt lgkmcnt(0)
	v_mfma_f32_16x16x32_bf16 v[62:65], v[130:133], v[194:197], v[62:65]
	v_mfma_f32_16x16x32_bf16 v[58:61], v[138:141], v[194:197], v[58:61]
	v_mfma_f32_16x16x32_bf16 v[46:49], v[130:133], v[220:223], v[46:49]
	v_mfma_f32_16x16x32_bf16 v[42:45], v[138:141], v[220:223], v[42:45]
	v_mfma_f32_16x16x32_bf16 v[28:31], v[130:133], v[228:231], v[28:31]
	v_mfma_f32_16x16x32_bf16 v[24:27], v[138:141], v[228:231], v[24:27]
	v_mfma_f32_16x16x32_bf16 v[12:15], v[130:133], v[236:239], v[12:15]
	v_mfma_f32_16x16x32_bf16 v[8:11], v[138:141], v[236:239], v[8:11]
	v_mfma_f32_16x16x32_bf16 v[62:65], v[134:137], v[198:201], v[62:65]
	v_mfma_f32_16x16x32_bf16 v[58:61], v[154:157], v[198:201], v[58:61]
	v_mfma_f32_16x16x32_bf16 v[46:49], v[134:137], v[224:227], v[46:49]
	v_mfma_f32_16x16x32_bf16 v[42:45], v[154:157], v[224:227], v[42:45]
	v_mfma_f32_16x16x32_bf16 v[28:31], v[134:137], v[232:235], v[28:31]
	v_mfma_f32_16x16x32_bf16 v[24:27], v[154:157], v[232:235], v[24:27]
	v_mfma_f32_16x16x32_bf16 v[12:15], v[134:137], v[240:243], v[12:15]
	v_mfma_f32_16x16x32_bf16 v[8:11], v[154:157], v[240:243], v[8:11]
	s_setprio 0
	s_setprio 1
	v_mfma_f32_16x16x32_bf16 v[54:57], v[158:161], v[194:197], v[54:57]
	v_mfma_f32_16x16x32_bf16 v[50:53], v[184:187], v[194:197], v[50:53]
	v_mfma_f32_16x16x32_bf16 v[38:41], v[158:161], v[220:223], v[38:41]
	v_mfma_f32_16x16x32_bf16 v[34:37], v[184:187], v[220:223], v[34:37]
	v_mfma_f32_16x16x32_bf16 v[20:23], v[158:161], v[228:231], v[20:23]
	v_mfma_f32_16x16x32_bf16 v[16:19], v[184:187], v[228:231], v[16:19]
	v_mfma_f32_16x16x32_bf16 v[4:7], v[158:161], v[236:239], v[4:7]
	v_mfma_f32_16x16x32_bf16 v[0:3], v[184:187], v[236:239], v[0:3]
	v_mfma_f32_16x16x32_bf16 v[54:57], v[180:183], v[198:201], v[54:57]
	v_mfma_f32_16x16x32_bf16 v[50:53], v[190:193], v[198:201], v[50:53]
	v_mfma_f32_16x16x32_bf16 v[38:41], v[180:183], v[224:227], v[38:41]
	v_mfma_f32_16x16x32_bf16 v[34:37], v[190:193], v[224:227], v[34:37]
	v_mfma_f32_16x16x32_bf16 v[20:23], v[180:183], v[232:235], v[20:23]
	v_mfma_f32_16x16x32_bf16 v[16:19], v[190:193], v[232:235], v[16:19]
	v_mfma_f32_16x16x32_bf16 v[4:7], v[180:183], v[240:243], v[4:7]
	v_mfma_f32_16x16x32_bf16 v[0:3], v[190:193], v[240:243], v[0:3]
	s_setprio 0
	s_barrier
	s_add_i32 s62, s62, 2
	s_add_u32 s8, s8, 0x100
	s_addc_u32 s9, s9, 0
	s_add_u32 s60, s60, 0x100
	s_addc_u32 s61, s61, 0
	s_cmpk_gt_u32 s62, 0x7d
	s_cbranch_scc0 .LBB0_801
	s_and_b64 vcc, exec, s[30:31]
	s_cbranch_vccz .LBB0_804
	s_barrier
